# K-loops: all per-segment s_setprio flips deleted, one static s_setprio 1 for the older half (waves 0-3) in front of each K-loop, cleared behind it
# baseline (speedup 1.0000x reference)
; #define PG8_STAGE(bufoff, gbase, voff) do { _Pragma("unroll") for (int _i = 0; _i < 2; ++_i) \
;         __builtin_amdgcn_global_load_lds((const unsigned*)((const char*)(gbase) + (voff)[_i]), (PG8_LAS unsigned*)(lds + (bufoff) + ldsw + _i * 8192), 16, 0, 0); } while (0)
; #define PG8_LDA(dst, b, h) do { _Pragma("unroll") for (int m = 0; m < 4; ++m) _Pragma("unroll") for (int k = 0; k < 2; ++k) dst[m][k] = *(const PG8_LAS bf16x8*)(lds + PG8_SA(b, h) + aoff + m * 2048 + k * 1024); } while (0)
; #define PG8_LDB(dst, b, h) do { _Pragma("unroll") for (int n = 0; n < 2; ++n) _Pragma("unroll") for (int k = 0; k < 2; ++k) dst[n][k] = *(const PG8_LAS bf16x8*)(lds + PG8_SB(b, h) + boff + n * 2048 + k * 1024); } while (0)
; #define PG8_WAIT_V(n) asm volatile("s_waitcnt vmcnt(" #n ")" ::: "memory")
; #define PG8_WAIT_L(n) asm volatile("s_waitcnt lgkmcnt(" #n ")" ::: "memory")
; #define PG8_BAR __builtin_amdgcn_s_barrier()
; #define PG8_SCHED __builtin_amdgcn_sched_barrier(0)
; template <class Epi, class Sched, bool ALIGN_EPI = false, bool SP2 = false>
; __device__ __forceinline__ void gemm_phase(PG8_LAS unsigned char* lds, const Gemm g, const Sched& S, const Epi& E) {
;     ...
;         const bool has_next = S.next(ui + 1, nxt);
;         const char* nA = has_next ? (const char*)g.A + (size_t)nxt.pm * tstep : cA; const char* nB = has_next ? (const char*)g.Bt + (size_t)nxt.pn * tstep : cB;
;         for (int t = 0; t < nt; t += 2) {
;             const bool last = (t == nt - 2);
;             const char* a1 = cA + (size_t)(t + 1) * kstep;
;             const char* a2 = last ? nA : cA + (size_t)(t + 2) * kstep; const char* b2 = last ? nB : cB + (size_t)(t + 2) * kstep;
;             const char* a3 = a2 + kstep; const char* b3 = b2 + kstep;
;             if (last && has_next) S.a_ready(nxt);
;             if constexpr (SP2) {
;             PG8_LDB(B0, 0, 0); PG8_LDB(B1, 0, 1); PG8_SCHED; PG8_LDA(At, 0, 0); PG8_STAGE(PG8_SA(1, 1), a1 + hstep, voffA);
;             PG8_WAIT_V(8); PG8_WAIT_L(0); PG8_BAR; PG8_MMA(0, 0, At, B0); PG8_MMA(0, 1, At, B1); PG8_BAR; PG8_SCHED;
;     ...
;         for (int a = 0; a < 2; ++a)
; #pragma unroll
;             for (int b = 0; b < 2; ++b)
; #pragma unroll
;                 for (int m = 0; m < 4; ++m)
; #pragma unroll
;                     for (int n = 0; n < 2; ++n) acc[a][b][m][n] = (f32x4){0.f, 0.f, 0.f, 0.f};
;         cur = nxt; cA = nA; cB = nB; ++ui;
.LBB0_135:
	s_ashr_i32 s55, s54, 31
	s_lshl_b64 s[26:27], s[54:55], 19
	s_add_u32 s56, s96, s26
	s_addc_u32 s57, s97, s27
	s_and_b64 s[26:27], s[0:1], exec
	s_cselect_b32 s5, s57, s63
	s_cselect_b32 s26, s56, s62
	s_ashr_i32 s53, s52, 31
	s_lshl_b64 s[58:59], s[52:53], 19
	s_add_u32 s58, s24, s58
	s_addc_u32 s59, s25, s59
	s_and_b64 s[70:71], s[0:1], exec
	s_cselect_b32 s27, s59, s65
	s_cselect_b32 s53, s58, s64
	s_add_u32 s62, s62, 0x40080
	s_addc_u32 s63, s63, 0
	s_add_u32 s55, s64, 0x100
	v_mov_b32_e32 v0, 0
	s_addc_u32 s75, s65, 0
	s_mov_b32 s76, -2
	v_mov_b32_e32 v1, v0
	v_mov_b32_e32 v2, v0
	v_mov_b32_e32 v3, v0
	v_mov_b32_e32 v4, v0
	v_mov_b32_e32 v5, v0
	v_mov_b32_e32 v6, v0
	v_mov_b32_e32 v7, v0
	v_mov_b32_e32 v16, v0
	v_mov_b32_e32 v17, v0
	v_mov_b32_e32 v18, v0
	v_mov_b32_e32 v19, v0
	v_mov_b32_e32 v20, v0
	v_mov_b32_e32 v21, v0
	v_mov_b32_e32 v22, v0
	v_mov_b32_e32 v23, v0
	v_mov_b32_e32 v32, v0
	v_mov_b32_e32 v33, v0
	v_mov_b32_e32 v34, v0
	v_mov_b32_e32 v35, v0
	v_mov_b32_e32 v36, v0
	v_mov_b32_e32 v37, v0
	v_mov_b32_e32 v38, v0
	v_mov_b32_e32 v39, v0
	v_mov_b32_e32 v48, v0
	v_mov_b32_e32 v49, v0
	v_mov_b32_e32 v50, v0
	v_mov_b32_e32 v51, v0
	v_mov_b32_e32 v52, v0
	v_mov_b32_e32 v53, v0
	v_mov_b32_e32 v54, v0
	v_mov_b32_e32 v55, v0
	v_mov_b32_e32 v8, v0
	v_mov_b32_e32 v9, v0
	v_mov_b32_e32 v10, v0
	v_mov_b32_e32 v11, v0
	v_mov_b32_e32 v12, v0
	v_mov_b32_e32 v13, v0
	v_mov_b32_e32 v14, v0
	v_mov_b32_e32 v15, v0
	v_mov_b32_e32 v24, v0
	v_mov_b32_e32 v25, v0
	v_mov_b32_e32 v26, v0
	v_mov_b32_e32 v27, v0
	v_mov_b32_e32 v28, v0
	v_mov_b32_e32 v29, v0
	v_mov_b32_e32 v30, v0
	v_mov_b32_e32 v31, v0
	v_mov_b32_e32 v40, v0
	v_mov_b32_e32 v41, v0
	v_mov_b32_e32 v42, v0
	v_mov_b32_e32 v43, v0
	v_mov_b32_e32 v44, v0
	v_mov_b32_e32 v45, v0
	v_mov_b32_e32 v46, v0
	v_mov_b32_e32 v47, v0
	v_mov_b32_e32 v56, v0
	v_mov_b32_e32 v57, v0
	v_mov_b32_e32 v58, v0
	v_mov_b32_e32 v59, v0
	v_mov_b32_e32 v60, v0
	v_mov_b32_e32 v61, v0
	v_mov_b32_e32 v62, v0
	v_mov_b32_e32 v63, v0
	v_mov_b32_e32 v64, v0
	v_mov_b32_e32 v65, v0
	v_mov_b32_e32 v66, v0
	v_mov_b32_e32 v67, v0
	v_mov_b32_e32 v68, v0
	v_mov_b32_e32 v69, v0
	v_mov_b32_e32 v70, v0
	v_mov_b32_e32 v71, v0
	v_mov_b32_e32 v80, v0
	v_mov_b32_e32 v81, v0
	v_mov_b32_e32 v82, v0
	v_mov_b32_e32 v83, v0
	v_mov_b32_e32 v84, v0
	v_mov_b32_e32 v85, v0
	v_mov_b32_e32 v86, v0
	v_mov_b32_e32 v87, v0
	v_mov_b32_e32 v96, v0
	v_mov_b32_e32 v97, v0
	v_mov_b32_e32 v98, v0
	v_mov_b32_e32 v99, v0
	v_mov_b32_e32 v100, v0
	v_mov_b32_e32 v101, v0
	v_mov_b32_e32 v102, v0
	v_mov_b32_e32 v103, v0
	v_mov_b32_e32 v112, v0
	v_mov_b32_e32 v113, v0
	v_mov_b32_e32 v114, v0
	v_mov_b32_e32 v115, v0
	v_mov_b32_e32 v116, v0
	v_mov_b32_e32 v117, v0
	v_mov_b32_e32 v118, v0
	v_mov_b32_e32 v119, v0
	v_mov_b32_e32 v72, v0
	v_mov_b32_e32 v73, v0
	v_mov_b32_e32 v74, v0
	v_mov_b32_e32 v75, v0
	v_mov_b32_e32 v76, v0
	v_mov_b32_e32 v77, v0
	v_mov_b32_e32 v78, v0
	v_mov_b32_e32 v79, v0
	v_mov_b32_e32 v88, v0
	v_mov_b32_e32 v89, v0
	v_mov_b32_e32 v90, v0
	v_mov_b32_e32 v91, v0
	v_mov_b32_e32 v92, v0
	v_mov_b32_e32 v93, v0
	v_mov_b32_e32 v94, v0
	v_mov_b32_e32 v95, v0
	v_mov_b32_e32 v104, v0
	v_mov_b32_e32 v105, v0
	v_mov_b32_e32 v106, v0
	v_mov_b32_e32 v107, v0
	v_mov_b32_e32 v108, v0
	v_mov_b32_e32 v109, v0
	v_mov_b32_e32 v110, v0
	v_mov_b32_e32 v111, v0
	v_mov_b32_e32 v120, v0
	v_mov_b32_e32 v121, v0
	v_mov_b32_e32 v122, v0
	v_mov_b32_e32 v123, v0
	v_mov_b32_e32 v124, v0
	v_mov_b32_e32 v125, v0
	v_mov_b32_e32 v126, v0
	v_mov_b32_e32 v127, v0
	v_add_u32_e32 v240, 0x18000, v149
	v_add_u32_e32 v241, 0x1c000, v149
	s_and_b64 vcc, exec, s[50:51]
	s_cbranch_vccz .Lsp0
	s_setprio 1
.Lsp0:
.LBB0_136:
	ds_read_b128 v[158:161], v152
	ds_read_b128 v[162:165], v152 offset:1024
	ds_read_b128 v[166:169], v152 offset:2048
	ds_read_b128 v[170:173], v152 offset:3072
	ds_read_b128 v[174:177], v153
	ds_read_b128 v[178:181], v153 offset:1024
	ds_read_b128 v[182:185], v153 offset:2048
	ds_read_b128 v[186:189], v153 offset:3072
	s_add_u32 s64, s62, 0xfffc0080
	s_addc_u32 s65, s63, -1
	s_cmp_eq_u32 s76, 12
	s_cselect_b32 s71, s5, s65
	s_cselect_b32 s70, s26, s64
	s_cselect_b32 s65, s27, s75
	s_cselect_b32 s64, s53, s55
	s_add_i32 m0, s61, 0xc000
	ds_read_b128 v[190:193], v154
	ds_read_b128 v[194:197], v154 offset:1024
	ds_read_b128 v[198:201], v154 offset:2048
	ds_read_b128 v[206:209], v154 offset:3072
	ds_read_b128 v[210:213], v154 offset:4096
	ds_read_b128 v[214:217], v154 offset:5120
	ds_read_b128 v[218:221], v154 offset:6144
	ds_read_b128 v[222:225], v154 offset:7168
	global_load_lds_dwordx4 v138, s[62:63]
	s_add_i32 m0, s61, 0xe000
	s_nop 0
	global_load_lds_dwordx4 v140, s[62:63]
	s_waitcnt vmcnt(8)
	s_waitcnt lgkmcnt(0)
	s_barrier
; #define PG8_STAGE(bufoff, gbase, voff) do { _Pragma("unroll") for (int _i = 0; _i < 2; ++_i) \
;         __builtin_amdgcn_global_load_lds((const unsigned*)((const char*)(gbase) + (voff)[_i]), (PG8_LAS unsigned*)(lds + (bufoff) + ldsw + _i * 8192), 16, 0, 0); } while (0)
; #define PG8_LDA(dst, b, h) do { _Pragma("unroll") for (int m = 0; m < 4; ++m) _Pragma("unroll") for (int k = 0; k < 2; ++k) dst[m][k] = *(const PG8_LAS bf16x8*)(lds + PG8_SA(b, h) + aoff + m * 2048 + k * 1024); } while (0)
; #define PG8_MMA(ai, bj, At, Bt) do { __builtin_amdgcn_s_setprio(1); _Pragma("unroll") for (int m = 0; m < 4; ++m) _Pragma("unroll") for (int n = 0; n < 2; ++n) _Pragma("unroll") for (int k = 0; k < 2; ++k) \
;         acc[ai][bj][m][n] = __builtin_amdgcn_mfma_f32_16x16x32_bf16(Bt[n][k], At[m][k], acc[ai][bj][m][n], 0, 0, 0); __builtin_amdgcn_s_setprio(0); } while (0)
; #define PG8_WAIT_V(n) asm volatile("s_waitcnt vmcnt(" #n ")" ::: "memory")
; #define PG8_WAIT_L(n) asm volatile("s_waitcnt lgkmcnt(" #n ")" ::: "memory")
; #define PG8_BAR __builtin_amdgcn_s_barrier()
; #define PG8_SCHED __builtin_amdgcn_sched_barrier(0)
; template <class Epi, class Sched, bool ALIGN_EPI = false, bool SP2 = false>
; __device__ __forceinline__ void gemm_phase(PG8_LAS unsigned char* lds, const Gemm g, const Sched& S, const Epi& E) {
;     ...
;             PG8_WAIT_V(8); PG8_WAIT_L(0); PG8_BAR; PG8_MMA(0, 0, At, B0); PG8_MMA(0, 1, At, B1); PG8_BAR; PG8_SCHED;
;             PG8_LDA(At, 0, 1); PG8_STAGE(PG8_SB(0, 0), b2, voffB); PG8_STAGE(PG8_SB(0, 1), b2 + hstep, voffB); PG8_STAGE(PG8_SA(0, 0), a2, voffA);
;             PG8_WAIT_V(8); PG8_WAIT_L(0); PG8_BAR; PG8_MMA(1, 0, At, B0); PG8_MMA(1, 1, At, B1); PG8_BAR; PG8_SCHED;
	v_mfma_f32_16x16x32_bf16 v[124:127], v[158:161], v[190:193], v[124:127]
	v_mfma_f32_16x16x32_bf16 v[120:123], v[166:169], v[190:193], v[120:123]
	v_mfma_f32_16x16x32_bf16 v[108:111], v[158:161], v[198:201], v[108:111]
	v_mfma_f32_16x16x32_bf16 v[104:107], v[166:169], v[198:201], v[104:107]
	v_mfma_f32_16x16x32_bf16 v[92:95], v[158:161], v[210:213], v[92:95]
	v_mfma_f32_16x16x32_bf16 v[88:91], v[166:169], v[210:213], v[88:91]
	v_mfma_f32_16x16x32_bf16 v[76:79], v[158:161], v[218:221], v[76:79]
	v_mfma_f32_16x16x32_bf16 v[72:75], v[166:169], v[218:221], v[72:75]
	v_mfma_f32_16x16x32_bf16 v[124:127], v[162:165], v[194:197], v[124:127]
	v_mfma_f32_16x16x32_bf16 v[120:123], v[170:173], v[194:197], v[120:123]
	v_mfma_f32_16x16x32_bf16 v[108:111], v[162:165], v[206:209], v[108:111]
	v_mfma_f32_16x16x32_bf16 v[104:107], v[170:173], v[206:209], v[104:107]
	v_mfma_f32_16x16x32_bf16 v[92:95], v[162:165], v[214:217], v[92:95]
	v_mfma_f32_16x16x32_bf16 v[88:91], v[170:173], v[214:217], v[88:91]
	v_mfma_f32_16x16x32_bf16 v[76:79], v[162:165], v[222:225], v[76:79]
	v_mfma_f32_16x16x32_bf16 v[72:75], v[170:173], v[222:225], v[72:75]
	v_mfma_f32_16x16x32_bf16 v[116:119], v[174:177], v[190:193], v[116:119]
	v_mfma_f32_16x16x32_bf16 v[112:115], v[182:185], v[190:193], v[112:115]
	v_mfma_f32_16x16x32_bf16 v[100:103], v[174:177], v[198:201], v[100:103]
	v_mfma_f32_16x16x32_bf16 v[96:99], v[182:185], v[198:201], v[96:99]
	v_mfma_f32_16x16x32_bf16 v[84:87], v[174:177], v[210:213], v[84:87]
	v_mfma_f32_16x16x32_bf16 v[80:83], v[182:185], v[210:213], v[80:83]
	v_mfma_f32_16x16x32_bf16 v[68:71], v[174:177], v[218:221], v[68:71]
	v_mfma_f32_16x16x32_bf16 v[64:67], v[182:185], v[218:221], v[64:67]
	v_mfma_f32_16x16x32_bf16 v[116:119], v[178:181], v[194:197], v[116:119]
	v_mfma_f32_16x16x32_bf16 v[112:115], v[186:189], v[194:197], v[112:115]
	v_mfma_f32_16x16x32_bf16 v[100:103], v[178:181], v[206:209], v[100:103]
	v_mfma_f32_16x16x32_bf16 v[96:99], v[186:189], v[206:209], v[96:99]
	v_mfma_f32_16x16x32_bf16 v[84:87], v[178:181], v[214:217], v[84:87]
	v_mfma_f32_16x16x32_bf16 v[80:83], v[186:189], v[214:217], v[80:83]
	v_mfma_f32_16x16x32_bf16 v[68:71], v[178:181], v[222:225], v[68:71]
	v_mfma_f32_16x16x32_bf16 v[64:67], v[186:189], v[222:225], v[64:67]
	s_barrier
	s_add_i32 s77, s72, s33
	s_mov_b32 m0, s77
	ds_read_b128 v[190:193], v154 offset:16384
	ds_read_b128 v[194:197], v154 offset:17408
	ds_read_b128 v[198:201], v154 offset:18432
	ds_read_b128 v[206:209], v154 offset:19456
	ds_read_b128 v[210:213], v154 offset:20480
	ds_read_b128 v[214:217], v154 offset:21504
	ds_read_b128 v[218:221], v154 offset:22528
	ds_read_b128 v[222:225], v154 offset:23552
	global_load_lds_dwordx4 v132, s[64:65]
	s_add_i32 m0, s77, 0x2000
	s_add_u32 s98, s64, 0x80
	s_addc_u32 s99, s65, 0
	s_add_u32 s78, s64, 0x40000
	s_addc_u32 s79, s65, 0
	s_add_i32 s77, s73, s33
	global_load_lds_dwordx4 v136, s[64:65]
	s_mov_b32 m0, s77
	s_nop 0
	global_load_lds_dwordx4 v132, s[78:79]
	s_add_i32 m0, s77, 0x2000
	s_nop 0
	global_load_lds_dwordx4 v136, s[78:79]
	s_mov_b32 m0, s61
	s_nop 0
	global_load_lds_dwordx4 v130, s[70:71]
	s_mov_b32 m0, s66
	s_nop 0
	global_load_lds_dwordx4 v134, s[70:71]
	s_waitcnt vmcnt(8)
	s_waitcnt lgkmcnt(0)
	s_barrier
	v_mfma_f32_16x16x32_bf16 v[60:63], v[158:161], v[190:193], v[60:63]
	v_mfma_f32_16x16x32_bf16 v[56:59], v[166:169], v[190:193], v[56:59]
	v_mfma_f32_16x16x32_bf16 v[44:47], v[158:161], v[198:201], v[44:47]
	v_mfma_f32_16x16x32_bf16 v[40:43], v[166:169], v[198:201], v[40:43]
	v_mfma_f32_16x16x32_bf16 v[28:31], v[158:161], v[210:213], v[28:31]
	v_mfma_f32_16x16x32_bf16 v[24:27], v[166:169], v[210:213], v[24:27]
	v_mfma_f32_16x16x32_bf16 v[12:15], v[158:161], v[218:221], v[12:15]
	v_mfma_f32_16x16x32_bf16 v[8:11], v[166:169], v[218:221], v[8:11]
	v_mfma_f32_16x16x32_bf16 v[60:63], v[162:165], v[194:197], v[60:63]
	v_mfma_f32_16x16x32_bf16 v[56:59], v[170:173], v[194:197], v[56:59]
	v_mfma_f32_16x16x32_bf16 v[44:47], v[162:165], v[206:209], v[44:47]
	v_mfma_f32_16x16x32_bf16 v[40:43], v[170:173], v[206:209], v[40:43]
	v_mfma_f32_16x16x32_bf16 v[28:31], v[162:165], v[214:217], v[28:31]
	v_mfma_f32_16x16x32_bf16 v[24:27], v[170:173], v[214:217], v[24:27]
	v_mfma_f32_16x16x32_bf16 v[12:15], v[162:165], v[222:225], v[12:15]
	v_mfma_f32_16x16x32_bf16 v[8:11], v[170:173], v[222:225], v[8:11]
	v_mfma_f32_16x16x32_bf16 v[52:55], v[174:177], v[190:193], v[52:55]
	v_mfma_f32_16x16x32_bf16 v[48:51], v[182:185], v[190:193], v[48:51]
	v_mfma_f32_16x16x32_bf16 v[36:39], v[174:177], v[198:201], v[36:39]
	v_mfma_f32_16x16x32_bf16 v[32:35], v[182:185], v[198:201], v[32:35]
	v_mfma_f32_16x16x32_bf16 v[20:23], v[174:177], v[210:213], v[20:23]
	v_mfma_f32_16x16x32_bf16 v[16:19], v[182:185], v[210:213], v[16:19]
	v_mfma_f32_16x16x32_bf16 v[4:7], v[174:177], v[218:221], v[4:7]
	v_mfma_f32_16x16x32_bf16 v[0:3], v[182:185], v[218:221], v[0:3]
	v_mfma_f32_16x16x32_bf16 v[52:55], v[178:181], v[194:197], v[52:55]
	v_mfma_f32_16x16x32_bf16 v[48:51], v[186:189], v[194:197], v[48:51]
	v_mfma_f32_16x16x32_bf16 v[36:39], v[178:181], v[206:209], v[36:39]
	v_mfma_f32_16x16x32_bf16 v[32:35], v[186:189], v[206:209], v[32:35]
	v_mfma_f32_16x16x32_bf16 v[20:23], v[178:181], v[214:217], v[20:23]
	v_mfma_f32_16x16x32_bf16 v[16:19], v[186:189], v[214:217], v[16:19]
	v_mfma_f32_16x16x32_bf16 v[4:7], v[178:181], v[222:225], v[4:7]
	v_mfma_f32_16x16x32_bf16 v[0:3], v[186:189], v[222:225], v[0:3]
	s_barrier
; #define PG8_STAGE(bufoff, gbase, voff) do { _Pragma("unroll") for (int _i = 0; _i < 2; ++_i) \
;         __builtin_amdgcn_global_load_lds((const unsigned*)((const char*)(gbase) + (voff)[_i]), (PG8_LAS unsigned*)(lds + (bufoff) + ldsw + _i * 8192), 16, 0, 0); } while (0)
; #define PG8_LDA(dst, b, h) do { _Pragma("unroll") for (int m = 0; m < 4; ++m) _Pragma("unroll") for (int k = 0; k < 2; ++k) dst[m][k] = *(const PG8_LAS bf16x8*)(lds + PG8_SA(b, h) + aoff + m * 2048 + k * 1024); } while (0)
; #define PG8_LDB(dst, b, h) do { _Pragma("unroll") for (int n = 0; n < 2; ++n) _Pragma("unroll") for (int k = 0; k < 2; ++k) dst[n][k] = *(const PG8_LAS bf16x8*)(lds + PG8_SB(b, h) + boff + n * 2048 + k * 1024); } while (0)
; #define PG8_MMA(ai, bj, At, Bt) do { __builtin_amdgcn_s_setprio(1); _Pragma("unroll") for (int m = 0; m < 4; ++m) _Pragma("unroll") for (int n = 0; n < 2; ++n) _Pragma("unroll") for (int k = 0; k < 2; ++k) \
;         acc[ai][bj][m][n] = __builtin_amdgcn_mfma_f32_16x16x32_bf16(Bt[n][k], At[m][k], acc[ai][bj][m][n], 0, 0, 0); __builtin_amdgcn_s_setprio(0); } while (0)
; #define PG8_WAIT_V(n) asm volatile("s_waitcnt vmcnt(" #n ")" ::: "memory")
; #define PG8_WAIT_L(n) asm volatile("s_waitcnt lgkmcnt(" #n ")" ::: "memory")
; #define PG8_BAR __builtin_amdgcn_s_barrier()
; #define PG8_SCHED __builtin_amdgcn_sched_barrier(0)
; template <class Epi, class Sched, bool ALIGN_EPI = false, bool SP2 = false>
; __device__ __forceinline__ void gemm_phase(PG8_LAS unsigned char* lds, const Gemm g, const Sched& S, const Epi& E) {
;     ...
;             PG8_LDB(B0, 1, 0); PG8_LDB(B1, 1, 1); PG8_SCHED; PG8_LDA(At, 1, 0); PG8_STAGE(PG8_SA(0, 1), a2 + hstep, voffA);
;             PG8_WAIT_V(8); PG8_WAIT_L(0); PG8_BAR; PG8_MMA(0, 0, At, B0); PG8_MMA(0, 1, At, B1); PG8_BAR; PG8_SCHED;
;             PG8_LDA(At, 1, 1); PG8_STAGE(PG8_SB(1, 0), b3, voffB); PG8_STAGE(PG8_SB(1, 1), b3 + hstep, voffB); PG8_STAGE(PG8_SA(1, 0), a3, voffA);
;             PG8_WAIT_V(8); PG8_WAIT_L(0); PG8_BAR; PG8_MMA(1, 0, At, B0); PG8_MMA(1, 1, At, B1); PG8_BAR; PG8_SCHED;
;     ...
;         }
;         if constexpr (ALIGN_EPI) { if (wr == 0) PG8_BAR; }
	s_add_i32 s77, 0, 0x18000
	s_add_i32 s78, 0, 0x1c000
	ds_read_b128 v[158:161], v240
	ds_read_b128 v[162:165], v240 offset:1024
	ds_read_b128 v[166:169], v240 offset:2048
	ds_read_b128 v[170:173], v240 offset:3072
	ds_read_b128 v[174:177], v241
	ds_read_b128 v[178:181], v241 offset:1024
	ds_read_b128 v[182:185], v241 offset:2048
	ds_read_b128 v[186:189], v241 offset:3072
	s_add_u32 s100, s70, 0x80
	s_addc_u32 s101, s71, 0
	s_add_u32 s70, s70, 0x40000
	s_addc_u32 s71, s71, 0
	s_mov_b32 m0, s67
	ds_read_b128 v[190:193], v154 offset:32768
	ds_read_b128 v[194:197], v154 offset:33792
	ds_read_b128 v[198:201], v154 offset:34816
	ds_read_b128 v[206:209], v154 offset:35840
	ds_read_b128 v[210:213], v154 offset:36864
	ds_read_b128 v[214:217], v154 offset:37888
	ds_read_b128 v[218:221], v154 offset:38912
	ds_read_b128 v[222:225], v154 offset:39936
	global_load_lds_dwordx4 v130, s[70:71]
	s_mov_b32 m0, s88
	s_nop 0
	global_load_lds_dwordx4 v134, s[70:71]
	s_waitcnt vmcnt(8)
	s_waitcnt lgkmcnt(0)
	s_barrier
	v_mfma_f32_16x16x32_bf16 v[124:127], v[158:161], v[190:193], v[124:127]
	v_mfma_f32_16x16x32_bf16 v[120:123], v[166:169], v[190:193], v[120:123]
	v_mfma_f32_16x16x32_bf16 v[108:111], v[158:161], v[198:201], v[108:111]
	v_mfma_f32_16x16x32_bf16 v[104:107], v[166:169], v[198:201], v[104:107]
	v_mfma_f32_16x16x32_bf16 v[92:95], v[158:161], v[210:213], v[92:95]
	v_mfma_f32_16x16x32_bf16 v[88:91], v[166:169], v[210:213], v[88:91]
	v_mfma_f32_16x16x32_bf16 v[76:79], v[158:161], v[218:221], v[76:79]
	v_mfma_f32_16x16x32_bf16 v[72:75], v[166:169], v[218:221], v[72:75]
	v_mfma_f32_16x16x32_bf16 v[124:127], v[162:165], v[194:197], v[124:127]
	v_mfma_f32_16x16x32_bf16 v[120:123], v[170:173], v[194:197], v[120:123]
	v_mfma_f32_16x16x32_bf16 v[108:111], v[162:165], v[206:209], v[108:111]
	v_mfma_f32_16x16x32_bf16 v[104:107], v[170:173], v[206:209], v[104:107]
	v_mfma_f32_16x16x32_bf16 v[92:95], v[162:165], v[214:217], v[92:95]
	v_mfma_f32_16x16x32_bf16 v[88:91], v[170:173], v[214:217], v[88:91]
	v_mfma_f32_16x16x32_bf16 v[76:79], v[162:165], v[222:225], v[76:79]
	v_mfma_f32_16x16x32_bf16 v[72:75], v[170:173], v[222:225], v[72:75]
	v_mfma_f32_16x16x32_bf16 v[116:119], v[174:177], v[190:193], v[116:119]
	v_mfma_f32_16x16x32_bf16 v[112:115], v[182:185], v[190:193], v[112:115]
	v_mfma_f32_16x16x32_bf16 v[100:103], v[174:177], v[198:201], v[100:103]
	v_mfma_f32_16x16x32_bf16 v[96:99], v[182:185], v[198:201], v[96:99]
	v_mfma_f32_16x16x32_bf16 v[84:87], v[174:177], v[210:213], v[84:87]
	v_mfma_f32_16x16x32_bf16 v[80:83], v[182:185], v[210:213], v[80:83]
	v_mfma_f32_16x16x32_bf16 v[68:71], v[174:177], v[218:221], v[68:71]
	v_mfma_f32_16x16x32_bf16 v[64:67], v[182:185], v[218:221], v[64:67]
	v_mfma_f32_16x16x32_bf16 v[116:119], v[178:181], v[194:197], v[116:119]
	v_mfma_f32_16x16x32_bf16 v[112:115], v[186:189], v[194:197], v[112:115]
	v_mfma_f32_16x16x32_bf16 v[100:103], v[178:181], v[206:209], v[100:103]
	v_mfma_f32_16x16x32_bf16 v[96:99], v[186:189], v[206:209], v[96:99]
	v_mfma_f32_16x16x32_bf16 v[84:87], v[178:181], v[214:217], v[84:87]
	v_mfma_f32_16x16x32_bf16 v[80:83], v[186:189], v[214:217], v[80:83]
	v_mfma_f32_16x16x32_bf16 v[68:71], v[178:181], v[222:225], v[68:71]
	v_mfma_f32_16x16x32_bf16 v[64:67], v[186:189], v[222:225], v[64:67]
	s_barrier
	s_add_i32 s70, s77, s33
	s_mov_b32 m0, s70
	ds_read_b128 v[190:193], v154 offset:49152
	ds_read_b128 v[194:197], v154 offset:50176
	ds_read_b128 v[198:201], v154 offset:51200
	ds_read_b128 v[206:209], v154 offset:52224
	ds_read_b128 v[210:213], v154 offset:53248
	ds_read_b128 v[214:217], v154 offset:54272
	ds_read_b128 v[218:221], v154 offset:55296
	ds_read_b128 v[222:225], v154 offset:56320
	global_load_lds_dwordx4 v132, s[98:99]
	s_add_i32 m0, s70, 0x2000
	s_add_u32 s64, s64, 0x40080
	s_addc_u32 s65, s65, 0
	s_add_i32 s70, s78, s33
	global_load_lds_dwordx4 v136, s[98:99]
	s_mov_b32 m0, s70
	s_nop 0
	global_load_lds_dwordx4 v132, s[64:65]
	s_add_i32 m0, s70, 0x2000
	s_nop 0
	global_load_lds_dwordx4 v136, s[64:65]
	s_mov_b32 m0, s3
	s_nop 0
	global_load_lds_dwordx4 v130, s[100:101]
	s_mov_b32 m0, s68
	s_nop 0
	global_load_lds_dwordx4 v134, s[100:101]
	s_waitcnt vmcnt(8)
	s_waitcnt lgkmcnt(0)
	s_barrier
	v_mfma_f32_16x16x32_bf16 v[60:63], v[158:161], v[190:193], v[60:63]
	v_mfma_f32_16x16x32_bf16 v[56:59], v[166:169], v[190:193], v[56:59]
	v_mfma_f32_16x16x32_bf16 v[44:47], v[158:161], v[198:201], v[44:47]
	v_mfma_f32_16x16x32_bf16 v[40:43], v[166:169], v[198:201], v[40:43]
	v_mfma_f32_16x16x32_bf16 v[28:31], v[158:161], v[210:213], v[28:31]
	v_mfma_f32_16x16x32_bf16 v[24:27], v[166:169], v[210:213], v[24:27]
	v_mfma_f32_16x16x32_bf16 v[12:15], v[158:161], v[218:221], v[12:15]
	v_mfma_f32_16x16x32_bf16 v[8:11], v[166:169], v[218:221], v[8:11]
	v_mfma_f32_16x16x32_bf16 v[60:63], v[162:165], v[194:197], v[60:63]
	v_mfma_f32_16x16x32_bf16 v[56:59], v[170:173], v[194:197], v[56:59]
	v_mfma_f32_16x16x32_bf16 v[44:47], v[162:165], v[206:209], v[44:47]
	v_mfma_f32_16x16x32_bf16 v[40:43], v[170:173], v[206:209], v[40:43]
	v_mfma_f32_16x16x32_bf16 v[28:31], v[162:165], v[214:217], v[28:31]
	v_mfma_f32_16x16x32_bf16 v[24:27], v[170:173], v[214:217], v[24:27]
	v_mfma_f32_16x16x32_bf16 v[12:15], v[162:165], v[222:225], v[12:15]
	v_mfma_f32_16x16x32_bf16 v[8:11], v[170:173], v[222:225], v[8:11]
	v_mfma_f32_16x16x32_bf16 v[52:55], v[174:177], v[190:193], v[52:55]
	v_mfma_f32_16x16x32_bf16 v[48:51], v[182:185], v[190:193], v[48:51]
	v_mfma_f32_16x16x32_bf16 v[36:39], v[174:177], v[198:201], v[36:39]
	v_mfma_f32_16x16x32_bf16 v[32:35], v[182:185], v[198:201], v[32:35]
	v_mfma_f32_16x16x32_bf16 v[20:23], v[174:177], v[210:213], v[20:23]
	v_mfma_f32_16x16x32_bf16 v[16:19], v[182:185], v[210:213], v[16:19]
	v_mfma_f32_16x16x32_bf16 v[4:7], v[174:177], v[218:221], v[4:7]
	v_mfma_f32_16x16x32_bf16 v[0:3], v[182:185], v[218:221], v[0:3]
	v_mfma_f32_16x16x32_bf16 v[52:55], v[178:181], v[194:197], v[52:55]
	v_mfma_f32_16x16x32_bf16 v[48:51], v[186:189], v[194:197], v[48:51]
	v_mfma_f32_16x16x32_bf16 v[36:39], v[178:181], v[206:209], v[36:39]
	v_mfma_f32_16x16x32_bf16 v[32:35], v[186:189], v[206:209], v[32:35]
	v_mfma_f32_16x16x32_bf16 v[20:23], v[178:181], v[214:217], v[20:23]
	v_mfma_f32_16x16x32_bf16 v[16:19], v[186:189], v[214:217], v[16:19]
	v_mfma_f32_16x16x32_bf16 v[4:7], v[178:181], v[222:225], v[4:7]
	v_mfma_f32_16x16x32_bf16 v[0:3], v[186:189], v[222:225], v[0:3]
	s_barrier
	s_add_i32 s76, s76, 2
	s_add_u32 s62, s62, 0x100
	s_addc_u32 s63, s63, 0
	s_add_u32 s55, s55, 0x100
	s_addc_u32 s75, s75, 0
	s_cmp_gt_u32 s76, 13
	s_cbranch_scc0 .LBB0_136
	s_setprio 0
	s_and_b64 vcc, exec, s[50:51]
	s_cbranch_vccz .LBB0_139
	s_barrier

; #define PG8_STAGE(bufoff, gbase, voff) do { _Pragma("unroll") for (int _i = 0; _i < 2; ++_i) \
;         __builtin_amdgcn_global_load_lds((const unsigned*)((const char*)(gbase) + (voff)[_i]), (PG8_LAS unsigned*)(lds + (bufoff) + ldsw + _i * 8192), 16, 0, 0); } while (0)
; #define PG8_LDA(dst, b, h) do { _Pragma("unroll") for (int m = 0; m < 4; ++m) _Pragma("unroll") for (int k = 0; k < 2; ++k) dst[m][k] = *(const PG8_LAS bf16x8*)(lds + PG8_SA(b, h) + aoff + m * 2048 + k * 1024); } while (0)
; #define PG8_LDB(dst, b, h) do { _Pragma("unroll") for (int n = 0; n < 2; ++n) _Pragma("unroll") for (int k = 0; k < 2; ++k) dst[n][k] = *(const PG8_LAS bf16x8*)(lds + PG8_SB(b, h) + boff + n * 2048 + k * 1024); } while (0)
; #define PG8_WAIT_V(n) asm volatile("s_waitcnt vmcnt(" #n ")" ::: "memory")
; #define PG8_WAIT_L(n) asm volatile("s_waitcnt lgkmcnt(" #n ")" ::: "memory")
; #define PG8_BAR __builtin_amdgcn_s_barrier()
; #define PG8_SCHED __builtin_amdgcn_sched_barrier(0)
; template <class Epi, class Sched, bool ALIGN_EPI = false, bool SP2 = false>
; __device__ __forceinline__ void gemm_phase(PG8_LAS unsigned char* lds, const Gemm g, const Sched& S, const Epi& E) {
;     ...
;         const bool has_next = S.next(ui + 1, nxt);
;         const char* nA = has_next ? (const char*)g.A + (size_t)nxt.pm * tstep : cA; const char* nB = has_next ? (const char*)g.Bt + (size_t)nxt.pn * tstep : cB;
;         for (int t = 0; t < nt; t += 2) {
;             const bool last = (t == nt - 2);
;             const char* a1 = cA + (size_t)(t + 1) * kstep;
;             const char* a2 = last ? nA : cA + (size_t)(t + 2) * kstep; const char* b2 = last ? nB : cB + (size_t)(t + 2) * kstep;
;             const char* a3 = a2 + kstep; const char* b3 = b2 + kstep;
;             if (last && has_next) S.a_ready(nxt);
;             if constexpr (SP2) {
;             PG8_LDB(B0, 0, 0); PG8_LDB(B1, 0, 1); PG8_SCHED; PG8_LDA(At, 0, 0); PG8_STAGE(PG8_SA(1, 1), a1 + hstep, voffA);
;             PG8_WAIT_V(8); PG8_WAIT_L(0); PG8_BAR; PG8_MMA(0, 0, At, B0); PG8_MMA(0, 1, At, B1); PG8_BAR; PG8_SCHED;
;     ...
;         for (int a = 0; a < 2; ++a)
; #pragma unroll
;             for (int b = 0; b < 2; ++b)
; #pragma unroll
;                 for (int m = 0; m < 4; ++m)
; #pragma unroll
;                     for (int n = 0; n < 2; ++n) acc[a][b][m][n] = (f32x4){0.f, 0.f, 0.f, 0.f};
;         cur = nxt; cA = nA; cB = nB; ++ui;
.LBB0_519:
	s_ashr_i32 s35, s34, 31
	s_lshl_b64 s[36:37], s[34:35], 19
	s_add_u32 s36, s70, s36
	s_addc_u32 s37, s71, s37
	s_and_b64 s[38:39], s[6:7], exec
	s_cselect_b32 s35, s37, s45
	s_cselect_b32 s41, s36, s44
	s_ashr_i32 s31, s30, 31
	s_lshl_b64 s[38:39], s[30:31], 19
	v_readlane_b32 s14, v255, 28
	v_readlane_b32 s15, v255, 29
	s_add_u32 s38, s14, s38
	s_addc_u32 s39, s15, s39
	s_and_b64 s[48:49], s[6:7], exec
	s_cselect_b32 s31, s39, s47
	s_cselect_b32 s60, s38, s46
	s_add_u32 s44, s44, 0x40080
	s_addc_u32 s45, s45, 0
	s_add_u32 s61, s46, 0x100
	v_mov_b32_e32 v0, 0
	s_addc_u32 s62, s47, 0
	s_mov_b32 s63, -2
	s_waitcnt lgkmcnt(0)
	v_mov_b32_e32 v1, v0
	v_mov_b32_e32 v2, v0
	v_mov_b32_e32 v3, v0
	v_mov_b32_e32 v4, v0
	v_mov_b32_e32 v5, v0
	v_mov_b32_e32 v6, v0
	v_mov_b32_e32 v7, v0
	v_mov_b32_e32 v16, v0
	v_mov_b32_e32 v17, v0
	v_mov_b32_e32 v18, v0
	v_mov_b32_e32 v19, v0
	v_mov_b32_e32 v20, v0
	v_mov_b32_e32 v21, v0
	v_mov_b32_e32 v22, v0
	v_mov_b32_e32 v23, v0
	v_mov_b32_e32 v32, v0
	v_mov_b32_e32 v33, v0
	v_mov_b32_e32 v34, v0
	v_mov_b32_e32 v35, v0
	v_mov_b32_e32 v36, v0
	v_mov_b32_e32 v37, v0
	v_mov_b32_e32 v38, v0
	v_mov_b32_e32 v39, v0
	v_mov_b32_e32 v48, v0
	v_mov_b32_e32 v49, v0
	v_mov_b32_e32 v50, v0
	v_mov_b32_e32 v51, v0
	v_mov_b32_e32 v52, v0
	v_mov_b32_e32 v53, v0
	v_mov_b32_e32 v54, v0
	v_mov_b32_e32 v55, v0
	v_mov_b32_e32 v8, v0
	v_mov_b32_e32 v9, v0
	v_mov_b32_e32 v10, v0
	v_mov_b32_e32 v11, v0
	v_mov_b32_e32 v12, v0
	v_mov_b32_e32 v13, v0
	v_mov_b32_e32 v14, v0
	v_mov_b32_e32 v15, v0
	v_mov_b32_e32 v24, v0
	v_mov_b32_e32 v25, v0
	v_mov_b32_e32 v26, v0
	v_mov_b32_e32 v27, v0
	v_mov_b32_e32 v28, v0
	v_mov_b32_e32 v29, v0
	v_mov_b32_e32 v30, v0
	v_mov_b32_e32 v31, v0
	v_mov_b32_e32 v40, v0
	v_mov_b32_e32 v41, v0
	v_mov_b32_e32 v42, v0
	v_mov_b32_e32 v43, v0
	v_mov_b32_e32 v44, v0
	v_mov_b32_e32 v45, v0
	v_mov_b32_e32 v46, v0
	v_mov_b32_e32 v47, v0
	v_mov_b32_e32 v56, v0
	v_mov_b32_e32 v57, v0
	v_mov_b32_e32 v58, v0
	v_mov_b32_e32 v59, v0
	v_mov_b32_e32 v60, v0
	v_mov_b32_e32 v61, v0
	v_mov_b32_e32 v62, v0
	v_mov_b32_e32 v63, v0
	v_mov_b32_e32 v64, v0
	v_mov_b32_e32 v65, v0
	v_mov_b32_e32 v66, v0
	v_mov_b32_e32 v67, v0
	v_mov_b32_e32 v68, v0
	v_mov_b32_e32 v69, v0
	v_mov_b32_e32 v70, v0
	v_mov_b32_e32 v71, v0
	v_mov_b32_e32 v80, v0
	v_mov_b32_e32 v81, v0
	v_mov_b32_e32 v82, v0
	v_mov_b32_e32 v83, v0
	v_mov_b32_e32 v84, v0
	v_mov_b32_e32 v85, v0
	v_mov_b32_e32 v86, v0
	v_mov_b32_e32 v87, v0
	v_mov_b32_e32 v96, v0
	v_mov_b32_e32 v97, v0
	v_mov_b32_e32 v98, v0
	v_mov_b32_e32 v99, v0
	v_mov_b32_e32 v100, v0
	v_mov_b32_e32 v101, v0
	v_mov_b32_e32 v102, v0
	v_mov_b32_e32 v103, v0
	v_mov_b32_e32 v112, v0
	v_mov_b32_e32 v113, v0
	v_mov_b32_e32 v114, v0
	v_mov_b32_e32 v115, v0
	v_mov_b32_e32 v116, v0
	v_mov_b32_e32 v117, v0
	v_mov_b32_e32 v118, v0
	v_mov_b32_e32 v119, v0
	v_mov_b32_e32 v72, v0
	v_mov_b32_e32 v73, v0
	v_mov_b32_e32 v74, v0
	v_mov_b32_e32 v75, v0
	v_mov_b32_e32 v76, v0
	v_mov_b32_e32 v77, v0
	v_mov_b32_e32 v78, v0
	v_mov_b32_e32 v79, v0
	v_mov_b32_e32 v88, v0
	v_mov_b32_e32 v89, v0
	v_mov_b32_e32 v90, v0
	v_mov_b32_e32 v91, v0
	v_mov_b32_e32 v92, v0
	v_mov_b32_e32 v93, v0
	v_mov_b32_e32 v94, v0
	v_mov_b32_e32 v95, v0
	v_mov_b32_e32 v104, v0
	v_mov_b32_e32 v105, v0
	v_mov_b32_e32 v106, v0
	v_mov_b32_e32 v107, v0
	v_mov_b32_e32 v108, v0
	v_mov_b32_e32 v109, v0
	v_mov_b32_e32 v110, v0
	v_mov_b32_e32 v111, v0
	v_mov_b32_e32 v120, v0
	v_mov_b32_e32 v121, v0
	v_mov_b32_e32 v122, v0
	v_mov_b32_e32 v123, v0
	v_mov_b32_e32 v124, v0
	v_mov_b32_e32 v125, v0
	v_mov_b32_e32 v126, v0
	v_mov_b32_e32 v127, v0
	v_add_u32_e32 v240, 0x18000, v150
	v_add_u32_e32 v241, 0x1c000, v150
	s_and_b64 vcc, exec, s[28:29]
	s_cbranch_vccz .Lsp1
	s_setprio 1
.Lsp1:
.LBB0_520:
	ds_read_b128 v[146:149], v152
	ds_read_b128 v[156:159], v152 offset:1024
	ds_read_b128 v[160:163], v152 offset:2048
	ds_read_b128 v[164:167], v152 offset:3072
	ds_read_b128 v[168:171], v153
	ds_read_b128 v[172:175], v153 offset:1024
	ds_read_b128 v[176:179], v153 offset:2048
	ds_read_b128 v[180:183], v153 offset:3072
	s_add_u32 s46, s44, 0xfffc0080
	s_addc_u32 s47, s45, -1
	s_cmp_eq_u32 s63, 12
	s_cselect_b32 s49, s35, s47
	s_cselect_b32 s48, s41, s46
	s_cselect_b32 s47, s31, s62
	s_cselect_b32 s46, s60, s61
	s_add_i32 m0, s43, 0xc000
	ds_read_b128 v[184:187], v154
	ds_read_b128 v[188:191], v154 offset:1024
	ds_read_b128 v[192:195], v154 offset:2048
	ds_read_b128 v[196:199], v154 offset:3072
	ds_read_b128 v[200:203], v154 offset:4096
	ds_read_b128 v[206:209], v154 offset:5120
	ds_read_b128 v[210:213], v154 offset:6144
	ds_read_b128 v[214:217], v154 offset:7168
	global_load_lds_dwordx4 v138, s[44:45]
	s_add_i32 m0, s43, 0xe000
	s_nop 0
	global_load_lds_dwordx4 v140, s[44:45]
	s_waitcnt vmcnt(8)
	s_waitcnt lgkmcnt(0)
	s_barrier
; #define PG8_STAGE(bufoff, gbase, voff) do { _Pragma("unroll") for (int _i = 0; _i < 2; ++_i) \
;         __builtin_amdgcn_global_load_lds((const unsigned*)((const char*)(gbase) + (voff)[_i]), (PG8_LAS unsigned*)(lds + (bufoff) + ldsw + _i * 8192), 16, 0, 0); } while (0)
; #define PG8_LDA(dst, b, h) do { _Pragma("unroll") for (int m = 0; m < 4; ++m) _Pragma("unroll") for (int k = 0; k < 2; ++k) dst[m][k] = *(const PG8_LAS bf16x8*)(lds + PG8_SA(b, h) + aoff + m * 2048 + k * 1024); } while (0)
; #define PG8_MMA(ai, bj, At, Bt) do { __builtin_amdgcn_s_setprio(1); _Pragma("unroll") for (int m = 0; m < 4; ++m) _Pragma("unroll") for (int n = 0; n < 2; ++n) _Pragma("unroll") for (int k = 0; k < 2; ++k) \
;         acc[ai][bj][m][n] = __builtin_amdgcn_mfma_f32_16x16x32_bf16(Bt[n][k], At[m][k], acc[ai][bj][m][n], 0, 0, 0); __builtin_amdgcn_s_setprio(0); } while (0)
; #define PG8_WAIT_V(n) asm volatile("s_waitcnt vmcnt(" #n ")" ::: "memory")
; #define PG8_WAIT_L(n) asm volatile("s_waitcnt lgkmcnt(" #n ")" ::: "memory")
; #define PG8_BAR __builtin_amdgcn_s_barrier()
; #define PG8_SCHED __builtin_amdgcn_sched_barrier(0)
; template <class Epi, class Sched, bool ALIGN_EPI = false, bool SP2 = false>
; __device__ __forceinline__ void gemm_phase(PG8_LAS unsigned char* lds, const Gemm g, const Sched& S, const Epi& E) {
;     ...
;             PG8_WAIT_V(8); PG8_WAIT_L(0); PG8_BAR; PG8_MMA(0, 0, At, B0); PG8_MMA(0, 1, At, B1); PG8_BAR; PG8_SCHED;
;             PG8_LDA(At, 0, 1); PG8_STAGE(PG8_SB(0, 0), b2, voffB); PG8_STAGE(PG8_SB(0, 1), b2 + hstep, voffB); PG8_STAGE(PG8_SA(0, 0), a2, voffA);
;             PG8_WAIT_V(8); PG8_WAIT_L(0); PG8_BAR; PG8_MMA(1, 0, At, B0); PG8_MMA(1, 1, At, B1); PG8_BAR; PG8_SCHED;
	v_mfma_f32_16x16x32_bf16 v[124:127], v[146:149], v[184:187], v[124:127]
	v_mfma_f32_16x16x32_bf16 v[120:123], v[160:163], v[184:187], v[120:123]
	v_mfma_f32_16x16x32_bf16 v[108:111], v[146:149], v[192:195], v[108:111]
	v_mfma_f32_16x16x32_bf16 v[104:107], v[160:163], v[192:195], v[104:107]
	v_mfma_f32_16x16x32_bf16 v[92:95], v[146:149], v[200:203], v[92:95]
	v_mfma_f32_16x16x32_bf16 v[88:91], v[160:163], v[200:203], v[88:91]
	v_mfma_f32_16x16x32_bf16 v[76:79], v[146:149], v[210:213], v[76:79]
	v_mfma_f32_16x16x32_bf16 v[72:75], v[160:163], v[210:213], v[72:75]
	v_mfma_f32_16x16x32_bf16 v[124:127], v[156:159], v[188:191], v[124:127]
	v_mfma_f32_16x16x32_bf16 v[120:123], v[164:167], v[188:191], v[120:123]
	v_mfma_f32_16x16x32_bf16 v[108:111], v[156:159], v[196:199], v[108:111]
	v_mfma_f32_16x16x32_bf16 v[104:107], v[164:167], v[196:199], v[104:107]
	v_mfma_f32_16x16x32_bf16 v[92:95], v[156:159], v[206:209], v[92:95]
	v_mfma_f32_16x16x32_bf16 v[88:91], v[164:167], v[206:209], v[88:91]
	v_mfma_f32_16x16x32_bf16 v[76:79], v[156:159], v[214:217], v[76:79]
	v_mfma_f32_16x16x32_bf16 v[72:75], v[164:167], v[214:217], v[72:75]
	v_mfma_f32_16x16x32_bf16 v[116:119], v[168:171], v[184:187], v[116:119]
	v_mfma_f32_16x16x32_bf16 v[112:115], v[176:179], v[184:187], v[112:115]
	v_mfma_f32_16x16x32_bf16 v[100:103], v[168:171], v[192:195], v[100:103]
	v_mfma_f32_16x16x32_bf16 v[96:99], v[176:179], v[192:195], v[96:99]
	v_mfma_f32_16x16x32_bf16 v[84:87], v[168:171], v[200:203], v[84:87]
	v_mfma_f32_16x16x32_bf16 v[80:83], v[176:179], v[200:203], v[80:83]
	v_mfma_f32_16x16x32_bf16 v[68:71], v[168:171], v[210:213], v[68:71]
	v_mfma_f32_16x16x32_bf16 v[64:67], v[176:179], v[210:213], v[64:67]
	v_mfma_f32_16x16x32_bf16 v[116:119], v[172:175], v[188:191], v[116:119]
	v_mfma_f32_16x16x32_bf16 v[112:115], v[180:183], v[188:191], v[112:115]
	v_mfma_f32_16x16x32_bf16 v[100:103], v[172:175], v[196:199], v[100:103]
	v_mfma_f32_16x16x32_bf16 v[96:99], v[180:183], v[196:199], v[96:99]
	v_mfma_f32_16x16x32_bf16 v[84:87], v[172:175], v[206:209], v[84:87]
	v_mfma_f32_16x16x32_bf16 v[80:83], v[180:183], v[206:209], v[80:83]
	v_mfma_f32_16x16x32_bf16 v[68:71], v[172:175], v[214:217], v[68:71]
	v_mfma_f32_16x16x32_bf16 v[64:67], v[180:183], v[214:217], v[64:67]
	s_barrier
	s_add_i32 s64, s58, s13
	s_mov_b32 m0, s64
	ds_read_b128 v[184:187], v154 offset:16384
	ds_read_b128 v[188:191], v154 offset:17408
	ds_read_b128 v[192:195], v154 offset:18432
	ds_read_b128 v[196:199], v154 offset:19456
	ds_read_b128 v[200:203], v154 offset:20480
	ds_read_b128 v[206:209], v154 offset:21504
	ds_read_b128 v[210:213], v154 offset:22528
	ds_read_b128 v[214:217], v154 offset:23552
	global_load_lds_dwordx4 v132, s[46:47]
	s_add_i32 m0, s64, 0x2000
	s_add_u32 s98, s46, 0x80
	s_addc_u32 s99, s47, 0
	s_add_u32 s64, s46, 0x40000
	s_addc_u32 s65, s47, 0
	s_add_i32 s66, s59, s13
	global_load_lds_dwordx4 v136, s[46:47]
	s_mov_b32 m0, s66
	s_nop 0
	global_load_lds_dwordx4 v132, s[64:65]
	s_add_i32 m0, s66, 0x2000
	s_nop 0
	global_load_lds_dwordx4 v136, s[64:65]
	s_mov_b32 m0, s43
	s_nop 0
	global_load_lds_dwordx4 v130, s[48:49]
	s_mov_b32 m0, s50
	s_nop 0
	global_load_lds_dwordx4 v134, s[48:49]
	s_waitcnt vmcnt(8)
	s_waitcnt lgkmcnt(0)
	s_barrier
	v_mfma_f32_16x16x32_bf16 v[60:63], v[146:149], v[184:187], v[60:63]
	v_mfma_f32_16x16x32_bf16 v[56:59], v[160:163], v[184:187], v[56:59]
	v_mfma_f32_16x16x32_bf16 v[44:47], v[146:149], v[192:195], v[44:47]
	v_mfma_f32_16x16x32_bf16 v[40:43], v[160:163], v[192:195], v[40:43]
	v_mfma_f32_16x16x32_bf16 v[28:31], v[146:149], v[200:203], v[28:31]
	v_mfma_f32_16x16x32_bf16 v[24:27], v[160:163], v[200:203], v[24:27]
	v_mfma_f32_16x16x32_bf16 v[12:15], v[146:149], v[210:213], v[12:15]
	v_mfma_f32_16x16x32_bf16 v[8:11], v[160:163], v[210:213], v[8:11]
	v_mfma_f32_16x16x32_bf16 v[60:63], v[156:159], v[188:191], v[60:63]
	v_mfma_f32_16x16x32_bf16 v[56:59], v[164:167], v[188:191], v[56:59]
	v_mfma_f32_16x16x32_bf16 v[44:47], v[156:159], v[196:199], v[44:47]
	v_mfma_f32_16x16x32_bf16 v[40:43], v[164:167], v[196:199], v[40:43]
	v_mfma_f32_16x16x32_bf16 v[28:31], v[156:159], v[206:209], v[28:31]
	v_mfma_f32_16x16x32_bf16 v[24:27], v[164:167], v[206:209], v[24:27]
	v_mfma_f32_16x16x32_bf16 v[12:15], v[156:159], v[214:217], v[12:15]
	v_mfma_f32_16x16x32_bf16 v[8:11], v[164:167], v[214:217], v[8:11]
	v_mfma_f32_16x16x32_bf16 v[52:55], v[168:171], v[184:187], v[52:55]
	v_mfma_f32_16x16x32_bf16 v[48:51], v[176:179], v[184:187], v[48:51]
	v_mfma_f32_16x16x32_bf16 v[36:39], v[168:171], v[192:195], v[36:39]
	v_mfma_f32_16x16x32_bf16 v[32:35], v[176:179], v[192:195], v[32:35]
	v_mfma_f32_16x16x32_bf16 v[20:23], v[168:171], v[200:203], v[20:23]
	v_mfma_f32_16x16x32_bf16 v[16:19], v[176:179], v[200:203], v[16:19]
	v_mfma_f32_16x16x32_bf16 v[4:7], v[168:171], v[210:213], v[4:7]
	v_mfma_f32_16x16x32_bf16 v[0:3], v[176:179], v[210:213], v[0:3]
	v_mfma_f32_16x16x32_bf16 v[52:55], v[172:175], v[188:191], v[52:55]
	v_mfma_f32_16x16x32_bf16 v[48:51], v[180:183], v[188:191], v[48:51]
	v_mfma_f32_16x16x32_bf16 v[36:39], v[172:175], v[196:199], v[36:39]
	v_mfma_f32_16x16x32_bf16 v[32:35], v[180:183], v[196:199], v[32:35]
	v_mfma_f32_16x16x32_bf16 v[20:23], v[172:175], v[206:209], v[20:23]
	v_mfma_f32_16x16x32_bf16 v[16:19], v[180:183], v[206:209], v[16:19]
	v_mfma_f32_16x16x32_bf16 v[4:7], v[172:175], v[214:217], v[4:7]
	v_mfma_f32_16x16x32_bf16 v[0:3], v[180:183], v[214:217], v[0:3]
	s_barrier
; #define PG8_STAGE(bufoff, gbase, voff) do { _Pragma("unroll") for (int _i = 0; _i < 2; ++_i) \
;         __builtin_amdgcn_global_load_lds((const unsigned*)((const char*)(gbase) + (voff)[_i]), (PG8_LAS unsigned*)(lds + (bufoff) + ldsw + _i * 8192), 16, 0, 0); } while (0)
; #define PG8_LDA(dst, b, h) do { _Pragma("unroll") for (int m = 0; m < 4; ++m) _Pragma("unroll") for (int k = 0; k < 2; ++k) dst[m][k] = *(const PG8_LAS bf16x8*)(lds + PG8_SA(b, h) + aoff + m * 2048 + k * 1024); } while (0)
; #define PG8_LDB(dst, b, h) do { _Pragma("unroll") for (int n = 0; n < 2; ++n) _Pragma("unroll") for (int k = 0; k < 2; ++k) dst[n][k] = *(const PG8_LAS bf16x8*)(lds + PG8_SB(b, h) + boff + n * 2048 + k * 1024); } while (0)
; #define PG8_MMA(ai, bj, At, Bt) do { __builtin_amdgcn_s_setprio(1); _Pragma("unroll") for (int m = 0; m < 4; ++m) _Pragma("unroll") for (int n = 0; n < 2; ++n) _Pragma("unroll") for (int k = 0; k < 2; ++k) \
;         acc[ai][bj][m][n] = __builtin_amdgcn_mfma_f32_16x16x32_bf16(Bt[n][k], At[m][k], acc[ai][bj][m][n], 0, 0, 0); __builtin_amdgcn_s_setprio(0); } while (0)
; #define PG8_WAIT_V(n) asm volatile("s_waitcnt vmcnt(" #n ")" ::: "memory")
; #define PG8_WAIT_L(n) asm volatile("s_waitcnt lgkmcnt(" #n ")" ::: "memory")
; #define PG8_BAR __builtin_amdgcn_s_barrier()
; #define PG8_SCHED __builtin_amdgcn_sched_barrier(0)
; template <class Epi, class Sched, bool ALIGN_EPI = false, bool SP2 = false>
; __device__ __forceinline__ void gemm_phase(PG8_LAS unsigned char* lds, const Gemm g, const Sched& S, const Epi& E) {
;     ...
;             PG8_LDB(B0, 1, 0); PG8_LDB(B1, 1, 1); PG8_SCHED; PG8_LDA(At, 1, 0); PG8_STAGE(PG8_SA(0, 1), a2 + hstep, voffA);
;             PG8_WAIT_V(8); PG8_WAIT_L(0); PG8_BAR; PG8_MMA(0, 0, At, B0); PG8_MMA(0, 1, At, B1); PG8_BAR; PG8_SCHED;
;             PG8_LDA(At, 1, 1); PG8_STAGE(PG8_SB(1, 0), b3, voffB); PG8_STAGE(PG8_SB(1, 1), b3 + hstep, voffB); PG8_STAGE(PG8_SA(1, 0), a3, voffA);
;             PG8_WAIT_V(8); PG8_WAIT_L(0); PG8_BAR; PG8_MMA(1, 0, At, B0); PG8_MMA(1, 1, At, B1); PG8_BAR; PG8_SCHED;
;     ...
;         }
;         if constexpr (ALIGN_EPI) { if (wr == 0) PG8_BAR; }
	s_add_i32 s64, 0, 0x18000
	s_add_i32 s65, 0, 0x1c000
	ds_read_b128 v[146:149], v240
	ds_read_b128 v[156:159], v240 offset:1024
	ds_read_b128 v[160:163], v240 offset:2048
	ds_read_b128 v[164:167], v240 offset:3072
	ds_read_b128 v[168:171], v241
	ds_read_b128 v[172:175], v241 offset:1024
	ds_read_b128 v[176:179], v241 offset:2048
	ds_read_b128 v[180:183], v241 offset:3072
	s_add_u32 s100, s48, 0x80
	s_addc_u32 s101, s49, 0
	s_add_u32 s48, s48, 0x40000
	s_addc_u32 s49, s49, 0
	s_mov_b32 m0, s51
	ds_read_b128 v[184:187], v154 offset:32768
	ds_read_b128 v[188:191], v154 offset:33792
	ds_read_b128 v[192:195], v154 offset:34816
	ds_read_b128 v[196:199], v154 offset:35840
	ds_read_b128 v[200:203], v154 offset:36864
	ds_read_b128 v[206:209], v154 offset:37888
	ds_read_b128 v[210:213], v154 offset:38912
	ds_read_b128 v[214:217], v154 offset:39936
	global_load_lds_dwordx4 v130, s[48:49]
	s_mov_b32 m0, s52
	s_nop 0
	global_load_lds_dwordx4 v134, s[48:49]
	s_waitcnt vmcnt(8)
	s_waitcnt lgkmcnt(0)
	s_barrier
	v_mfma_f32_16x16x32_bf16 v[124:127], v[146:149], v[184:187], v[124:127]
	v_mfma_f32_16x16x32_bf16 v[120:123], v[160:163], v[184:187], v[120:123]
	v_mfma_f32_16x16x32_bf16 v[108:111], v[146:149], v[192:195], v[108:111]
	v_mfma_f32_16x16x32_bf16 v[104:107], v[160:163], v[192:195], v[104:107]
	v_mfma_f32_16x16x32_bf16 v[92:95], v[146:149], v[200:203], v[92:95]
	v_mfma_f32_16x16x32_bf16 v[88:91], v[160:163], v[200:203], v[88:91]
	v_mfma_f32_16x16x32_bf16 v[76:79], v[146:149], v[210:213], v[76:79]
	v_mfma_f32_16x16x32_bf16 v[72:75], v[160:163], v[210:213], v[72:75]
	v_mfma_f32_16x16x32_bf16 v[124:127], v[156:159], v[188:191], v[124:127]
	v_mfma_f32_16x16x32_bf16 v[120:123], v[164:167], v[188:191], v[120:123]
	v_mfma_f32_16x16x32_bf16 v[108:111], v[156:159], v[196:199], v[108:111]
	v_mfma_f32_16x16x32_bf16 v[104:107], v[164:167], v[196:199], v[104:107]
	v_mfma_f32_16x16x32_bf16 v[92:95], v[156:159], v[206:209], v[92:95]
	v_mfma_f32_16x16x32_bf16 v[88:91], v[164:167], v[206:209], v[88:91]
	v_mfma_f32_16x16x32_bf16 v[76:79], v[156:159], v[214:217], v[76:79]
	v_mfma_f32_16x16x32_bf16 v[72:75], v[164:167], v[214:217], v[72:75]
	v_mfma_f32_16x16x32_bf16 v[116:119], v[168:171], v[184:187], v[116:119]
	v_mfma_f32_16x16x32_bf16 v[112:115], v[176:179], v[184:187], v[112:115]
	v_mfma_f32_16x16x32_bf16 v[100:103], v[168:171], v[192:195], v[100:103]
	v_mfma_f32_16x16x32_bf16 v[96:99], v[176:179], v[192:195], v[96:99]
	v_mfma_f32_16x16x32_bf16 v[84:87], v[168:171], v[200:203], v[84:87]
	v_mfma_f32_16x16x32_bf16 v[80:83], v[176:179], v[200:203], v[80:83]
	v_mfma_f32_16x16x32_bf16 v[68:71], v[168:171], v[210:213], v[68:71]
	v_mfma_f32_16x16x32_bf16 v[64:67], v[176:179], v[210:213], v[64:67]
	v_mfma_f32_16x16x32_bf16 v[116:119], v[172:175], v[188:191], v[116:119]
	v_mfma_f32_16x16x32_bf16 v[112:115], v[180:183], v[188:191], v[112:115]
	v_mfma_f32_16x16x32_bf16 v[100:103], v[172:175], v[196:199], v[100:103]
	v_mfma_f32_16x16x32_bf16 v[96:99], v[180:183], v[196:199], v[96:99]
	v_mfma_f32_16x16x32_bf16 v[84:87], v[172:175], v[206:209], v[84:87]
	v_mfma_f32_16x16x32_bf16 v[80:83], v[180:183], v[206:209], v[80:83]
	v_mfma_f32_16x16x32_bf16 v[68:71], v[172:175], v[214:217], v[68:71]
	v_mfma_f32_16x16x32_bf16 v[64:67], v[180:183], v[214:217], v[64:67]
	s_barrier
	s_add_i32 s48, s64, s13
	s_mov_b32 m0, s48
	ds_read_b128 v[184:187], v154 offset:49152
	ds_read_b128 v[188:191], v154 offset:50176
	ds_read_b128 v[192:195], v154 offset:51200
	ds_read_b128 v[196:199], v154 offset:52224
	ds_read_b128 v[200:203], v154 offset:53248
	ds_read_b128 v[206:209], v154 offset:54272
	ds_read_b128 v[210:213], v154 offset:55296
	ds_read_b128 v[214:217], v154 offset:56320
	global_load_lds_dwordx4 v132, s[98:99]
	s_add_i32 m0, s48, 0x2000
	s_add_u32 s46, s46, 0x40080
	s_addc_u32 s47, s47, 0
	s_add_i32 s48, s65, s13
	global_load_lds_dwordx4 v136, s[98:99]
	s_mov_b32 m0, s48
	s_nop 0
	global_load_lds_dwordx4 v132, s[46:47]
	s_add_i32 m0, s48, 0x2000
	s_nop 0
	global_load_lds_dwordx4 v136, s[46:47]
	s_mov_b32 m0, s54
	s_nop 0
	global_load_lds_dwordx4 v130, s[100:101]
	s_mov_b32 m0, s55
	s_nop 0
	global_load_lds_dwordx4 v134, s[100:101]
	s_waitcnt vmcnt(8)
	s_waitcnt lgkmcnt(0)
	s_barrier
	v_mfma_f32_16x16x32_bf16 v[60:63], v[146:149], v[184:187], v[60:63]
	v_mfma_f32_16x16x32_bf16 v[56:59], v[160:163], v[184:187], v[56:59]
	v_mfma_f32_16x16x32_bf16 v[44:47], v[146:149], v[192:195], v[44:47]
	v_mfma_f32_16x16x32_bf16 v[40:43], v[160:163], v[192:195], v[40:43]
	v_mfma_f32_16x16x32_bf16 v[28:31], v[146:149], v[200:203], v[28:31]
	v_mfma_f32_16x16x32_bf16 v[24:27], v[160:163], v[200:203], v[24:27]
	v_mfma_f32_16x16x32_bf16 v[12:15], v[146:149], v[210:213], v[12:15]
	v_mfma_f32_16x16x32_bf16 v[8:11], v[160:163], v[210:213], v[8:11]
	v_mfma_f32_16x16x32_bf16 v[60:63], v[156:159], v[188:191], v[60:63]
	v_mfma_f32_16x16x32_bf16 v[56:59], v[164:167], v[188:191], v[56:59]
	v_mfma_f32_16x16x32_bf16 v[44:47], v[156:159], v[196:199], v[44:47]
	v_mfma_f32_16x16x32_bf16 v[40:43], v[164:167], v[196:199], v[40:43]
	v_mfma_f32_16x16x32_bf16 v[28:31], v[156:159], v[206:209], v[28:31]
	v_mfma_f32_16x16x32_bf16 v[24:27], v[164:167], v[206:209], v[24:27]
	v_mfma_f32_16x16x32_bf16 v[12:15], v[156:159], v[214:217], v[12:15]
	v_mfma_f32_16x16x32_bf16 v[8:11], v[164:167], v[214:217], v[8:11]
	v_mfma_f32_16x16x32_bf16 v[52:55], v[168:171], v[184:187], v[52:55]
	v_mfma_f32_16x16x32_bf16 v[48:51], v[176:179], v[184:187], v[48:51]
	v_mfma_f32_16x16x32_bf16 v[36:39], v[168:171], v[192:195], v[36:39]
	v_mfma_f32_16x16x32_bf16 v[32:35], v[176:179], v[192:195], v[32:35]
	v_mfma_f32_16x16x32_bf16 v[20:23], v[168:171], v[200:203], v[20:23]
	v_mfma_f32_16x16x32_bf16 v[16:19], v[176:179], v[200:203], v[16:19]
	v_mfma_f32_16x16x32_bf16 v[4:7], v[168:171], v[210:213], v[4:7]
	v_mfma_f32_16x16x32_bf16 v[0:3], v[176:179], v[210:213], v[0:3]
	v_mfma_f32_16x16x32_bf16 v[52:55], v[172:175], v[188:191], v[52:55]
	v_mfma_f32_16x16x32_bf16 v[48:51], v[180:183], v[188:191], v[48:51]
	v_mfma_f32_16x16x32_bf16 v[36:39], v[172:175], v[196:199], v[36:39]
	v_mfma_f32_16x16x32_bf16 v[32:35], v[180:183], v[196:199], v[32:35]
	v_mfma_f32_16x16x32_bf16 v[20:23], v[172:175], v[206:209], v[20:23]
	v_mfma_f32_16x16x32_bf16 v[16:19], v[180:183], v[206:209], v[16:19]
	v_mfma_f32_16x16x32_bf16 v[4:7], v[172:175], v[214:217], v[4:7]
	v_mfma_f32_16x16x32_bf16 v[0:3], v[180:183], v[214:217], v[0:3]
	s_barrier
	s_add_i32 s63, s63, 2
	s_add_u32 s44, s44, 0x100
	s_addc_u32 s45, s45, 0
	s_add_u32 s61, s61, 0x100
	s_addc_u32 s62, s62, 0
	s_cmp_gt_u32 s63, 13
	s_cbranch_scc0 .LBB0_520
	s_setprio 0
	s_and_b64 vcc, exec, s[28:29]
	s_cbranch_vccz .LBB0_523
	s_barrier

; #define PG8_STAGE(bufoff, gbase, voff) do { _Pragma("unroll") for (int _i = 0; _i < 2; ++_i) \
;         __builtin_amdgcn_global_load_lds((const unsigned*)((const char*)(gbase) + (voff)[_i]), (PG8_LAS unsigned*)(lds + (bufoff) + ldsw + _i * 8192), 16, 0, 0); } while (0)
; #define PG8_LDA(dst, b, h) do { _Pragma("unroll") for (int m = 0; m < 4; ++m) _Pragma("unroll") for (int k = 0; k < 2; ++k) dst[m][k] = *(const PG8_LAS bf16x8*)(lds + PG8_SA(b, h) + aoff + m * 2048 + k * 1024); } while (0)
; #define PG8_LDB(dst, b, h) do { _Pragma("unroll") for (int n = 0; n < 2; ++n) _Pragma("unroll") for (int k = 0; k < 2; ++k) dst[n][k] = *(const PG8_LAS bf16x8*)(lds + PG8_SB(b, h) + boff + n * 2048 + k * 1024); } while (0)
; #define PG8_WAIT_V(n) asm volatile("s_waitcnt vmcnt(" #n ")" ::: "memory")
; #define PG8_WAIT_L(n) asm volatile("s_waitcnt lgkmcnt(" #n ")" ::: "memory")
; #define PG8_BAR __builtin_amdgcn_s_barrier()
; #define PG8_SCHED __builtin_amdgcn_sched_barrier(0)
; template <class Epi, class Sched, bool ALIGN_EPI = false, bool SP2 = false>
; __device__ __forceinline__ void gemm_phase(PG8_LAS unsigned char* lds, const Gemm g, const Sched& S, const Epi& E) {
;     ...
;         const bool has_next = S.next(ui + 1, nxt);
;         const char* nA = has_next ? (const char*)g.A + (size_t)nxt.pm * tstep : cA; const char* nB = has_next ? (const char*)g.Bt + (size_t)nxt.pn * tstep : cB;
;         for (int t = 0; t < nt; t += 2) {
;             const bool last = (t == nt - 2);
;             const char* a1 = cA + (size_t)(t + 1) * kstep;
;             const char* a2 = last ? nA : cA + (size_t)(t + 2) * kstep; const char* b2 = last ? nB : cB + (size_t)(t + 2) * kstep;
;             const char* a3 = a2 + kstep; const char* b3 = b2 + kstep;
;             if (last && has_next) S.a_ready(nxt);
;             if constexpr (SP2) {
;             PG8_LDB(B0, 0, 0); PG8_LDB(B1, 0, 1); PG8_SCHED; PG8_LDA(At, 0, 0); PG8_STAGE(PG8_SA(1, 1), a1 + hstep, voffA);
;             PG8_WAIT_V(8); PG8_WAIT_L(0); PG8_BAR; PG8_MMA(0, 0, At, B0); PG8_MMA(0, 1, At, B1); PG8_BAR; PG8_SCHED;
;     ...
;         for (int a = 0; a < 2; ++a)
; #pragma unroll
;             for (int b = 0; b < 2; ++b)
; #pragma unroll
;                 for (int m = 0; m < 4; ++m)
; #pragma unroll
;                     for (int n = 0; n < 2; ++n) acc[a][b][m][n] = (f32x4){0.f, 0.f, 0.f, 0.f};
;         cur = nxt; cA = nA; cB = nB; ++ui;
.LBB0_626:
	s_ashr_i32 s37, s36, 31
	s_lshl_b64 s[38:39], s[36:37], 19
	s_add_u32 s38, s96, s38
	s_addc_u32 s39, s97, s39
	s_and_b64 s[40:41], s[4:5], exec
	s_cselect_b32 s37, s39, s43
	s_cselect_b32 s60, s38, s42
	s_ashr_i32 s35, s34, 31
	s_lshl_b64 s[40:41], s[34:35], 19
	v_readlane_b32 s14, v255, 30
	v_readlane_b32 s15, v255, 31
	s_add_u32 s40, s14, s40
	s_addc_u32 s41, s15, s41
	s_and_b64 s[46:47], s[4:5], exec
	s_cselect_b32 s35, s41, s45
	s_cselect_b32 s61, s40, s44
	s_add_u32 s42, s42, 0x40080
	s_addc_u32 s43, s43, 0
	s_add_u32 s62, s44, 0x100
	v_mov_b32_e32 v0, 0
	s_addc_u32 s63, s45, 0
	s_mov_b32 s64, -2
	v_mov_b32_e32 v1, v0
	v_mov_b32_e32 v2, v0
	v_mov_b32_e32 v3, v0
	v_mov_b32_e32 v4, v0
	v_mov_b32_e32 v5, v0
	v_mov_b32_e32 v6, v0
	v_mov_b32_e32 v7, v0
	v_mov_b32_e32 v16, v0
	v_mov_b32_e32 v17, v0
	v_mov_b32_e32 v18, v0
	v_mov_b32_e32 v19, v0
	v_mov_b32_e32 v20, v0
	v_mov_b32_e32 v21, v0
	v_mov_b32_e32 v22, v0
	v_mov_b32_e32 v23, v0
	v_mov_b32_e32 v32, v0
	v_mov_b32_e32 v33, v0
	v_mov_b32_e32 v34, v0
	v_mov_b32_e32 v35, v0
	v_mov_b32_e32 v36, v0
	v_mov_b32_e32 v37, v0
	v_mov_b32_e32 v38, v0
	v_mov_b32_e32 v39, v0
	v_mov_b32_e32 v48, v0
	v_mov_b32_e32 v49, v0
	v_mov_b32_e32 v50, v0
	v_mov_b32_e32 v51, v0
	v_mov_b32_e32 v52, v0
	v_mov_b32_e32 v53, v0
	v_mov_b32_e32 v54, v0
	v_mov_b32_e32 v55, v0
	v_mov_b32_e32 v8, v0
	v_mov_b32_e32 v9, v0
	v_mov_b32_e32 v10, v0
	v_mov_b32_e32 v11, v0
	v_mov_b32_e32 v12, v0
	v_mov_b32_e32 v13, v0
	v_mov_b32_e32 v14, v0
	v_mov_b32_e32 v15, v0
	v_mov_b32_e32 v24, v0
	v_mov_b32_e32 v25, v0
	v_mov_b32_e32 v26, v0
	v_mov_b32_e32 v27, v0
	v_mov_b32_e32 v28, v0
	v_mov_b32_e32 v29, v0
	v_mov_b32_e32 v30, v0
	v_mov_b32_e32 v31, v0
	v_mov_b32_e32 v40, v0
	v_mov_b32_e32 v41, v0
	v_mov_b32_e32 v42, v0
	v_mov_b32_e32 v43, v0
	v_mov_b32_e32 v44, v0
	v_mov_b32_e32 v45, v0
	v_mov_b32_e32 v46, v0
	v_mov_b32_e32 v47, v0
	v_mov_b32_e32 v56, v0
	v_mov_b32_e32 v57, v0
	v_mov_b32_e32 v58, v0
	v_mov_b32_e32 v59, v0
	v_mov_b32_e32 v60, v0
	v_mov_b32_e32 v61, v0
	v_mov_b32_e32 v62, v0
	v_mov_b32_e32 v63, v0
	v_mov_b32_e32 v64, v0
	v_mov_b32_e32 v65, v0
	v_mov_b32_e32 v66, v0
	v_mov_b32_e32 v67, v0
	v_mov_b32_e32 v68, v0
	v_mov_b32_e32 v69, v0
	v_mov_b32_e32 v70, v0
	v_mov_b32_e32 v71, v0
	v_mov_b32_e32 v80, v0
	v_mov_b32_e32 v81, v0
	v_mov_b32_e32 v82, v0
	v_mov_b32_e32 v83, v0
	v_mov_b32_e32 v84, v0
	v_mov_b32_e32 v85, v0
	v_mov_b32_e32 v86, v0
	v_mov_b32_e32 v87, v0
	v_mov_b32_e32 v96, v0
	v_mov_b32_e32 v97, v0
	v_mov_b32_e32 v98, v0
	v_mov_b32_e32 v99, v0
	v_mov_b32_e32 v100, v0
	v_mov_b32_e32 v101, v0
	v_mov_b32_e32 v102, v0
	v_mov_b32_e32 v103, v0
	v_mov_b32_e32 v112, v0
	v_mov_b32_e32 v113, v0
	v_mov_b32_e32 v114, v0
	v_mov_b32_e32 v115, v0
	v_mov_b32_e32 v116, v0
	v_mov_b32_e32 v117, v0
	v_mov_b32_e32 v118, v0
	v_mov_b32_e32 v119, v0
	v_mov_b32_e32 v72, v0
	v_mov_b32_e32 v73, v0
	v_mov_b32_e32 v74, v0
	v_mov_b32_e32 v75, v0
	v_mov_b32_e32 v76, v0
	v_mov_b32_e32 v77, v0
	v_mov_b32_e32 v78, v0
	v_mov_b32_e32 v79, v0
	v_mov_b32_e32 v88, v0
	v_mov_b32_e32 v89, v0
	v_mov_b32_e32 v90, v0
	v_mov_b32_e32 v91, v0
	v_mov_b32_e32 v92, v0
	v_mov_b32_e32 v93, v0
	v_mov_b32_e32 v94, v0
	v_mov_b32_e32 v95, v0
	v_mov_b32_e32 v104, v0
	v_mov_b32_e32 v105, v0
	v_mov_b32_e32 v106, v0
	v_mov_b32_e32 v107, v0
	v_mov_b32_e32 v108, v0
	v_mov_b32_e32 v109, v0
	v_mov_b32_e32 v110, v0
	v_mov_b32_e32 v111, v0
	v_mov_b32_e32 v120, v0
	v_mov_b32_e32 v121, v0
	v_mov_b32_e32 v122, v0
	v_mov_b32_e32 v123, v0
	v_mov_b32_e32 v124, v0
	v_mov_b32_e32 v125, v0
	v_mov_b32_e32 v126, v0
	v_mov_b32_e32 v127, v0
	v_add_u32_e32 v240, 0x18000, v148
	v_add_u32_e32 v241, 0x1c000, v148
	s_and_b64 vcc, exec, s[30:31]
	s_cbranch_vccz .Lsp2
	s_setprio 1
.Lsp2:
.LBB0_627:
	ds_read_b128 v[154:157], v149
	ds_read_b128 v[158:161], v149 offset:1024
	ds_read_b128 v[162:165], v149 offset:2048
	ds_read_b128 v[166:169], v149 offset:3072
	ds_read_b128 v[170:173], v150
	ds_read_b128 v[174:177], v150 offset:1024
	ds_read_b128 v[178:181], v150 offset:2048
	ds_read_b128 v[182:185], v150 offset:3072
	s_add_u32 s44, s42, 0xfffc0080
	s_addc_u32 s45, s43, -1
	s_cmp_eq_u32 s64, 12
	s_cselect_b32 s47, s37, s45
	s_cselect_b32 s46, s60, s44
	s_cselect_b32 s45, s35, s63
	s_cselect_b32 s44, s61, s62
	s_add_i32 m0, s48, 0xc000
	ds_read_b128 v[186:189], v151
	ds_read_b128 v[190:193], v151 offset:1024
	ds_read_b128 v[194:197], v151 offset:2048
	ds_read_b128 v[198:201], v151 offset:3072
	ds_read_b128 v[206:209], v151 offset:4096
	ds_read_b128 v[210:213], v151 offset:5120
	ds_read_b128 v[214:217], v151 offset:6144
	ds_read_b128 v[218:221], v151 offset:7168
	global_load_lds_dwordx4 v138, s[42:43]
	s_add_i32 m0, s48, 0xe000
	s_nop 0
	global_load_lds_dwordx4 v140, s[42:43]
	s_waitcnt vmcnt(8)
	s_waitcnt lgkmcnt(0)
	s_barrier
; #define PG8_STAGE(bufoff, gbase, voff) do { _Pragma("unroll") for (int _i = 0; _i < 2; ++_i) \
;         __builtin_amdgcn_global_load_lds((const unsigned*)((const char*)(gbase) + (voff)[_i]), (PG8_LAS unsigned*)(lds + (bufoff) + ldsw + _i * 8192), 16, 0, 0); } while (0)
; #define PG8_LDA(dst, b, h) do { _Pragma("unroll") for (int m = 0; m < 4; ++m) _Pragma("unroll") for (int k = 0; k < 2; ++k) dst[m][k] = *(const PG8_LAS bf16x8*)(lds + PG8_SA(b, h) + aoff + m * 2048 + k * 1024); } while (0)
; #define PG8_MMA(ai, bj, At, Bt) do { __builtin_amdgcn_s_setprio(1); _Pragma("unroll") for (int m = 0; m < 4; ++m) _Pragma("unroll") for (int n = 0; n < 2; ++n) _Pragma("unroll") for (int k = 0; k < 2; ++k) \
;         acc[ai][bj][m][n] = __builtin_amdgcn_mfma_f32_16x16x32_bf16(Bt[n][k], At[m][k], acc[ai][bj][m][n], 0, 0, 0); __builtin_amdgcn_s_setprio(0); } while (0)
; #define PG8_WAIT_V(n) asm volatile("s_waitcnt vmcnt(" #n ")" ::: "memory")
; #define PG8_WAIT_L(n) asm volatile("s_waitcnt lgkmcnt(" #n ")" ::: "memory")
; #define PG8_BAR __builtin_amdgcn_s_barrier()
; #define PG8_SCHED __builtin_amdgcn_sched_barrier(0)
; template <class Epi, class Sched, bool ALIGN_EPI = false, bool SP2 = false>
; __device__ __forceinline__ void gemm_phase(PG8_LAS unsigned char* lds, const Gemm g, const Sched& S, const Epi& E) {
;     ...
;             PG8_WAIT_V(8); PG8_WAIT_L(0); PG8_BAR; PG8_MMA(0, 0, At, B0); PG8_MMA(0, 1, At, B1); PG8_BAR; PG8_SCHED;
;             PG8_LDA(At, 0, 1); PG8_STAGE(PG8_SB(0, 0), b2, voffB); PG8_STAGE(PG8_SB(0, 1), b2 + hstep, voffB); PG8_STAGE(PG8_SA(0, 0), a2, voffA);
;             PG8_WAIT_V(8); PG8_WAIT_L(0); PG8_BAR; PG8_MMA(1, 0, At, B0); PG8_MMA(1, 1, At, B1); PG8_BAR; PG8_SCHED;
	v_mfma_f32_16x16x32_bf16 v[124:127], v[154:157], v[186:189], v[124:127]
	v_mfma_f32_16x16x32_bf16 v[120:123], v[162:165], v[186:189], v[120:123]
	v_mfma_f32_16x16x32_bf16 v[108:111], v[154:157], v[194:197], v[108:111]
	v_mfma_f32_16x16x32_bf16 v[104:107], v[162:165], v[194:197], v[104:107]
	v_mfma_f32_16x16x32_bf16 v[92:95], v[154:157], v[206:209], v[92:95]
	v_mfma_f32_16x16x32_bf16 v[88:91], v[162:165], v[206:209], v[88:91]
	v_mfma_f32_16x16x32_bf16 v[76:79], v[154:157], v[214:217], v[76:79]
	v_mfma_f32_16x16x32_bf16 v[72:75], v[162:165], v[214:217], v[72:75]
	v_mfma_f32_16x16x32_bf16 v[124:127], v[158:161], v[190:193], v[124:127]
	v_mfma_f32_16x16x32_bf16 v[120:123], v[166:169], v[190:193], v[120:123]
	v_mfma_f32_16x16x32_bf16 v[108:111], v[158:161], v[198:201], v[108:111]
	v_mfma_f32_16x16x32_bf16 v[104:107], v[166:169], v[198:201], v[104:107]
	v_mfma_f32_16x16x32_bf16 v[92:95], v[158:161], v[210:213], v[92:95]
	v_mfma_f32_16x16x32_bf16 v[88:91], v[166:169], v[210:213], v[88:91]
	v_mfma_f32_16x16x32_bf16 v[76:79], v[158:161], v[218:221], v[76:79]
	v_mfma_f32_16x16x32_bf16 v[72:75], v[166:169], v[218:221], v[72:75]
	v_mfma_f32_16x16x32_bf16 v[116:119], v[170:173], v[186:189], v[116:119]
	v_mfma_f32_16x16x32_bf16 v[112:115], v[178:181], v[186:189], v[112:115]
	v_mfma_f32_16x16x32_bf16 v[100:103], v[170:173], v[194:197], v[100:103]
	v_mfma_f32_16x16x32_bf16 v[96:99], v[178:181], v[194:197], v[96:99]
	v_mfma_f32_16x16x32_bf16 v[84:87], v[170:173], v[206:209], v[84:87]
	v_mfma_f32_16x16x32_bf16 v[80:83], v[178:181], v[206:209], v[80:83]
	v_mfma_f32_16x16x32_bf16 v[68:71], v[170:173], v[214:217], v[68:71]
	v_mfma_f32_16x16x32_bf16 v[64:67], v[178:181], v[214:217], v[64:67]
	v_mfma_f32_16x16x32_bf16 v[116:119], v[174:177], v[190:193], v[116:119]
	v_mfma_f32_16x16x32_bf16 v[112:115], v[182:185], v[190:193], v[112:115]
	v_mfma_f32_16x16x32_bf16 v[100:103], v[174:177], v[198:201], v[100:103]
	v_mfma_f32_16x16x32_bf16 v[96:99], v[182:185], v[198:201], v[96:99]
	v_mfma_f32_16x16x32_bf16 v[84:87], v[174:177], v[210:213], v[84:87]
	v_mfma_f32_16x16x32_bf16 v[80:83], v[182:185], v[210:213], v[80:83]
	v_mfma_f32_16x16x32_bf16 v[68:71], v[174:177], v[218:221], v[68:71]
	v_mfma_f32_16x16x32_bf16 v[64:67], v[182:185], v[218:221], v[64:67]
	s_barrier
	s_add_i32 s65, s57, s13
	s_mov_b32 m0, s65
	ds_read_b128 v[186:189], v151 offset:16384
	ds_read_b128 v[190:193], v151 offset:17408
	ds_read_b128 v[194:197], v151 offset:18432
	ds_read_b128 v[198:201], v151 offset:19456
	ds_read_b128 v[206:209], v151 offset:20480
	ds_read_b128 v[210:213], v151 offset:21504
	ds_read_b128 v[214:217], v151 offset:22528
	ds_read_b128 v[218:221], v151 offset:23552
	global_load_lds_dwordx4 v132, s[44:45]
	s_add_i32 m0, s65, 0x2000
	s_add_u32 s98, s44, 0x80
	s_addc_u32 s99, s45, 0
	s_add_u32 s66, s44, 0x40000
	s_addc_u32 s67, s45, 0
	s_add_i32 s65, s58, s13
	global_load_lds_dwordx4 v136, s[44:45]
	s_mov_b32 m0, s65
	s_nop 0
	global_load_lds_dwordx4 v132, s[66:67]
	s_add_i32 m0, s65, 0x2000
	s_nop 0
	global_load_lds_dwordx4 v136, s[66:67]
	s_mov_b32 m0, s48
	s_nop 0
	global_load_lds_dwordx4 v130, s[46:47]
	s_mov_b32 m0, s49
	s_nop 0
	global_load_lds_dwordx4 v134, s[46:47]
	s_waitcnt vmcnt(8)
	s_waitcnt lgkmcnt(0)
	s_barrier
	v_mfma_f32_16x16x32_bf16 v[60:63], v[154:157], v[186:189], v[60:63]
	v_mfma_f32_16x16x32_bf16 v[56:59], v[162:165], v[186:189], v[56:59]
	v_mfma_f32_16x16x32_bf16 v[44:47], v[154:157], v[194:197], v[44:47]
	v_mfma_f32_16x16x32_bf16 v[40:43], v[162:165], v[194:197], v[40:43]
	v_mfma_f32_16x16x32_bf16 v[28:31], v[154:157], v[206:209], v[28:31]
	v_mfma_f32_16x16x32_bf16 v[24:27], v[162:165], v[206:209], v[24:27]
	v_mfma_f32_16x16x32_bf16 v[12:15], v[154:157], v[214:217], v[12:15]
	v_mfma_f32_16x16x32_bf16 v[8:11], v[162:165], v[214:217], v[8:11]
	v_mfma_f32_16x16x32_bf16 v[60:63], v[158:161], v[190:193], v[60:63]
	v_mfma_f32_16x16x32_bf16 v[56:59], v[166:169], v[190:193], v[56:59]
	v_mfma_f32_16x16x32_bf16 v[44:47], v[158:161], v[198:201], v[44:47]
	v_mfma_f32_16x16x32_bf16 v[40:43], v[166:169], v[198:201], v[40:43]
	v_mfma_f32_16x16x32_bf16 v[28:31], v[158:161], v[210:213], v[28:31]
	v_mfma_f32_16x16x32_bf16 v[24:27], v[166:169], v[210:213], v[24:27]
	v_mfma_f32_16x16x32_bf16 v[12:15], v[158:161], v[218:221], v[12:15]
	v_mfma_f32_16x16x32_bf16 v[8:11], v[166:169], v[218:221], v[8:11]
	v_mfma_f32_16x16x32_bf16 v[52:55], v[170:173], v[186:189], v[52:55]
	v_mfma_f32_16x16x32_bf16 v[48:51], v[178:181], v[186:189], v[48:51]
	v_mfma_f32_16x16x32_bf16 v[36:39], v[170:173], v[194:197], v[36:39]
	v_mfma_f32_16x16x32_bf16 v[32:35], v[178:181], v[194:197], v[32:35]
	v_mfma_f32_16x16x32_bf16 v[20:23], v[170:173], v[206:209], v[20:23]
	v_mfma_f32_16x16x32_bf16 v[16:19], v[178:181], v[206:209], v[16:19]
	v_mfma_f32_16x16x32_bf16 v[4:7], v[170:173], v[214:217], v[4:7]
	v_mfma_f32_16x16x32_bf16 v[0:3], v[178:181], v[214:217], v[0:3]
	v_mfma_f32_16x16x32_bf16 v[52:55], v[174:177], v[190:193], v[52:55]
	v_mfma_f32_16x16x32_bf16 v[48:51], v[182:185], v[190:193], v[48:51]
	v_mfma_f32_16x16x32_bf16 v[36:39], v[174:177], v[198:201], v[36:39]
	v_mfma_f32_16x16x32_bf16 v[32:35], v[182:185], v[198:201], v[32:35]
	v_mfma_f32_16x16x32_bf16 v[20:23], v[174:177], v[210:213], v[20:23]
	v_mfma_f32_16x16x32_bf16 v[16:19], v[182:185], v[210:213], v[16:19]
	v_mfma_f32_16x16x32_bf16 v[4:7], v[174:177], v[218:221], v[4:7]
	v_mfma_f32_16x16x32_bf16 v[0:3], v[182:185], v[218:221], v[0:3]
	s_barrier
; #define PG8_STAGE(bufoff, gbase, voff) do { _Pragma("unroll") for (int _i = 0; _i < 2; ++_i) \
;         __builtin_amdgcn_global_load_lds((const unsigned*)((const char*)(gbase) + (voff)[_i]), (PG8_LAS unsigned*)(lds + (bufoff) + ldsw + _i * 8192), 16, 0, 0); } while (0)
; #define PG8_LDA(dst, b, h) do { _Pragma("unroll") for (int m = 0; m < 4; ++m) _Pragma("unroll") for (int k = 0; k < 2; ++k) dst[m][k] = *(const PG8_LAS bf16x8*)(lds + PG8_SA(b, h) + aoff + m * 2048 + k * 1024); } while (0)
; #define PG8_LDB(dst, b, h) do { _Pragma("unroll") for (int n = 0; n < 2; ++n) _Pragma("unroll") for (int k = 0; k < 2; ++k) dst[n][k] = *(const PG8_LAS bf16x8*)(lds + PG8_SB(b, h) + boff + n * 2048 + k * 1024); } while (0)
; #define PG8_MMA(ai, bj, At, Bt) do { __builtin_amdgcn_s_setprio(1); _Pragma("unroll") for (int m = 0; m < 4; ++m) _Pragma("unroll") for (int n = 0; n < 2; ++n) _Pragma("unroll") for (int k = 0; k < 2; ++k) \
;         acc[ai][bj][m][n] = __builtin_amdgcn_mfma_f32_16x16x32_bf16(Bt[n][k], At[m][k], acc[ai][bj][m][n], 0, 0, 0); __builtin_amdgcn_s_setprio(0); } while (0)
; #define PG8_WAIT_V(n) asm volatile("s_waitcnt vmcnt(" #n ")" ::: "memory")
; #define PG8_WAIT_L(n) asm volatile("s_waitcnt lgkmcnt(" #n ")" ::: "memory")
; #define PG8_BAR __builtin_amdgcn_s_barrier()
; #define PG8_SCHED __builtin_amdgcn_sched_barrier(0)
; template <class Epi, class Sched, bool ALIGN_EPI = false, bool SP2 = false>
; __device__ __forceinline__ void gemm_phase(PG8_LAS unsigned char* lds, const Gemm g, const Sched& S, const Epi& E) {
;     ...
;             PG8_LDB(B0, 1, 0); PG8_LDB(B1, 1, 1); PG8_SCHED; PG8_LDA(At, 1, 0); PG8_STAGE(PG8_SA(0, 1), a2 + hstep, voffA);
;             PG8_WAIT_V(8); PG8_WAIT_L(0); PG8_BAR; PG8_MMA(0, 0, At, B0); PG8_MMA(0, 1, At, B1); PG8_BAR; PG8_SCHED;
;             PG8_LDA(At, 1, 1); PG8_STAGE(PG8_SB(1, 0), b3, voffB); PG8_STAGE(PG8_SB(1, 1), b3 + hstep, voffB); PG8_STAGE(PG8_SA(1, 0), a3, voffA);
;             PG8_WAIT_V(8); PG8_WAIT_L(0); PG8_BAR; PG8_MMA(1, 0, At, B0); PG8_MMA(1, 1, At, B1); PG8_BAR; PG8_SCHED;
;     ...
;         if constexpr (ALIGN_EPI) { if (wr == 0) PG8_BAR; }
	s_add_i32 s65, 0, 0x18000
	s_add_i32 s66, 0, 0x1c000
	ds_read_b128 v[154:157], v240
	ds_read_b128 v[158:161], v240 offset:1024
	ds_read_b128 v[162:165], v240 offset:2048
	ds_read_b128 v[166:169], v240 offset:3072
	ds_read_b128 v[170:173], v241
	ds_read_b128 v[174:177], v241 offset:1024
	ds_read_b128 v[178:181], v241 offset:2048
	ds_read_b128 v[182:185], v241 offset:3072
	s_add_u32 s100, s46, 0x80
	s_addc_u32 s101, s47, 0
	s_add_u32 s46, s46, 0x40000
	s_addc_u32 s47, s47, 0
	s_mov_b32 m0, s50
	ds_read_b128 v[186:189], v151 offset:32768
	ds_read_b128 v[190:193], v151 offset:33792
	ds_read_b128 v[194:197], v151 offset:34816
	ds_read_b128 v[198:201], v151 offset:35840
	ds_read_b128 v[206:209], v151 offset:36864
	ds_read_b128 v[210:213], v151 offset:37888
	ds_read_b128 v[214:217], v151 offset:38912
	ds_read_b128 v[218:221], v151 offset:39936
	global_load_lds_dwordx4 v130, s[46:47]
	s_mov_b32 m0, s51
	s_nop 0
	global_load_lds_dwordx4 v134, s[46:47]
	s_waitcnt vmcnt(8)
	s_waitcnt lgkmcnt(0)
	s_barrier
	v_mfma_f32_16x16x32_bf16 v[124:127], v[154:157], v[186:189], v[124:127]
	v_mfma_f32_16x16x32_bf16 v[120:123], v[162:165], v[186:189], v[120:123]
	v_mfma_f32_16x16x32_bf16 v[108:111], v[154:157], v[194:197], v[108:111]
	v_mfma_f32_16x16x32_bf16 v[104:107], v[162:165], v[194:197], v[104:107]
	v_mfma_f32_16x16x32_bf16 v[92:95], v[154:157], v[206:209], v[92:95]
	v_mfma_f32_16x16x32_bf16 v[88:91], v[162:165], v[206:209], v[88:91]
	v_mfma_f32_16x16x32_bf16 v[76:79], v[154:157], v[214:217], v[76:79]
	v_mfma_f32_16x16x32_bf16 v[72:75], v[162:165], v[214:217], v[72:75]
	v_mfma_f32_16x16x32_bf16 v[124:127], v[158:161], v[190:193], v[124:127]
	v_mfma_f32_16x16x32_bf16 v[120:123], v[166:169], v[190:193], v[120:123]
	v_mfma_f32_16x16x32_bf16 v[108:111], v[158:161], v[198:201], v[108:111]
	v_mfma_f32_16x16x32_bf16 v[104:107], v[166:169], v[198:201], v[104:107]
	v_mfma_f32_16x16x32_bf16 v[92:95], v[158:161], v[210:213], v[92:95]
	v_mfma_f32_16x16x32_bf16 v[88:91], v[166:169], v[210:213], v[88:91]
	v_mfma_f32_16x16x32_bf16 v[76:79], v[158:161], v[218:221], v[76:79]
	v_mfma_f32_16x16x32_bf16 v[72:75], v[166:169], v[218:221], v[72:75]
	v_mfma_f32_16x16x32_bf16 v[116:119], v[170:173], v[186:189], v[116:119]
	v_mfma_f32_16x16x32_bf16 v[112:115], v[178:181], v[186:189], v[112:115]
	v_mfma_f32_16x16x32_bf16 v[100:103], v[170:173], v[194:197], v[100:103]
	v_mfma_f32_16x16x32_bf16 v[96:99], v[178:181], v[194:197], v[96:99]
	v_mfma_f32_16x16x32_bf16 v[84:87], v[170:173], v[206:209], v[84:87]
	v_mfma_f32_16x16x32_bf16 v[80:83], v[178:181], v[206:209], v[80:83]
	v_mfma_f32_16x16x32_bf16 v[68:71], v[170:173], v[214:217], v[68:71]
	v_mfma_f32_16x16x32_bf16 v[64:67], v[178:181], v[214:217], v[64:67]
	v_mfma_f32_16x16x32_bf16 v[116:119], v[174:177], v[190:193], v[116:119]
	v_mfma_f32_16x16x32_bf16 v[112:115], v[182:185], v[190:193], v[112:115]
	v_mfma_f32_16x16x32_bf16 v[100:103], v[174:177], v[198:201], v[100:103]
	v_mfma_f32_16x16x32_bf16 v[96:99], v[182:185], v[198:201], v[96:99]
	v_mfma_f32_16x16x32_bf16 v[84:87], v[174:177], v[210:213], v[84:87]
	v_mfma_f32_16x16x32_bf16 v[80:83], v[182:185], v[210:213], v[80:83]
	v_mfma_f32_16x16x32_bf16 v[68:71], v[174:177], v[218:221], v[68:71]
	v_mfma_f32_16x16x32_bf16 v[64:67], v[182:185], v[218:221], v[64:67]
	s_barrier
	s_add_i32 s46, s65, s13
	s_mov_b32 m0, s46
	ds_read_b128 v[186:189], v151 offset:49152
	ds_read_b128 v[190:193], v151 offset:50176
	ds_read_b128 v[194:197], v151 offset:51200
	ds_read_b128 v[198:201], v151 offset:52224
	ds_read_b128 v[206:209], v151 offset:53248
	ds_read_b128 v[210:213], v151 offset:54272
	ds_read_b128 v[214:217], v151 offset:55296
	ds_read_b128 v[218:221], v151 offset:56320
	global_load_lds_dwordx4 v132, s[98:99]
	s_add_i32 m0, s46, 0x2000
	s_add_u32 s44, s44, 0x40080
	s_addc_u32 s45, s45, 0
	s_add_i32 s46, s66, s13
	global_load_lds_dwordx4 v136, s[98:99]
	s_mov_b32 m0, s46
	s_nop 0
	global_load_lds_dwordx4 v132, s[44:45]
	s_add_i32 m0, s46, 0x2000
	s_nop 0
	global_load_lds_dwordx4 v136, s[44:45]
	s_mov_b32 m0, s54
	s_nop 0
	global_load_lds_dwordx4 v130, s[100:101]
	s_mov_b32 m0, s55
	s_nop 0
	global_load_lds_dwordx4 v134, s[100:101]
	s_waitcnt vmcnt(8)
	s_waitcnt lgkmcnt(0)
	s_barrier
	v_mfma_f32_16x16x32_bf16 v[60:63], v[154:157], v[186:189], v[60:63]
	v_mfma_f32_16x16x32_bf16 v[56:59], v[162:165], v[186:189], v[56:59]
	v_mfma_f32_16x16x32_bf16 v[44:47], v[154:157], v[194:197], v[44:47]
	v_mfma_f32_16x16x32_bf16 v[40:43], v[162:165], v[194:197], v[40:43]
	v_mfma_f32_16x16x32_bf16 v[28:31], v[154:157], v[206:209], v[28:31]
	v_mfma_f32_16x16x32_bf16 v[24:27], v[162:165], v[206:209], v[24:27]
	v_mfma_f32_16x16x32_bf16 v[12:15], v[154:157], v[214:217], v[12:15]
	v_mfma_f32_16x16x32_bf16 v[8:11], v[162:165], v[214:217], v[8:11]
	v_mfma_f32_16x16x32_bf16 v[60:63], v[158:161], v[190:193], v[60:63]
	v_mfma_f32_16x16x32_bf16 v[56:59], v[166:169], v[190:193], v[56:59]
	v_mfma_f32_16x16x32_bf16 v[44:47], v[158:161], v[198:201], v[44:47]
	v_mfma_f32_16x16x32_bf16 v[40:43], v[166:169], v[198:201], v[40:43]
	v_mfma_f32_16x16x32_bf16 v[28:31], v[158:161], v[210:213], v[28:31]
	v_mfma_f32_16x16x32_bf16 v[24:27], v[166:169], v[210:213], v[24:27]
	v_mfma_f32_16x16x32_bf16 v[12:15], v[158:161], v[218:221], v[12:15]
	v_mfma_f32_16x16x32_bf16 v[8:11], v[166:169], v[218:221], v[8:11]
	v_mfma_f32_16x16x32_bf16 v[52:55], v[170:173], v[186:189], v[52:55]
	v_mfma_f32_16x16x32_bf16 v[48:51], v[178:181], v[186:189], v[48:51]
	v_mfma_f32_16x16x32_bf16 v[36:39], v[170:173], v[194:197], v[36:39]
	v_mfma_f32_16x16x32_bf16 v[32:35], v[178:181], v[194:197], v[32:35]
	v_mfma_f32_16x16x32_bf16 v[20:23], v[170:173], v[206:209], v[20:23]
	v_mfma_f32_16x16x32_bf16 v[16:19], v[178:181], v[206:209], v[16:19]
	v_mfma_f32_16x16x32_bf16 v[4:7], v[170:173], v[214:217], v[4:7]
	v_mfma_f32_16x16x32_bf16 v[0:3], v[178:181], v[214:217], v[0:3]
	v_mfma_f32_16x16x32_bf16 v[52:55], v[174:177], v[190:193], v[52:55]
	v_mfma_f32_16x16x32_bf16 v[48:51], v[182:185], v[190:193], v[48:51]
	v_mfma_f32_16x16x32_bf16 v[36:39], v[174:177], v[198:201], v[36:39]
	v_mfma_f32_16x16x32_bf16 v[32:35], v[182:185], v[198:201], v[32:35]
	v_mfma_f32_16x16x32_bf16 v[20:23], v[174:177], v[210:213], v[20:23]
	v_mfma_f32_16x16x32_bf16 v[16:19], v[182:185], v[210:213], v[16:19]
	v_mfma_f32_16x16x32_bf16 v[4:7], v[174:177], v[218:221], v[4:7]
	v_mfma_f32_16x16x32_bf16 v[0:3], v[182:185], v[218:221], v[0:3]
	s_barrier
	s_add_i32 s64, s64, 2
	s_add_u32 s42, s42, 0x100
	s_addc_u32 s43, s43, 0
	s_add_u32 s62, s62, 0x100
	s_addc_u32 s63, s63, 0
	s_cmp_gt_u32 s64, 13
	s_cbranch_scc0 .LBB0_627
	s_setprio 0
	s_and_b64 vcc, exec, s[30:31]
	s_cbranch_vccz .LBB0_630
	s_barrier

; #define PG8_STAGE(bufoff, gbase, voff) do { _Pragma("unroll") for (int _i = 0; _i < 2; ++_i) \
;         __builtin_amdgcn_global_load_lds((const unsigned*)((const char*)(gbase) + (voff)[_i]), (PG8_LAS unsigned*)(lds + (bufoff) + ldsw + _i * 8192), 16, 0, 0); } while (0)
; #define PG8_LDA(dst, b, h) do { _Pragma("unroll") for (int m = 0; m < 4; ++m) _Pragma("unroll") for (int k = 0; k < 2; ++k) dst[m][k] = *(const PG8_LAS bf16x8*)(lds + PG8_SA(b, h) + aoff + m * 2048 + k * 1024); } while (0)
; #define PG8_LDB(dst, b, h) do { _Pragma("unroll") for (int n = 0; n < 2; ++n) _Pragma("unroll") for (int k = 0; k < 2; ++k) dst[n][k] = *(const PG8_LAS bf16x8*)(lds + PG8_SB(b, h) + boff + n * 2048 + k * 1024); } while (0)
; #define PG8_WAIT_V(n) asm volatile("s_waitcnt vmcnt(" #n ")" ::: "memory")
; #define PG8_WAIT_L(n) asm volatile("s_waitcnt lgkmcnt(" #n ")" ::: "memory")
; #define PG8_BAR __builtin_amdgcn_s_barrier()
; #define PG8_SCHED __builtin_amdgcn_sched_barrier(0)
; template <class Epi, class Sched, bool ALIGN_EPI = false, bool SP2 = false>
; __device__ __forceinline__ void gemm_phase(PG8_LAS unsigned char* lds, const Gemm g, const Sched& S, const Epi& E) {
;     ...
;         const bool has_next = S.next(ui + 1, nxt);
;         const char* nA = has_next ? (const char*)g.A + (size_t)nxt.pm * tstep : cA; const char* nB = has_next ? (const char*)g.Bt + (size_t)nxt.pn * tstep : cB;
;         for (int t = 0; t < nt; t += 2) {
;             const bool last = (t == nt - 2);
;             const char* a1 = cA + (size_t)(t + 1) * kstep;
;             const char* a2 = last ? nA : cA + (size_t)(t + 2) * kstep; const char* b2 = last ? nB : cB + (size_t)(t + 2) * kstep;
;             const char* a3 = a2 + kstep; const char* b3 = b2 + kstep;
;             if (last && has_next) S.a_ready(nxt);
;             if constexpr (SP2) {
;             PG8_LDB(B0, 0, 0); PG8_LDB(B1, 0, 1); PG8_SCHED; PG8_LDA(At, 0, 0); PG8_STAGE(PG8_SA(1, 1), a1 + hstep, voffA);
;             PG8_WAIT_V(8); PG8_WAIT_L(0); PG8_BAR; PG8_MMA(0, 0, At, B0); PG8_MMA(0, 1, At, B1); PG8_BAR; PG8_SCHED;
;     ...
; #pragma unroll
;         for (int a = 0; a < 2; ++a)
; #pragma unroll
;             for (int b = 0; b < 2; ++b)
; #pragma unroll
;                 for (int m = 0; m < 4; ++m)
; #pragma unroll
;                     for (int n = 0; n < 2; ++n) acc[a][b][m][n] = (f32x4){0.f, 0.f, 0.f, 0.f};
.LBB0_797:
	s_ashr_i32 s35, s34, 31
	s_lshl_b64 s[36:37], s[34:35], 19
	s_add_u32 s36, s70, s36
	s_addc_u32 s37, s71, s37
	s_and_b64 s[38:39], s[8:9], exec
	s_cselect_b32 s35, s37, s45
	s_cselect_b32 s41, s36, s44
	s_ashr_i32 s31, s30, 31
	s_lshl_b64 s[38:39], s[30:31], 19
	s_add_u32 s38, s68, s38
	s_addc_u32 s39, s69, s39
	s_and_b64 s[48:49], s[8:9], exec
	s_cselect_b32 s31, s39, s47
	s_cselect_b32 s60, s38, s46
	s_add_u32 s44, s44, 0x40080
	s_addc_u32 s45, s45, 0
	s_add_u32 s61, s46, 0x100
	v_mov_b32_e32 v0, 0
	s_addc_u32 s62, s47, 0
	s_mov_b32 s63, -2
	s_waitcnt lgkmcnt(0)
	v_mov_b32_e32 v1, v0
	v_mov_b32_e32 v2, v0
	v_mov_b32_e32 v3, v0
	v_mov_b32_e32 v4, v0
	v_mov_b32_e32 v5, v0
	v_mov_b32_e32 v6, v0
	v_mov_b32_e32 v7, v0
	v_mov_b32_e32 v16, v0
	v_mov_b32_e32 v17, v0
	v_mov_b32_e32 v18, v0
	v_mov_b32_e32 v19, v0
	v_mov_b32_e32 v20, v0
	v_mov_b32_e32 v21, v0
	v_mov_b32_e32 v22, v0
	v_mov_b32_e32 v23, v0
	v_mov_b32_e32 v32, v0
	v_mov_b32_e32 v33, v0
	v_mov_b32_e32 v34, v0
	v_mov_b32_e32 v35, v0
	v_mov_b32_e32 v36, v0
	v_mov_b32_e32 v37, v0
	v_mov_b32_e32 v38, v0
	v_mov_b32_e32 v39, v0
	v_mov_b32_e32 v48, v0
	v_mov_b32_e32 v49, v0
	v_mov_b32_e32 v50, v0
	v_mov_b32_e32 v51, v0
	v_mov_b32_e32 v52, v0
	v_mov_b32_e32 v53, v0
	v_mov_b32_e32 v54, v0
	v_mov_b32_e32 v55, v0
	v_mov_b32_e32 v8, v0
	v_mov_b32_e32 v9, v0
	v_mov_b32_e32 v10, v0
	v_mov_b32_e32 v11, v0
	v_mov_b32_e32 v12, v0
	v_mov_b32_e32 v13, v0
	v_mov_b32_e32 v14, v0
	v_mov_b32_e32 v15, v0
	v_mov_b32_e32 v24, v0
	v_mov_b32_e32 v25, v0
	v_mov_b32_e32 v26, v0
	v_mov_b32_e32 v27, v0
	v_mov_b32_e32 v28, v0
	v_mov_b32_e32 v29, v0
	v_mov_b32_e32 v30, v0
	v_mov_b32_e32 v31, v0
	v_mov_b32_e32 v40, v0
	v_mov_b32_e32 v41, v0
	v_mov_b32_e32 v42, v0
	v_mov_b32_e32 v43, v0
	v_mov_b32_e32 v44, v0
	v_mov_b32_e32 v45, v0
	v_mov_b32_e32 v46, v0
	v_mov_b32_e32 v47, v0
	v_mov_b32_e32 v56, v0
	v_mov_b32_e32 v57, v0
	v_mov_b32_e32 v58, v0
	v_mov_b32_e32 v59, v0
	v_mov_b32_e32 v60, v0
	v_mov_b32_e32 v61, v0
	v_mov_b32_e32 v62, v0
	v_mov_b32_e32 v63, v0
	v_mov_b32_e32 v64, v0
	v_mov_b32_e32 v65, v0
	v_mov_b32_e32 v66, v0
	v_mov_b32_e32 v67, v0
	v_mov_b32_e32 v68, v0
	v_mov_b32_e32 v69, v0
	v_mov_b32_e32 v70, v0
	v_mov_b32_e32 v71, v0
	v_mov_b32_e32 v80, v0
	v_mov_b32_e32 v81, v0
	v_mov_b32_e32 v82, v0
	v_mov_b32_e32 v83, v0
	v_mov_b32_e32 v84, v0
	v_mov_b32_e32 v85, v0
	v_mov_b32_e32 v86, v0
	v_mov_b32_e32 v87, v0
	v_mov_b32_e32 v96, v0
	v_mov_b32_e32 v97, v0
	v_mov_b32_e32 v98, v0
	v_mov_b32_e32 v99, v0
	v_mov_b32_e32 v100, v0
	v_mov_b32_e32 v101, v0
	v_mov_b32_e32 v102, v0
	v_mov_b32_e32 v103, v0
	v_mov_b32_e32 v112, v0
	v_mov_b32_e32 v113, v0
	v_mov_b32_e32 v114, v0
	v_mov_b32_e32 v115, v0
	v_mov_b32_e32 v116, v0
	v_mov_b32_e32 v117, v0
	v_mov_b32_e32 v118, v0
	v_mov_b32_e32 v119, v0
	v_mov_b32_e32 v72, v0
	v_mov_b32_e32 v73, v0
	v_mov_b32_e32 v74, v0
	v_mov_b32_e32 v75, v0
	v_mov_b32_e32 v76, v0
	v_mov_b32_e32 v77, v0
	v_mov_b32_e32 v78, v0
	v_mov_b32_e32 v79, v0
	v_mov_b32_e32 v88, v0
	v_mov_b32_e32 v89, v0
	v_mov_b32_e32 v90, v0
	v_mov_b32_e32 v91, v0
	v_mov_b32_e32 v92, v0
	v_mov_b32_e32 v93, v0
	v_mov_b32_e32 v94, v0
	v_mov_b32_e32 v95, v0
	v_mov_b32_e32 v104, v0
	v_mov_b32_e32 v105, v0
	v_mov_b32_e32 v106, v0
	v_mov_b32_e32 v107, v0
	v_mov_b32_e32 v108, v0
	v_mov_b32_e32 v109, v0
	v_mov_b32_e32 v110, v0
	v_mov_b32_e32 v111, v0
	v_mov_b32_e32 v120, v0
	v_mov_b32_e32 v121, v0
	v_mov_b32_e32 v122, v0
	v_mov_b32_e32 v123, v0
	v_mov_b32_e32 v124, v0
	v_mov_b32_e32 v125, v0
	v_mov_b32_e32 v126, v0
	v_mov_b32_e32 v127, v0
	v_add_u32_e32 v240, 0x18000, v150
	v_add_u32_e32 v241, 0x1c000, v150
	s_and_b64 vcc, exec, s[28:29]
	s_cbranch_vccz .Lsp3
	s_setprio 1
.Lsp3:
.LBB0_798:
	ds_read_b128 v[146:149], v152
	ds_read_b128 v[156:159], v152 offset:1024
	ds_read_b128 v[160:163], v152 offset:2048
	ds_read_b128 v[164:167], v152 offset:3072
	ds_read_b128 v[168:171], v153
	ds_read_b128 v[172:175], v153 offset:1024
	ds_read_b128 v[176:179], v153 offset:2048
	ds_read_b128 v[180:183], v153 offset:3072
	s_add_u32 s46, s44, 0xfffc0080
	s_addc_u32 s47, s45, -1
	s_cmp_eq_u32 s63, 12
	s_cselect_b32 s49, s35, s47
	s_cselect_b32 s48, s41, s46
	s_cselect_b32 s47, s31, s62
	s_cselect_b32 s46, s60, s61
	s_add_i32 m0, s43, 0xc000
	ds_read_b128 v[184:187], v154
	ds_read_b128 v[188:191], v154 offset:1024
	ds_read_b128 v[192:195], v154 offset:2048
	ds_read_b128 v[196:199], v154 offset:3072
	ds_read_b128 v[200:203], v154 offset:4096
	ds_read_b128 v[206:209], v154 offset:5120
	ds_read_b128 v[210:213], v154 offset:6144
	ds_read_b128 v[214:217], v154 offset:7168
	global_load_lds_dwordx4 v138, s[44:45]
	s_add_i32 m0, s43, 0xe000
	s_nop 0
	global_load_lds_dwordx4 v140, s[44:45]
	s_waitcnt vmcnt(8)
	s_waitcnt lgkmcnt(0)
	s_barrier
; #define PG8_STAGE(bufoff, gbase, voff) do { _Pragma("unroll") for (int _i = 0; _i < 2; ++_i) \
;         __builtin_amdgcn_global_load_lds((const unsigned*)((const char*)(gbase) + (voff)[_i]), (PG8_LAS unsigned*)(lds + (bufoff) + ldsw + _i * 8192), 16, 0, 0); } while (0)
; #define PG8_LDA(dst, b, h) do { _Pragma("unroll") for (int m = 0; m < 4; ++m) _Pragma("unroll") for (int k = 0; k < 2; ++k) dst[m][k] = *(const PG8_LAS bf16x8*)(lds + PG8_SA(b, h) + aoff + m * 2048 + k * 1024); } while (0)
; #define PG8_MMA(ai, bj, At, Bt) do { __builtin_amdgcn_s_setprio(1); _Pragma("unroll") for (int m = 0; m < 4; ++m) _Pragma("unroll") for (int n = 0; n < 2; ++n) _Pragma("unroll") for (int k = 0; k < 2; ++k) \
;         acc[ai][bj][m][n] = __builtin_amdgcn_mfma_f32_16x16x32_bf16(Bt[n][k], At[m][k], acc[ai][bj][m][n], 0, 0, 0); __builtin_amdgcn_s_setprio(0); } while (0)
; #define PG8_WAIT_V(n) asm volatile("s_waitcnt vmcnt(" #n ")" ::: "memory")
; #define PG8_WAIT_L(n) asm volatile("s_waitcnt lgkmcnt(" #n ")" ::: "memory")
; #define PG8_BAR __builtin_amdgcn_s_barrier()
; #define PG8_SCHED __builtin_amdgcn_sched_barrier(0)
; template <class Epi, class Sched, bool ALIGN_EPI = false, bool SP2 = false>
; __device__ __forceinline__ void gemm_phase(PG8_LAS unsigned char* lds, const Gemm g, const Sched& S, const Epi& E) {
;     ...
;             PG8_WAIT_V(8); PG8_WAIT_L(0); PG8_BAR; PG8_MMA(0, 0, At, B0); PG8_MMA(0, 1, At, B1); PG8_BAR; PG8_SCHED;
;             PG8_LDA(At, 0, 1); PG8_STAGE(PG8_SB(0, 0), b2, voffB); PG8_STAGE(PG8_SB(0, 1), b2 + hstep, voffB); PG8_STAGE(PG8_SA(0, 0), a2, voffA);
;             PG8_WAIT_V(8); PG8_WAIT_L(0); PG8_BAR; PG8_MMA(1, 0, At, B0); PG8_MMA(1, 1, At, B1); PG8_BAR; PG8_SCHED;
	v_mfma_f32_16x16x32_bf16 v[124:127], v[146:149], v[184:187], v[124:127]
	v_mfma_f32_16x16x32_bf16 v[120:123], v[160:163], v[184:187], v[120:123]
	v_mfma_f32_16x16x32_bf16 v[108:111], v[146:149], v[192:195], v[108:111]
	v_mfma_f32_16x16x32_bf16 v[104:107], v[160:163], v[192:195], v[104:107]
	v_mfma_f32_16x16x32_bf16 v[92:95], v[146:149], v[200:203], v[92:95]
	v_mfma_f32_16x16x32_bf16 v[88:91], v[160:163], v[200:203], v[88:91]
	v_mfma_f32_16x16x32_bf16 v[76:79], v[146:149], v[210:213], v[76:79]
	v_mfma_f32_16x16x32_bf16 v[72:75], v[160:163], v[210:213], v[72:75]
	v_mfma_f32_16x16x32_bf16 v[124:127], v[156:159], v[188:191], v[124:127]
	v_mfma_f32_16x16x32_bf16 v[120:123], v[164:167], v[188:191], v[120:123]
	v_mfma_f32_16x16x32_bf16 v[108:111], v[156:159], v[196:199], v[108:111]
	v_mfma_f32_16x16x32_bf16 v[104:107], v[164:167], v[196:199], v[104:107]
	v_mfma_f32_16x16x32_bf16 v[92:95], v[156:159], v[206:209], v[92:95]
	v_mfma_f32_16x16x32_bf16 v[88:91], v[164:167], v[206:209], v[88:91]
	v_mfma_f32_16x16x32_bf16 v[76:79], v[156:159], v[214:217], v[76:79]
	v_mfma_f32_16x16x32_bf16 v[72:75], v[164:167], v[214:217], v[72:75]
	v_mfma_f32_16x16x32_bf16 v[116:119], v[168:171], v[184:187], v[116:119]
	v_mfma_f32_16x16x32_bf16 v[112:115], v[176:179], v[184:187], v[112:115]
	v_mfma_f32_16x16x32_bf16 v[100:103], v[168:171], v[192:195], v[100:103]
	v_mfma_f32_16x16x32_bf16 v[96:99], v[176:179], v[192:195], v[96:99]
	v_mfma_f32_16x16x32_bf16 v[84:87], v[168:171], v[200:203], v[84:87]
	v_mfma_f32_16x16x32_bf16 v[80:83], v[176:179], v[200:203], v[80:83]
	v_mfma_f32_16x16x32_bf16 v[68:71], v[168:171], v[210:213], v[68:71]
	v_mfma_f32_16x16x32_bf16 v[64:67], v[176:179], v[210:213], v[64:67]
	v_mfma_f32_16x16x32_bf16 v[116:119], v[172:175], v[188:191], v[116:119]
	v_mfma_f32_16x16x32_bf16 v[112:115], v[180:183], v[188:191], v[112:115]
	v_mfma_f32_16x16x32_bf16 v[100:103], v[172:175], v[196:199], v[100:103]
	v_mfma_f32_16x16x32_bf16 v[96:99], v[180:183], v[196:199], v[96:99]
	v_mfma_f32_16x16x32_bf16 v[84:87], v[172:175], v[206:209], v[84:87]
	v_mfma_f32_16x16x32_bf16 v[80:83], v[180:183], v[206:209], v[80:83]
	v_mfma_f32_16x16x32_bf16 v[68:71], v[172:175], v[214:217], v[68:71]
	v_mfma_f32_16x16x32_bf16 v[64:67], v[180:183], v[214:217], v[64:67]
	s_barrier
	s_add_i32 s64, s58, s33
	s_mov_b32 m0, s64
	ds_read_b128 v[184:187], v154 offset:16384
	ds_read_b128 v[188:191], v154 offset:17408
	ds_read_b128 v[192:195], v154 offset:18432
	ds_read_b128 v[196:199], v154 offset:19456
	ds_read_b128 v[200:203], v154 offset:20480
	ds_read_b128 v[206:209], v154 offset:21504
	ds_read_b128 v[210:213], v154 offset:22528
	ds_read_b128 v[214:217], v154 offset:23552
	global_load_lds_dwordx4 v132, s[46:47]
	s_add_i32 m0, s64, 0x2000
	s_add_u32 s98, s46, 0x80
	s_addc_u32 s99, s47, 0
	s_add_u32 s64, s46, 0x40000
	s_addc_u32 s65, s47, 0
	s_add_i32 s66, s59, s33
	global_load_lds_dwordx4 v136, s[46:47]
	s_mov_b32 m0, s66
	s_nop 0
	global_load_lds_dwordx4 v132, s[64:65]
	s_add_i32 m0, s66, 0x2000
	s_nop 0
	global_load_lds_dwordx4 v136, s[64:65]
	s_mov_b32 m0, s43
	s_nop 0
	global_load_lds_dwordx4 v130, s[48:49]
	s_mov_b32 m0, s50
	s_nop 0
	global_load_lds_dwordx4 v134, s[48:49]
	s_waitcnt vmcnt(8)
	s_waitcnt lgkmcnt(0)
	s_barrier
	v_mfma_f32_16x16x32_bf16 v[60:63], v[146:149], v[184:187], v[60:63]
	v_mfma_f32_16x16x32_bf16 v[56:59], v[160:163], v[184:187], v[56:59]
	v_mfma_f32_16x16x32_bf16 v[44:47], v[146:149], v[192:195], v[44:47]
	v_mfma_f32_16x16x32_bf16 v[40:43], v[160:163], v[192:195], v[40:43]
	v_mfma_f32_16x16x32_bf16 v[28:31], v[146:149], v[200:203], v[28:31]
	v_mfma_f32_16x16x32_bf16 v[24:27], v[160:163], v[200:203], v[24:27]
	v_mfma_f32_16x16x32_bf16 v[12:15], v[146:149], v[210:213], v[12:15]
	v_mfma_f32_16x16x32_bf16 v[8:11], v[160:163], v[210:213], v[8:11]
	v_mfma_f32_16x16x32_bf16 v[60:63], v[156:159], v[188:191], v[60:63]
	v_mfma_f32_16x16x32_bf16 v[56:59], v[164:167], v[188:191], v[56:59]
	v_mfma_f32_16x16x32_bf16 v[44:47], v[156:159], v[196:199], v[44:47]
	v_mfma_f32_16x16x32_bf16 v[40:43], v[164:167], v[196:199], v[40:43]
	v_mfma_f32_16x16x32_bf16 v[28:31], v[156:159], v[206:209], v[28:31]
	v_mfma_f32_16x16x32_bf16 v[24:27], v[164:167], v[206:209], v[24:27]
	v_mfma_f32_16x16x32_bf16 v[12:15], v[156:159], v[214:217], v[12:15]
	v_mfma_f32_16x16x32_bf16 v[8:11], v[164:167], v[214:217], v[8:11]
	v_mfma_f32_16x16x32_bf16 v[52:55], v[168:171], v[184:187], v[52:55]
	v_mfma_f32_16x16x32_bf16 v[48:51], v[176:179], v[184:187], v[48:51]
	v_mfma_f32_16x16x32_bf16 v[36:39], v[168:171], v[192:195], v[36:39]
	v_mfma_f32_16x16x32_bf16 v[32:35], v[176:179], v[192:195], v[32:35]
	v_mfma_f32_16x16x32_bf16 v[20:23], v[168:171], v[200:203], v[20:23]
	v_mfma_f32_16x16x32_bf16 v[16:19], v[176:179], v[200:203], v[16:19]
	v_mfma_f32_16x16x32_bf16 v[4:7], v[168:171], v[210:213], v[4:7]
	v_mfma_f32_16x16x32_bf16 v[0:3], v[176:179], v[210:213], v[0:3]
	v_mfma_f32_16x16x32_bf16 v[52:55], v[172:175], v[188:191], v[52:55]
	v_mfma_f32_16x16x32_bf16 v[48:51], v[180:183], v[188:191], v[48:51]
	v_mfma_f32_16x16x32_bf16 v[36:39], v[172:175], v[196:199], v[36:39]
	v_mfma_f32_16x16x32_bf16 v[32:35], v[180:183], v[196:199], v[32:35]
	v_mfma_f32_16x16x32_bf16 v[20:23], v[172:175], v[206:209], v[20:23]
	v_mfma_f32_16x16x32_bf16 v[16:19], v[180:183], v[206:209], v[16:19]
	v_mfma_f32_16x16x32_bf16 v[4:7], v[172:175], v[214:217], v[4:7]
	v_mfma_f32_16x16x32_bf16 v[0:3], v[180:183], v[214:217], v[0:3]
	s_barrier
; #define PG8_STAGE(bufoff, gbase, voff) do { _Pragma("unroll") for (int _i = 0; _i < 2; ++_i) \
;         __builtin_amdgcn_global_load_lds((const unsigned*)((const char*)(gbase) + (voff)[_i]), (PG8_LAS unsigned*)(lds + (bufoff) + ldsw + _i * 8192), 16, 0, 0); } while (0)
; #define PG8_LDA(dst, b, h) do { _Pragma("unroll") for (int m = 0; m < 4; ++m) _Pragma("unroll") for (int k = 0; k < 2; ++k) dst[m][k] = *(const PG8_LAS bf16x8*)(lds + PG8_SA(b, h) + aoff + m * 2048 + k * 1024); } while (0)
; #define PG8_LDB(dst, b, h) do { _Pragma("unroll") for (int n = 0; n < 2; ++n) _Pragma("unroll") for (int k = 0; k < 2; ++k) dst[n][k] = *(const PG8_LAS bf16x8*)(lds + PG8_SB(b, h) + boff + n * 2048 + k * 1024); } while (0)
; #define PG8_MMA(ai, bj, At, Bt) do { __builtin_amdgcn_s_setprio(1); _Pragma("unroll") for (int m = 0; m < 4; ++m) _Pragma("unroll") for (int n = 0; n < 2; ++n) _Pragma("unroll") for (int k = 0; k < 2; ++k) \
;         acc[ai][bj][m][n] = __builtin_amdgcn_mfma_f32_16x16x32_bf16(Bt[n][k], At[m][k], acc[ai][bj][m][n], 0, 0, 0); __builtin_amdgcn_s_setprio(0); } while (0)
; #define PG8_WAIT_V(n) asm volatile("s_waitcnt vmcnt(" #n ")" ::: "memory")
; #define PG8_WAIT_L(n) asm volatile("s_waitcnt lgkmcnt(" #n ")" ::: "memory")
; #define PG8_BAR __builtin_amdgcn_s_barrier()
; #define PG8_SCHED __builtin_amdgcn_sched_barrier(0)
; template <class Epi, class Sched, bool ALIGN_EPI = false, bool SP2 = false>
; __device__ __forceinline__ void gemm_phase(PG8_LAS unsigned char* lds, const Gemm g, const Sched& S, const Epi& E) {
;     ...
;             PG8_LDB(B0, 1, 0); PG8_LDB(B1, 1, 1); PG8_SCHED; PG8_LDA(At, 1, 0); PG8_STAGE(PG8_SA(0, 1), a2 + hstep, voffA);
;             PG8_WAIT_V(8); PG8_WAIT_L(0); PG8_BAR; PG8_MMA(0, 0, At, B0); PG8_MMA(0, 1, At, B1); PG8_BAR; PG8_SCHED;
;             PG8_LDA(At, 1, 1); PG8_STAGE(PG8_SB(1, 0), b3, voffB); PG8_STAGE(PG8_SB(1, 1), b3 + hstep, voffB); PG8_STAGE(PG8_SA(1, 0), a3, voffA);
;             PG8_WAIT_V(8); PG8_WAIT_L(0); PG8_BAR; PG8_MMA(1, 0, At, B0); PG8_MMA(1, 1, At, B1); PG8_BAR; PG8_SCHED;
;     ...
;         if constexpr (ALIGN_EPI) { if (wr == 0) PG8_BAR; }
	s_add_i32 s64, 0, 0x18000
	s_add_i32 s65, 0, 0x1c000
	ds_read_b128 v[146:149], v240
	ds_read_b128 v[156:159], v240 offset:1024
	ds_read_b128 v[160:163], v240 offset:2048
	ds_read_b128 v[164:167], v240 offset:3072
	ds_read_b128 v[168:171], v241
	ds_read_b128 v[172:175], v241 offset:1024
	ds_read_b128 v[176:179], v241 offset:2048
	ds_read_b128 v[180:183], v241 offset:3072
	s_add_u32 s100, s48, 0x80
	s_addc_u32 s101, s49, 0
	s_add_u32 s48, s48, 0x40000
	s_addc_u32 s49, s49, 0
	s_mov_b32 m0, s51
	ds_read_b128 v[184:187], v154 offset:32768
	ds_read_b128 v[188:191], v154 offset:33792
	ds_read_b128 v[192:195], v154 offset:34816
	ds_read_b128 v[196:199], v154 offset:35840
	ds_read_b128 v[200:203], v154 offset:36864
	ds_read_b128 v[206:209], v154 offset:37888
	ds_read_b128 v[210:213], v154 offset:38912
	ds_read_b128 v[214:217], v154 offset:39936
	global_load_lds_dwordx4 v130, s[48:49]
	s_mov_b32 m0, s52
	s_nop 0
	global_load_lds_dwordx4 v134, s[48:49]
	s_waitcnt vmcnt(8)
	s_waitcnt lgkmcnt(0)
	s_barrier
	v_mfma_f32_16x16x32_bf16 v[124:127], v[146:149], v[184:187], v[124:127]
	v_mfma_f32_16x16x32_bf16 v[120:123], v[160:163], v[184:187], v[120:123]
	v_mfma_f32_16x16x32_bf16 v[108:111], v[146:149], v[192:195], v[108:111]
	v_mfma_f32_16x16x32_bf16 v[104:107], v[160:163], v[192:195], v[104:107]
	v_mfma_f32_16x16x32_bf16 v[92:95], v[146:149], v[200:203], v[92:95]
	v_mfma_f32_16x16x32_bf16 v[88:91], v[160:163], v[200:203], v[88:91]
	v_mfma_f32_16x16x32_bf16 v[76:79], v[146:149], v[210:213], v[76:79]
	v_mfma_f32_16x16x32_bf16 v[72:75], v[160:163], v[210:213], v[72:75]
	v_mfma_f32_16x16x32_bf16 v[124:127], v[156:159], v[188:191], v[124:127]
	v_mfma_f32_16x16x32_bf16 v[120:123], v[164:167], v[188:191], v[120:123]
	v_mfma_f32_16x16x32_bf16 v[108:111], v[156:159], v[196:199], v[108:111]
	v_mfma_f32_16x16x32_bf16 v[104:107], v[164:167], v[196:199], v[104:107]
	v_mfma_f32_16x16x32_bf16 v[92:95], v[156:159], v[206:209], v[92:95]
	v_mfma_f32_16x16x32_bf16 v[88:91], v[164:167], v[206:209], v[88:91]
	v_mfma_f32_16x16x32_bf16 v[76:79], v[156:159], v[214:217], v[76:79]
	v_mfma_f32_16x16x32_bf16 v[72:75], v[164:167], v[214:217], v[72:75]
	v_mfma_f32_16x16x32_bf16 v[116:119], v[168:171], v[184:187], v[116:119]
	v_mfma_f32_16x16x32_bf16 v[112:115], v[176:179], v[184:187], v[112:115]
	v_mfma_f32_16x16x32_bf16 v[100:103], v[168:171], v[192:195], v[100:103]
	v_mfma_f32_16x16x32_bf16 v[96:99], v[176:179], v[192:195], v[96:99]
	v_mfma_f32_16x16x32_bf16 v[84:87], v[168:171], v[200:203], v[84:87]
	v_mfma_f32_16x16x32_bf16 v[80:83], v[176:179], v[200:203], v[80:83]
	v_mfma_f32_16x16x32_bf16 v[68:71], v[168:171], v[210:213], v[68:71]
	v_mfma_f32_16x16x32_bf16 v[64:67], v[176:179], v[210:213], v[64:67]
	v_mfma_f32_16x16x32_bf16 v[116:119], v[172:175], v[188:191], v[116:119]
	v_mfma_f32_16x16x32_bf16 v[112:115], v[180:183], v[188:191], v[112:115]
	v_mfma_f32_16x16x32_bf16 v[100:103], v[172:175], v[196:199], v[100:103]
	v_mfma_f32_16x16x32_bf16 v[96:99], v[180:183], v[196:199], v[96:99]
	v_mfma_f32_16x16x32_bf16 v[84:87], v[172:175], v[206:209], v[84:87]
	v_mfma_f32_16x16x32_bf16 v[80:83], v[180:183], v[206:209], v[80:83]
	v_mfma_f32_16x16x32_bf16 v[68:71], v[172:175], v[214:217], v[68:71]
	v_mfma_f32_16x16x32_bf16 v[64:67], v[180:183], v[214:217], v[64:67]
	s_barrier
	s_add_i32 s48, s64, s33
	s_mov_b32 m0, s48
	ds_read_b128 v[184:187], v154 offset:49152
	ds_read_b128 v[188:191], v154 offset:50176
	ds_read_b128 v[192:195], v154 offset:51200
	ds_read_b128 v[196:199], v154 offset:52224
	ds_read_b128 v[200:203], v154 offset:53248
	ds_read_b128 v[206:209], v154 offset:54272
	ds_read_b128 v[210:213], v154 offset:55296
	ds_read_b128 v[214:217], v154 offset:56320
	global_load_lds_dwordx4 v132, s[98:99]
	s_add_i32 m0, s48, 0x2000
	s_add_u32 s46, s46, 0x40080
	s_addc_u32 s47, s47, 0
	s_add_i32 s48, s65, s33
	global_load_lds_dwordx4 v136, s[98:99]
	s_mov_b32 m0, s48
	s_nop 0
	global_load_lds_dwordx4 v132, s[46:47]
	s_add_i32 m0, s48, 0x2000
	s_nop 0
	global_load_lds_dwordx4 v136, s[46:47]
	s_mov_b32 m0, s54
	s_nop 0
	global_load_lds_dwordx4 v130, s[100:101]
	s_mov_b32 m0, s55
	s_nop 0
	global_load_lds_dwordx4 v134, s[100:101]
	s_waitcnt vmcnt(8)
	s_waitcnt lgkmcnt(0)
	s_barrier
	v_mfma_f32_16x16x32_bf16 v[60:63], v[146:149], v[184:187], v[60:63]
	v_mfma_f32_16x16x32_bf16 v[56:59], v[160:163], v[184:187], v[56:59]
	v_mfma_f32_16x16x32_bf16 v[44:47], v[146:149], v[192:195], v[44:47]
	v_mfma_f32_16x16x32_bf16 v[40:43], v[160:163], v[192:195], v[40:43]
	v_mfma_f32_16x16x32_bf16 v[28:31], v[146:149], v[200:203], v[28:31]
	v_mfma_f32_16x16x32_bf16 v[24:27], v[160:163], v[200:203], v[24:27]
	v_mfma_f32_16x16x32_bf16 v[12:15], v[146:149], v[210:213], v[12:15]
	v_mfma_f32_16x16x32_bf16 v[8:11], v[160:163], v[210:213], v[8:11]
	v_mfma_f32_16x16x32_bf16 v[60:63], v[156:159], v[188:191], v[60:63]
	v_mfma_f32_16x16x32_bf16 v[56:59], v[164:167], v[188:191], v[56:59]
	v_mfma_f32_16x16x32_bf16 v[44:47], v[156:159], v[196:199], v[44:47]
	v_mfma_f32_16x16x32_bf16 v[40:43], v[164:167], v[196:199], v[40:43]
	v_mfma_f32_16x16x32_bf16 v[28:31], v[156:159], v[206:209], v[28:31]
	v_mfma_f32_16x16x32_bf16 v[24:27], v[164:167], v[206:209], v[24:27]
	v_mfma_f32_16x16x32_bf16 v[12:15], v[156:159], v[214:217], v[12:15]
	v_mfma_f32_16x16x32_bf16 v[8:11], v[164:167], v[214:217], v[8:11]
	v_mfma_f32_16x16x32_bf16 v[52:55], v[168:171], v[184:187], v[52:55]
	v_mfma_f32_16x16x32_bf16 v[48:51], v[176:179], v[184:187], v[48:51]
	v_mfma_f32_16x16x32_bf16 v[36:39], v[168:171], v[192:195], v[36:39]
	v_mfma_f32_16x16x32_bf16 v[32:35], v[176:179], v[192:195], v[32:35]
	v_mfma_f32_16x16x32_bf16 v[20:23], v[168:171], v[200:203], v[20:23]
	v_mfma_f32_16x16x32_bf16 v[16:19], v[176:179], v[200:203], v[16:19]
	v_mfma_f32_16x16x32_bf16 v[4:7], v[168:171], v[210:213], v[4:7]
	v_mfma_f32_16x16x32_bf16 v[0:3], v[176:179], v[210:213], v[0:3]
	v_mfma_f32_16x16x32_bf16 v[52:55], v[172:175], v[188:191], v[52:55]
	v_mfma_f32_16x16x32_bf16 v[48:51], v[180:183], v[188:191], v[48:51]
	v_mfma_f32_16x16x32_bf16 v[36:39], v[172:175], v[196:199], v[36:39]
	v_mfma_f32_16x16x32_bf16 v[32:35], v[180:183], v[196:199], v[32:35]
	v_mfma_f32_16x16x32_bf16 v[20:23], v[172:175], v[206:209], v[20:23]
	v_mfma_f32_16x16x32_bf16 v[16:19], v[180:183], v[206:209], v[16:19]
	v_mfma_f32_16x16x32_bf16 v[4:7], v[172:175], v[214:217], v[4:7]
	v_mfma_f32_16x16x32_bf16 v[0:3], v[180:183], v[214:217], v[0:3]
	s_barrier
	s_add_i32 s63, s63, 2
	s_add_u32 s44, s44, 0x100
	s_addc_u32 s45, s45, 0
	s_add_u32 s61, s61, 0x100
	s_addc_u32 s62, s62, 0
	s_cmp_gt_u32 s63, 13
	s_cbranch_scc0 .LBB0_798
	s_setprio 0
	s_and_b64 vcc, exec, s[28:29]
	s_cbranch_vccz .LBB0_801
	s_barrier

; #define PG8_STAGE(bufoff, gbase, voff) do { _Pragma("unroll") for (int _i = 0; _i < 2; ++_i) \
;         __builtin_amdgcn_global_load_lds((const unsigned*)((const char*)(gbase) + (voff)[_i]), (PG8_LAS unsigned*)(lds + (bufoff) + ldsw + _i * 8192), 16, 0, 0); } while (0)
; #define PG8_LDA(dst, b, h) do { _Pragma("unroll") for (int m = 0; m < 4; ++m) _Pragma("unroll") for (int k = 0; k < 2; ++k) dst[m][k] = *(const PG8_LAS bf16x8*)(lds + PG8_SA(b, h) + aoff + m * 2048 + k * 1024); } while (0)
; #define PG8_LDB(dst, b, h) do { _Pragma("unroll") for (int n = 0; n < 2; ++n) _Pragma("unroll") for (int k = 0; k < 2; ++k) dst[n][k] = *(const PG8_LAS bf16x8*)(lds + PG8_SB(b, h) + boff + n * 2048 + k * 1024); } while (0)
; #define PG8_WAIT_V(n) asm volatile("s_waitcnt vmcnt(" #n ")" ::: "memory")
; #define PG8_WAIT_L(n) asm volatile("s_waitcnt lgkmcnt(" #n ")" ::: "memory")
; #define PG8_BAR __builtin_amdgcn_s_barrier()
; #define PG8_SCHED __builtin_amdgcn_sched_barrier(0)
; template <class Epi, class Sched, bool ALIGN_EPI = false, bool SP2 = false>
; __device__ __forceinline__ void gemm_phase(PG8_LAS unsigned char* lds, const Gemm g, const Sched& S, const Epi& E) {
;     ...
;         const bool has_next = S.next(ui + 1, nxt);
;         const char* nA = has_next ? (const char*)g.A + (size_t)nxt.pm * tstep : cA; const char* nB = has_next ? (const char*)g.Bt + (size_t)nxt.pn * tstep : cB;
;         for (int t = 0; t < nt; t += 2) {
;             const bool last = (t == nt - 2);
;             const char* a1 = cA + (size_t)(t + 1) * kstep;
;             const char* a2 = last ? nA : cA + (size_t)(t + 2) * kstep; const char* b2 = last ? nB : cB + (size_t)(t + 2) * kstep;
;             const char* a3 = a2 + kstep; const char* b3 = b2 + kstep;
;             if (last && has_next) S.a_ready(nxt);
;             if constexpr (SP2) {
;             PG8_LDB(B0, 0, 0); PG8_LDB(B1, 0, 1); PG8_SCHED; PG8_LDA(At, 0, 0); PG8_STAGE(PG8_SA(1, 1), a1 + hstep, voffA);
;             PG8_WAIT_V(8); PG8_WAIT_L(0); PG8_BAR; PG8_MMA(0, 0, At, B0); PG8_MMA(0, 1, At, B1); PG8_BAR; PG8_SCHED;
;     ...
; #pragma unroll
;         for (int a = 0; a < 2; ++a)
; #pragma unroll
;             for (int b = 0; b < 2; ++b)
; #pragma unroll
;                 for (int m = 0; m < 4; ++m)
; #pragma unroll
;                     for (int n = 0; n < 2; ++n) acc[a][b][m][n] = (f32x4){0.f, 0.f, 0.f, 0.f};
.LBB0_904:
	s_ashr_i32 s35, s34, 31
	s_lshl_b64 s[36:37], s[34:35], 19
	s_add_u32 s36, s96, s36
	s_addc_u32 s37, s97, s37
	s_and_b64 s[38:39], s[6:7], exec
	s_cselect_b32 s35, s37, s41
	s_cselect_b32 s58, s36, s40
	s_ashr_i32 s31, s30, 31
	s_lshl_b64 s[38:39], s[30:31], 19
	s_add_u32 s38, s68, s38
	s_addc_u32 s39, s69, s39
	s_and_b64 s[44:45], s[6:7], exec
	s_cselect_b32 s31, s39, s43
	s_cselect_b32 s59, s38, s42
	s_add_u32 s40, s40, 0x40080
	s_addc_u32 s41, s41, 0
	s_add_u32 s60, s42, 0x100
	v_mov_b32_e32 v0, 0
	s_addc_u32 s61, s43, 0
	s_mov_b32 s62, -2
	v_mov_b32_e32 v1, v0
	v_mov_b32_e32 v2, v0
	v_mov_b32_e32 v3, v0
	v_mov_b32_e32 v4, v0
	v_mov_b32_e32 v5, v0
	v_mov_b32_e32 v6, v0
	v_mov_b32_e32 v7, v0
	v_mov_b32_e32 v16, v0
	v_mov_b32_e32 v17, v0
	v_mov_b32_e32 v18, v0
	v_mov_b32_e32 v19, v0
	v_mov_b32_e32 v20, v0
	v_mov_b32_e32 v21, v0
	v_mov_b32_e32 v22, v0
	v_mov_b32_e32 v23, v0
	v_mov_b32_e32 v32, v0
	v_mov_b32_e32 v33, v0
	v_mov_b32_e32 v34, v0
	v_mov_b32_e32 v35, v0
	v_mov_b32_e32 v36, v0
	v_mov_b32_e32 v37, v0
	v_mov_b32_e32 v38, v0
	v_mov_b32_e32 v39, v0
	v_mov_b32_e32 v48, v0
	v_mov_b32_e32 v49, v0
	v_mov_b32_e32 v50, v0
	v_mov_b32_e32 v51, v0
	v_mov_b32_e32 v52, v0
	v_mov_b32_e32 v53, v0
	v_mov_b32_e32 v54, v0
	v_mov_b32_e32 v55, v0
	v_mov_b32_e32 v8, v0
	v_mov_b32_e32 v9, v0
	v_mov_b32_e32 v10, v0
	v_mov_b32_e32 v11, v0
	v_mov_b32_e32 v12, v0
	v_mov_b32_e32 v13, v0
	v_mov_b32_e32 v14, v0
	v_mov_b32_e32 v15, v0
	v_mov_b32_e32 v24, v0
	v_mov_b32_e32 v25, v0
	v_mov_b32_e32 v26, v0
	v_mov_b32_e32 v27, v0
	v_mov_b32_e32 v28, v0
	v_mov_b32_e32 v29, v0
	v_mov_b32_e32 v30, v0
	v_mov_b32_e32 v31, v0
	v_mov_b32_e32 v40, v0
	v_mov_b32_e32 v41, v0
	v_mov_b32_e32 v42, v0
	v_mov_b32_e32 v43, v0
	v_mov_b32_e32 v44, v0
	v_mov_b32_e32 v45, v0
	v_mov_b32_e32 v46, v0
	v_mov_b32_e32 v47, v0
	v_mov_b32_e32 v56, v0
	v_mov_b32_e32 v57, v0
	v_mov_b32_e32 v58, v0
	v_mov_b32_e32 v59, v0
	v_mov_b32_e32 v60, v0
	v_mov_b32_e32 v61, v0
	v_mov_b32_e32 v62, v0
	v_mov_b32_e32 v63, v0
	v_mov_b32_e32 v64, v0
	v_mov_b32_e32 v65, v0
	v_mov_b32_e32 v66, v0
	v_mov_b32_e32 v67, v0
	v_mov_b32_e32 v68, v0
	v_mov_b32_e32 v69, v0
	v_mov_b32_e32 v70, v0
	v_mov_b32_e32 v71, v0
	v_mov_b32_e32 v80, v0
	v_mov_b32_e32 v81, v0
	v_mov_b32_e32 v82, v0
	v_mov_b32_e32 v83, v0
	v_mov_b32_e32 v84, v0
	v_mov_b32_e32 v85, v0
	v_mov_b32_e32 v86, v0
	v_mov_b32_e32 v87, v0
	v_mov_b32_e32 v96, v0
	v_mov_b32_e32 v97, v0
	v_mov_b32_e32 v98, v0
	v_mov_b32_e32 v99, v0
	v_mov_b32_e32 v100, v0
	v_mov_b32_e32 v101, v0
	v_mov_b32_e32 v102, v0
	v_mov_b32_e32 v103, v0
	v_mov_b32_e32 v112, v0
	v_mov_b32_e32 v113, v0
	v_mov_b32_e32 v114, v0
	v_mov_b32_e32 v115, v0
	v_mov_b32_e32 v116, v0
	v_mov_b32_e32 v117, v0
	v_mov_b32_e32 v118, v0
	v_mov_b32_e32 v119, v0
	v_mov_b32_e32 v72, v0
	v_mov_b32_e32 v73, v0
	v_mov_b32_e32 v74, v0
	v_mov_b32_e32 v75, v0
	v_mov_b32_e32 v76, v0
	v_mov_b32_e32 v77, v0
	v_mov_b32_e32 v78, v0
	v_mov_b32_e32 v79, v0
	v_mov_b32_e32 v88, v0
	v_mov_b32_e32 v89, v0
	v_mov_b32_e32 v90, v0
	v_mov_b32_e32 v91, v0
	v_mov_b32_e32 v92, v0
	v_mov_b32_e32 v93, v0
	v_mov_b32_e32 v94, v0
	v_mov_b32_e32 v95, v0
	v_mov_b32_e32 v104, v0
	v_mov_b32_e32 v105, v0
	v_mov_b32_e32 v106, v0
	v_mov_b32_e32 v107, v0
	v_mov_b32_e32 v108, v0
	v_mov_b32_e32 v109, v0
	v_mov_b32_e32 v110, v0
	v_mov_b32_e32 v111, v0
	v_mov_b32_e32 v120, v0
	v_mov_b32_e32 v121, v0
	v_mov_b32_e32 v122, v0
	v_mov_b32_e32 v123, v0
	v_mov_b32_e32 v124, v0
	v_mov_b32_e32 v125, v0
	v_mov_b32_e32 v126, v0
	v_mov_b32_e32 v127, v0
	v_add_u32_e32 v240, 0x18000, v150
	v_add_u32_e32 v241, 0x1c000, v150
	s_and_b64 vcc, exec, s[28:29]
	s_cbranch_vccz .Lsp4
	s_setprio 1
.Lsp4:
.LBB0_905:
	ds_read_b128 v[146:149], v151
	ds_read_b128 v[156:159], v151 offset:1024
	ds_read_b128 v[160:163], v151 offset:2048
	ds_read_b128 v[164:167], v151 offset:3072
	ds_read_b128 v[168:171], v152
	ds_read_b128 v[172:175], v152 offset:1024
	ds_read_b128 v[176:179], v152 offset:2048
	ds_read_b128 v[180:183], v152 offset:3072
	s_add_u32 s42, s40, 0xfffc0080
	s_addc_u32 s43, s41, -1
	s_cmp_eq_u32 s62, 12
	s_cselect_b32 s45, s35, s43
	s_cselect_b32 s44, s58, s42
	s_cselect_b32 s43, s31, s61
	s_cselect_b32 s42, s59, s60
	s_add_i32 m0, s46, 0xc000
	ds_read_b128 v[184:187], v153
	ds_read_b128 v[188:191], v153 offset:1024
	ds_read_b128 v[192:195], v153 offset:2048
	ds_read_b128 v[196:199], v153 offset:3072
	ds_read_b128 v[200:203], v153 offset:4096
	ds_read_b128 v[206:209], v153 offset:5120
	ds_read_b128 v[210:213], v153 offset:6144
	ds_read_b128 v[214:217], v153 offset:7168
	global_load_lds_dwordx4 v138, s[40:41]
	s_add_i32 m0, s46, 0xe000
	s_nop 0
	global_load_lds_dwordx4 v140, s[40:41]
	s_waitcnt vmcnt(8)
	s_waitcnt lgkmcnt(0)
	s_barrier
; #define PG8_STAGE(bufoff, gbase, voff) do { _Pragma("unroll") for (int _i = 0; _i < 2; ++_i) \
;         __builtin_amdgcn_global_load_lds((const unsigned*)((const char*)(gbase) + (voff)[_i]), (PG8_LAS unsigned*)(lds + (bufoff) + ldsw + _i * 8192), 16, 0, 0); } while (0)
; #define PG8_LDA(dst, b, h) do { _Pragma("unroll") for (int m = 0; m < 4; ++m) _Pragma("unroll") for (int k = 0; k < 2; ++k) dst[m][k] = *(const PG8_LAS bf16x8*)(lds + PG8_SA(b, h) + aoff + m * 2048 + k * 1024); } while (0)
; #define PG8_MMA(ai, bj, At, Bt) do { __builtin_amdgcn_s_setprio(1); _Pragma("unroll") for (int m = 0; m < 4; ++m) _Pragma("unroll") for (int n = 0; n < 2; ++n) _Pragma("unroll") for (int k = 0; k < 2; ++k) \
;         acc[ai][bj][m][n] = __builtin_amdgcn_mfma_f32_16x16x32_bf16(Bt[n][k], At[m][k], acc[ai][bj][m][n], 0, 0, 0); __builtin_amdgcn_s_setprio(0); } while (0)
; #define PG8_WAIT_V(n) asm volatile("s_waitcnt vmcnt(" #n ")" ::: "memory")
; #define PG8_WAIT_L(n) asm volatile("s_waitcnt lgkmcnt(" #n ")" ::: "memory")
; #define PG8_BAR __builtin_amdgcn_s_barrier()
; #define PG8_SCHED __builtin_amdgcn_sched_barrier(0)
; template <class Epi, class Sched, bool ALIGN_EPI = false, bool SP2 = false>
; __device__ __forceinline__ void gemm_phase(PG8_LAS unsigned char* lds, const Gemm g, const Sched& S, const Epi& E) {
;     ...
;             PG8_WAIT_V(8); PG8_WAIT_L(0); PG8_BAR; PG8_MMA(0, 0, At, B0); PG8_MMA(0, 1, At, B1); PG8_BAR; PG8_SCHED;
;             PG8_LDA(At, 0, 1); PG8_STAGE(PG8_SB(0, 0), b2, voffB); PG8_STAGE(PG8_SB(0, 1), b2 + hstep, voffB); PG8_STAGE(PG8_SA(0, 0), a2, voffA);
;             PG8_WAIT_V(8); PG8_WAIT_L(0); PG8_BAR; PG8_MMA(1, 0, At, B0); PG8_MMA(1, 1, At, B1); PG8_BAR; PG8_SCHED;
	v_mfma_f32_16x16x32_bf16 v[124:127], v[146:149], v[184:187], v[124:127]
	v_mfma_f32_16x16x32_bf16 v[120:123], v[160:163], v[184:187], v[120:123]
	v_mfma_f32_16x16x32_bf16 v[108:111], v[146:149], v[192:195], v[108:111]
	v_mfma_f32_16x16x32_bf16 v[104:107], v[160:163], v[192:195], v[104:107]
	v_mfma_f32_16x16x32_bf16 v[92:95], v[146:149], v[200:203], v[92:95]
	v_mfma_f32_16x16x32_bf16 v[88:91], v[160:163], v[200:203], v[88:91]
	v_mfma_f32_16x16x32_bf16 v[76:79], v[146:149], v[210:213], v[76:79]
	v_mfma_f32_16x16x32_bf16 v[72:75], v[160:163], v[210:213], v[72:75]
	v_mfma_f32_16x16x32_bf16 v[124:127], v[156:159], v[188:191], v[124:127]
	v_mfma_f32_16x16x32_bf16 v[120:123], v[164:167], v[188:191], v[120:123]
	v_mfma_f32_16x16x32_bf16 v[108:111], v[156:159], v[196:199], v[108:111]
	v_mfma_f32_16x16x32_bf16 v[104:107], v[164:167], v[196:199], v[104:107]
	v_mfma_f32_16x16x32_bf16 v[92:95], v[156:159], v[206:209], v[92:95]
	v_mfma_f32_16x16x32_bf16 v[88:91], v[164:167], v[206:209], v[88:91]
	v_mfma_f32_16x16x32_bf16 v[76:79], v[156:159], v[214:217], v[76:79]
	v_mfma_f32_16x16x32_bf16 v[72:75], v[164:167], v[214:217], v[72:75]
	v_mfma_f32_16x16x32_bf16 v[116:119], v[168:171], v[184:187], v[116:119]
	v_mfma_f32_16x16x32_bf16 v[112:115], v[176:179], v[184:187], v[112:115]
	v_mfma_f32_16x16x32_bf16 v[100:103], v[168:171], v[192:195], v[100:103]
	v_mfma_f32_16x16x32_bf16 v[96:99], v[176:179], v[192:195], v[96:99]
	v_mfma_f32_16x16x32_bf16 v[84:87], v[168:171], v[200:203], v[84:87]
	v_mfma_f32_16x16x32_bf16 v[80:83], v[176:179], v[200:203], v[80:83]
	v_mfma_f32_16x16x32_bf16 v[68:71], v[168:171], v[210:213], v[68:71]
	v_mfma_f32_16x16x32_bf16 v[64:67], v[176:179], v[210:213], v[64:67]
	v_mfma_f32_16x16x32_bf16 v[116:119], v[172:175], v[188:191], v[116:119]
	v_mfma_f32_16x16x32_bf16 v[112:115], v[180:183], v[188:191], v[112:115]
	v_mfma_f32_16x16x32_bf16 v[100:103], v[172:175], v[196:199], v[100:103]
	v_mfma_f32_16x16x32_bf16 v[96:99], v[180:183], v[196:199], v[96:99]
	v_mfma_f32_16x16x32_bf16 v[84:87], v[172:175], v[206:209], v[84:87]
	v_mfma_f32_16x16x32_bf16 v[80:83], v[180:183], v[206:209], v[80:83]
	v_mfma_f32_16x16x32_bf16 v[68:71], v[172:175], v[214:217], v[68:71]
	v_mfma_f32_16x16x32_bf16 v[64:67], v[180:183], v[214:217], v[64:67]
	s_barrier
	s_add_i32 s63, s55, s33
	s_mov_b32 m0, s63
	ds_read_b128 v[184:187], v153 offset:16384
	ds_read_b128 v[188:191], v153 offset:17408
	ds_read_b128 v[192:195], v153 offset:18432
	ds_read_b128 v[196:199], v153 offset:19456
	ds_read_b128 v[200:203], v153 offset:20480
	ds_read_b128 v[206:209], v153 offset:21504
	ds_read_b128 v[210:213], v153 offset:22528
	ds_read_b128 v[214:217], v153 offset:23552
	global_load_lds_dwordx4 v132, s[42:43]
	s_add_i32 m0, s63, 0x2000
	s_add_u32 s98, s42, 0x80
	s_addc_u32 s99, s43, 0
	s_add_u32 s64, s42, 0x40000
	s_addc_u32 s65, s43, 0
	s_add_i32 s63, s56, s33
	global_load_lds_dwordx4 v136, s[42:43]
	s_mov_b32 m0, s63
	s_nop 0
	global_load_lds_dwordx4 v132, s[64:65]
	s_add_i32 m0, s63, 0x2000
	s_nop 0
	global_load_lds_dwordx4 v136, s[64:65]
	s_mov_b32 m0, s46
	s_nop 0
	global_load_lds_dwordx4 v130, s[44:45]
	s_mov_b32 m0, s47
	s_nop 0
	global_load_lds_dwordx4 v134, s[44:45]
	s_waitcnt vmcnt(8)
	s_waitcnt lgkmcnt(0)
	s_barrier
	v_mfma_f32_16x16x32_bf16 v[60:63], v[146:149], v[184:187], v[60:63]
	v_mfma_f32_16x16x32_bf16 v[56:59], v[160:163], v[184:187], v[56:59]
	v_mfma_f32_16x16x32_bf16 v[44:47], v[146:149], v[192:195], v[44:47]
	v_mfma_f32_16x16x32_bf16 v[40:43], v[160:163], v[192:195], v[40:43]
	v_mfma_f32_16x16x32_bf16 v[28:31], v[146:149], v[200:203], v[28:31]
	v_mfma_f32_16x16x32_bf16 v[24:27], v[160:163], v[200:203], v[24:27]
	v_mfma_f32_16x16x32_bf16 v[12:15], v[146:149], v[210:213], v[12:15]
	v_mfma_f32_16x16x32_bf16 v[8:11], v[160:163], v[210:213], v[8:11]
	v_mfma_f32_16x16x32_bf16 v[60:63], v[156:159], v[188:191], v[60:63]
	v_mfma_f32_16x16x32_bf16 v[56:59], v[164:167], v[188:191], v[56:59]
	v_mfma_f32_16x16x32_bf16 v[44:47], v[156:159], v[196:199], v[44:47]
	v_mfma_f32_16x16x32_bf16 v[40:43], v[164:167], v[196:199], v[40:43]
	v_mfma_f32_16x16x32_bf16 v[28:31], v[156:159], v[206:209], v[28:31]
	v_mfma_f32_16x16x32_bf16 v[24:27], v[164:167], v[206:209], v[24:27]
	v_mfma_f32_16x16x32_bf16 v[12:15], v[156:159], v[214:217], v[12:15]
	v_mfma_f32_16x16x32_bf16 v[8:11], v[164:167], v[214:217], v[8:11]
	v_mfma_f32_16x16x32_bf16 v[52:55], v[168:171], v[184:187], v[52:55]
	v_mfma_f32_16x16x32_bf16 v[48:51], v[176:179], v[184:187], v[48:51]
	v_mfma_f32_16x16x32_bf16 v[36:39], v[168:171], v[192:195], v[36:39]
	v_mfma_f32_16x16x32_bf16 v[32:35], v[176:179], v[192:195], v[32:35]
	v_mfma_f32_16x16x32_bf16 v[20:23], v[168:171], v[200:203], v[20:23]
	v_mfma_f32_16x16x32_bf16 v[16:19], v[176:179], v[200:203], v[16:19]
	v_mfma_f32_16x16x32_bf16 v[4:7], v[168:171], v[210:213], v[4:7]
	v_mfma_f32_16x16x32_bf16 v[0:3], v[176:179], v[210:213], v[0:3]
	v_mfma_f32_16x16x32_bf16 v[52:55], v[172:175], v[188:191], v[52:55]
	v_mfma_f32_16x16x32_bf16 v[48:51], v[180:183], v[188:191], v[48:51]
	v_mfma_f32_16x16x32_bf16 v[36:39], v[172:175], v[196:199], v[36:39]
	v_mfma_f32_16x16x32_bf16 v[32:35], v[180:183], v[196:199], v[32:35]
	v_mfma_f32_16x16x32_bf16 v[20:23], v[172:175], v[206:209], v[20:23]
	v_mfma_f32_16x16x32_bf16 v[16:19], v[180:183], v[206:209], v[16:19]
	v_mfma_f32_16x16x32_bf16 v[4:7], v[172:175], v[214:217], v[4:7]
	v_mfma_f32_16x16x32_bf16 v[0:3], v[180:183], v[214:217], v[0:3]
	s_barrier
; #define PG8_STAGE(bufoff, gbase, voff) do { _Pragma("unroll") for (int _i = 0; _i < 2; ++_i) \
;         __builtin_amdgcn_global_load_lds((const unsigned*)((const char*)(gbase) + (voff)[_i]), (PG8_LAS unsigned*)(lds + (bufoff) + ldsw + _i * 8192), 16, 0, 0); } while (0)
; #define PG8_LDA(dst, b, h) do { _Pragma("unroll") for (int m = 0; m < 4; ++m) _Pragma("unroll") for (int k = 0; k < 2; ++k) dst[m][k] = *(const PG8_LAS bf16x8*)(lds + PG8_SA(b, h) + aoff + m * 2048 + k * 1024); } while (0)
; #define PG8_LDB(dst, b, h) do { _Pragma("unroll") for (int n = 0; n < 2; ++n) _Pragma("unroll") for (int k = 0; k < 2; ++k) dst[n][k] = *(const PG8_LAS bf16x8*)(lds + PG8_SB(b, h) + boff + n * 2048 + k * 1024); } while (0)
; #define PG8_MMA(ai, bj, At, Bt) do { __builtin_amdgcn_s_setprio(1); _Pragma("unroll") for (int m = 0; m < 4; ++m) _Pragma("unroll") for (int n = 0; n < 2; ++n) _Pragma("unroll") for (int k = 0; k < 2; ++k) \
;         acc[ai][bj][m][n] = __builtin_amdgcn_mfma_f32_16x16x32_bf16(Bt[n][k], At[m][k], acc[ai][bj][m][n], 0, 0, 0); __builtin_amdgcn_s_setprio(0); } while (0)
; #define PG8_WAIT_V(n) asm volatile("s_waitcnt vmcnt(" #n ")" ::: "memory")
; #define PG8_WAIT_L(n) asm volatile("s_waitcnt lgkmcnt(" #n ")" ::: "memory")
; #define PG8_BAR __builtin_amdgcn_s_barrier()
; #define PG8_SCHED __builtin_amdgcn_sched_barrier(0)
; template <class Epi, class Sched, bool ALIGN_EPI = false, bool SP2 = false>
; __device__ __forceinline__ void gemm_phase(PG8_LAS unsigned char* lds, const Gemm g, const Sched& S, const Epi& E) {
;     ...
;             PG8_LDB(B0, 1, 0); PG8_LDB(B1, 1, 1); PG8_SCHED; PG8_LDA(At, 1, 0); PG8_STAGE(PG8_SA(0, 1), a2 + hstep, voffA);
;             PG8_WAIT_V(8); PG8_WAIT_L(0); PG8_BAR; PG8_MMA(0, 0, At, B0); PG8_MMA(0, 1, At, B1); PG8_BAR; PG8_SCHED;
;             PG8_LDA(At, 1, 1); PG8_STAGE(PG8_SB(1, 0), b3, voffB); PG8_STAGE(PG8_SB(1, 1), b3 + hstep, voffB); PG8_STAGE(PG8_SA(1, 0), a3, voffA);
;             PG8_WAIT_V(8); PG8_WAIT_L(0); PG8_BAR; PG8_MMA(1, 0, At, B0); PG8_MMA(1, 1, At, B1); PG8_BAR; PG8_SCHED;
;     ...
;         if constexpr (ALIGN_EPI) { if (wr == 0) PG8_BAR; }
	s_add_i32 s63, 0, 0x18000
	s_add_i32 s64, 0, 0x1c000
	ds_read_b128 v[146:149], v240
	ds_read_b128 v[156:159], v240 offset:1024
	ds_read_b128 v[160:163], v240 offset:2048
	ds_read_b128 v[164:167], v240 offset:3072
	ds_read_b128 v[168:171], v241
	ds_read_b128 v[172:175], v241 offset:1024
	ds_read_b128 v[176:179], v241 offset:2048
	ds_read_b128 v[180:183], v241 offset:3072
	s_add_u32 s100, s44, 0x80
	s_addc_u32 s101, s45, 0
	s_add_u32 s44, s44, 0x40000
	s_addc_u32 s45, s45, 0
	s_mov_b32 m0, s48
	ds_read_b128 v[184:187], v153 offset:32768
	ds_read_b128 v[188:191], v153 offset:33792
	ds_read_b128 v[192:195], v153 offset:34816
	ds_read_b128 v[196:199], v153 offset:35840
	ds_read_b128 v[200:203], v153 offset:36864
	ds_read_b128 v[206:209], v153 offset:37888
	ds_read_b128 v[210:213], v153 offset:38912
	ds_read_b128 v[214:217], v153 offset:39936
	global_load_lds_dwordx4 v130, s[44:45]
	s_mov_b32 m0, s49
	s_nop 0
	global_load_lds_dwordx4 v134, s[44:45]
	s_waitcnt vmcnt(8)
	s_waitcnt lgkmcnt(0)
	s_barrier
	v_mfma_f32_16x16x32_bf16 v[124:127], v[146:149], v[184:187], v[124:127]
	v_mfma_f32_16x16x32_bf16 v[120:123], v[160:163], v[184:187], v[120:123]
	v_mfma_f32_16x16x32_bf16 v[108:111], v[146:149], v[192:195], v[108:111]
	v_mfma_f32_16x16x32_bf16 v[104:107], v[160:163], v[192:195], v[104:107]
	v_mfma_f32_16x16x32_bf16 v[92:95], v[146:149], v[200:203], v[92:95]
	v_mfma_f32_16x16x32_bf16 v[88:91], v[160:163], v[200:203], v[88:91]
	v_mfma_f32_16x16x32_bf16 v[76:79], v[146:149], v[210:213], v[76:79]
	v_mfma_f32_16x16x32_bf16 v[72:75], v[160:163], v[210:213], v[72:75]
	v_mfma_f32_16x16x32_bf16 v[124:127], v[156:159], v[188:191], v[124:127]
	v_mfma_f32_16x16x32_bf16 v[120:123], v[164:167], v[188:191], v[120:123]
	v_mfma_f32_16x16x32_bf16 v[108:111], v[156:159], v[196:199], v[108:111]
	v_mfma_f32_16x16x32_bf16 v[104:107], v[164:167], v[196:199], v[104:107]
	v_mfma_f32_16x16x32_bf16 v[92:95], v[156:159], v[206:209], v[92:95]
	v_mfma_f32_16x16x32_bf16 v[88:91], v[164:167], v[206:209], v[88:91]
	v_mfma_f32_16x16x32_bf16 v[76:79], v[156:159], v[214:217], v[76:79]
	v_mfma_f32_16x16x32_bf16 v[72:75], v[164:167], v[214:217], v[72:75]
	v_mfma_f32_16x16x32_bf16 v[116:119], v[168:171], v[184:187], v[116:119]
	v_mfma_f32_16x16x32_bf16 v[112:115], v[176:179], v[184:187], v[112:115]
	v_mfma_f32_16x16x32_bf16 v[100:103], v[168:171], v[192:195], v[100:103]
	v_mfma_f32_16x16x32_bf16 v[96:99], v[176:179], v[192:195], v[96:99]
	v_mfma_f32_16x16x32_bf16 v[84:87], v[168:171], v[200:203], v[84:87]
	v_mfma_f32_16x16x32_bf16 v[80:83], v[176:179], v[200:203], v[80:83]
	v_mfma_f32_16x16x32_bf16 v[68:71], v[168:171], v[210:213], v[68:71]
	v_mfma_f32_16x16x32_bf16 v[64:67], v[176:179], v[210:213], v[64:67]
	v_mfma_f32_16x16x32_bf16 v[116:119], v[172:175], v[188:191], v[116:119]
	v_mfma_f32_16x16x32_bf16 v[112:115], v[180:183], v[188:191], v[112:115]
	v_mfma_f32_16x16x32_bf16 v[100:103], v[172:175], v[196:199], v[100:103]
	v_mfma_f32_16x16x32_bf16 v[96:99], v[180:183], v[196:199], v[96:99]
	v_mfma_f32_16x16x32_bf16 v[84:87], v[172:175], v[206:209], v[84:87]
	v_mfma_f32_16x16x32_bf16 v[80:83], v[180:183], v[206:209], v[80:83]
	v_mfma_f32_16x16x32_bf16 v[68:71], v[172:175], v[214:217], v[68:71]
	v_mfma_f32_16x16x32_bf16 v[64:67], v[180:183], v[214:217], v[64:67]
	s_barrier
	s_add_i32 s44, s63, s33
	s_mov_b32 m0, s44
	ds_read_b128 v[184:187], v153 offset:49152
	ds_read_b128 v[188:191], v153 offset:50176
	ds_read_b128 v[192:195], v153 offset:51200
	ds_read_b128 v[196:199], v153 offset:52224
	ds_read_b128 v[200:203], v153 offset:53248
	ds_read_b128 v[206:209], v153 offset:54272
	ds_read_b128 v[210:213], v153 offset:55296
	ds_read_b128 v[214:217], v153 offset:56320
	global_load_lds_dwordx4 v132, s[98:99]
	s_add_i32 m0, s44, 0x2000
	s_add_u32 s42, s42, 0x40080
	s_addc_u32 s43, s43, 0
	s_add_i32 s44, s64, s33
	global_load_lds_dwordx4 v136, s[98:99]
	s_mov_b32 m0, s44
	s_nop 0
	global_load_lds_dwordx4 v132, s[42:43]
	s_add_i32 m0, s44, 0x2000
	s_nop 0
	global_load_lds_dwordx4 v136, s[42:43]
	s_mov_b32 m0, s52
	s_nop 0
	global_load_lds_dwordx4 v130, s[100:101]
	s_mov_b32 m0, s53
	s_nop 0
	global_load_lds_dwordx4 v134, s[100:101]
	s_waitcnt vmcnt(8)
	s_waitcnt lgkmcnt(0)
	s_barrier
	v_mfma_f32_16x16x32_bf16 v[60:63], v[146:149], v[184:187], v[60:63]
	v_mfma_f32_16x16x32_bf16 v[56:59], v[160:163], v[184:187], v[56:59]
	v_mfma_f32_16x16x32_bf16 v[44:47], v[146:149], v[192:195], v[44:47]
	v_mfma_f32_16x16x32_bf16 v[40:43], v[160:163], v[192:195], v[40:43]
	v_mfma_f32_16x16x32_bf16 v[28:31], v[146:149], v[200:203], v[28:31]
	v_mfma_f32_16x16x32_bf16 v[24:27], v[160:163], v[200:203], v[24:27]
	v_mfma_f32_16x16x32_bf16 v[12:15], v[146:149], v[210:213], v[12:15]
	v_mfma_f32_16x16x32_bf16 v[8:11], v[160:163], v[210:213], v[8:11]
	v_mfma_f32_16x16x32_bf16 v[60:63], v[156:159], v[188:191], v[60:63]
	v_mfma_f32_16x16x32_bf16 v[56:59], v[164:167], v[188:191], v[56:59]
	v_mfma_f32_16x16x32_bf16 v[44:47], v[156:159], v[196:199], v[44:47]
	v_mfma_f32_16x16x32_bf16 v[40:43], v[164:167], v[196:199], v[40:43]
	v_mfma_f32_16x16x32_bf16 v[28:31], v[156:159], v[206:209], v[28:31]
	v_mfma_f32_16x16x32_bf16 v[24:27], v[164:167], v[206:209], v[24:27]
	v_mfma_f32_16x16x32_bf16 v[12:15], v[156:159], v[214:217], v[12:15]
	v_mfma_f32_16x16x32_bf16 v[8:11], v[164:167], v[214:217], v[8:11]
	v_mfma_f32_16x16x32_bf16 v[52:55], v[168:171], v[184:187], v[52:55]
	v_mfma_f32_16x16x32_bf16 v[48:51], v[176:179], v[184:187], v[48:51]
	v_mfma_f32_16x16x32_bf16 v[36:39], v[168:171], v[192:195], v[36:39]
	v_mfma_f32_16x16x32_bf16 v[32:35], v[176:179], v[192:195], v[32:35]
	v_mfma_f32_16x16x32_bf16 v[20:23], v[168:171], v[200:203], v[20:23]
	v_mfma_f32_16x16x32_bf16 v[16:19], v[176:179], v[200:203], v[16:19]
	v_mfma_f32_16x16x32_bf16 v[4:7], v[168:171], v[210:213], v[4:7]
	v_mfma_f32_16x16x32_bf16 v[0:3], v[176:179], v[210:213], v[0:3]
	v_mfma_f32_16x16x32_bf16 v[52:55], v[172:175], v[188:191], v[52:55]
	v_mfma_f32_16x16x32_bf16 v[48:51], v[180:183], v[188:191], v[48:51]
	v_mfma_f32_16x16x32_bf16 v[36:39], v[172:175], v[196:199], v[36:39]
	v_mfma_f32_16x16x32_bf16 v[32:35], v[180:183], v[196:199], v[32:35]
	v_mfma_f32_16x16x32_bf16 v[20:23], v[172:175], v[206:209], v[20:23]
	v_mfma_f32_16x16x32_bf16 v[16:19], v[180:183], v[206:209], v[16:19]
	v_mfma_f32_16x16x32_bf16 v[4:7], v[172:175], v[214:217], v[4:7]
	v_mfma_f32_16x16x32_bf16 v[0:3], v[180:183], v[214:217], v[0:3]
	s_barrier
	s_add_i32 s62, s62, 2
	s_add_u32 s40, s40, 0x100
	s_addc_u32 s41, s41, 0
	s_add_u32 s60, s60, 0x100
	s_addc_u32 s61, s61, 0
	s_cmp_gt_u32 s62, 13
	s_cbranch_scc0 .LBB0_905
	s_setprio 0
	s_and_b64 vcc, exec, s[28:29]
	s_cbranch_vccz .LBB0_908
	s_barrier

; #define PG8_STAGE(bufoff, gbase, voff) do { _Pragma("unroll") for (int _i = 0; _i < 2; ++_i) \
;         __builtin_amdgcn_global_load_lds((const unsigned*)((const char*)(gbase) + (voff)[_i]), (PG8_LAS unsigned*)(lds + (bufoff) + ldsw + _i * 8192), 16, 0, 0); } while (0)
; #define PG8_LDA(dst, b, h) do { _Pragma("unroll") for (int m = 0; m < 4; ++m) _Pragma("unroll") for (int k = 0; k < 2; ++k) dst[m][k] = *(const PG8_LAS bf16x8*)(lds + PG8_SA(b, h) + aoff + m * 2048 + k * 1024); } while (0)
; #define PG8_LDB(dst, b, h) do { _Pragma("unroll") for (int n = 0; n < 2; ++n) _Pragma("unroll") for (int k = 0; k < 2; ++k) dst[n][k] = *(const PG8_LAS bf16x8*)(lds + PG8_SB(b, h) + boff + n * 2048 + k * 1024); } while (0)
; #define PG8_WAIT_V(n) asm volatile("s_waitcnt vmcnt(" #n ")" ::: "memory")
; #define PG8_WAIT_L(n) asm volatile("s_waitcnt lgkmcnt(" #n ")" ::: "memory")
; #define PG8_BAR __builtin_amdgcn_s_barrier()
; #define PG8_SCHED __builtin_amdgcn_sched_barrier(0)
; template <class Epi, class Sched, bool ALIGN_EPI = false, bool SP2 = false>
; __device__ __forceinline__ void gemm_phase(PG8_LAS unsigned char* lds, const Gemm g, const Sched& S, const Epi& E) {
;     ...
;         const bool has_next = S.next(ui + 1, nxt);
;         const char* nA = has_next ? (const char*)g.A + (size_t)nxt.pm * tstep : cA; const char* nB = has_next ? (const char*)g.Bt + (size_t)nxt.pn * tstep : cB;
;         for (int t = 0; t < nt; t += 2) {
;             const bool last = (t == nt - 2);
;             const char* a1 = cA + (size_t)(t + 1) * kstep;
;             const char* a2 = last ? nA : cA + (size_t)(t + 2) * kstep; const char* b2 = last ? nB : cB + (size_t)(t + 2) * kstep;
;             const char* a3 = a2 + kstep; const char* b3 = b2 + kstep;
;             if (last && has_next) S.a_ready(nxt);
;             if constexpr (SP2) {
;             PG8_LDB(B0, 0, 0); PG8_LDB(B1, 0, 1); PG8_SCHED; PG8_LDA(At, 0, 0); PG8_STAGE(PG8_SA(1, 1), a1 + hstep, voffA);
;             PG8_WAIT_V(8); PG8_WAIT_L(0); PG8_BAR; PG8_MMA(0, 0, At, B0); PG8_MMA(0, 1, At, B1); PG8_BAR; PG8_SCHED;
;     ...
; #pragma unroll
;         for (int a = 0; a < 2; ++a)
; #pragma unroll
;             for (int b = 0; b < 2; ++b)
; #pragma unroll
;                 for (int m = 0; m < 4; ++m)
; #pragma unroll
;                     for (int n = 0; n < 2; ++n) acc[a][b][m][n] = (f32x4){0.f, 0.f, 0.f, 0.f};
.LBB0_1000:
	s_ashr_i32 s21, s20, 31
	s_lshl_b64 s[22:23], s[20:21], 21
	v_readlane_b32 s16, v255, 26
	v_readlane_b32 s17, v255, 27
	s_add_u32 s22, s16, s22
	s_addc_u32 s23, s17, s23
	s_and_b64 s[24:25], s[6:7], exec
	s_cselect_b32 s21, s23, s29
	s_cselect_b32 s47, s22, s28
	s_ashr_i32 s19, s18, 31
	s_lshl_b64 s[24:25], s[18:19], 21
	s_add_u32 s24, s66, s24
	s_addc_u32 s25, s67, s25
	s_and_b64 s[34:35], s[6:7], exec
	s_cselect_b32 s19, s25, s31
	s_cselect_b32 s48, s24, s30
	s_add_u32 s28, s28, 0x100080
	s_addc_u32 s29, s29, 0
	s_add_u32 s49, s30, 0x100
	v_mov_b32_e32 v0, 0
	s_addc_u32 s50, s31, 0
	s_mov_b32 s51, -2
	v_mov_b32_e32 v1, v0
	v_mov_b32_e32 v2, v0
	v_mov_b32_e32 v3, v0
	v_mov_b32_e32 v4, v0
	v_mov_b32_e32 v5, v0
	v_mov_b32_e32 v6, v0
	v_mov_b32_e32 v7, v0
	v_mov_b32_e32 v16, v0
	v_mov_b32_e32 v17, v0
	v_mov_b32_e32 v18, v0
	v_mov_b32_e32 v19, v0
	v_mov_b32_e32 v20, v0
	v_mov_b32_e32 v21, v0
	v_mov_b32_e32 v22, v0
	v_mov_b32_e32 v23, v0
	v_mov_b32_e32 v32, v0
	v_mov_b32_e32 v33, v0
	v_mov_b32_e32 v34, v0
	v_mov_b32_e32 v35, v0
	v_mov_b32_e32 v36, v0
	v_mov_b32_e32 v37, v0
	v_mov_b32_e32 v38, v0
	v_mov_b32_e32 v39, v0
	v_mov_b32_e32 v48, v0
	v_mov_b32_e32 v49, v0
	v_mov_b32_e32 v50, v0
	v_mov_b32_e32 v51, v0
	v_mov_b32_e32 v52, v0
	v_mov_b32_e32 v53, v0
	v_mov_b32_e32 v54, v0
	v_mov_b32_e32 v55, v0
	v_mov_b32_e32 v8, v0
	v_mov_b32_e32 v9, v0
	v_mov_b32_e32 v10, v0
	v_mov_b32_e32 v11, v0
	v_mov_b32_e32 v12, v0
	v_mov_b32_e32 v13, v0
	v_mov_b32_e32 v14, v0
	v_mov_b32_e32 v15, v0
	v_mov_b32_e32 v24, v0
	v_mov_b32_e32 v25, v0
	v_mov_b32_e32 v26, v0
	v_mov_b32_e32 v27, v0
	v_mov_b32_e32 v28, v0
	v_mov_b32_e32 v29, v0
	v_mov_b32_e32 v30, v0
	v_mov_b32_e32 v31, v0
	v_mov_b32_e32 v40, v0
	v_mov_b32_e32 v41, v0
	v_mov_b32_e32 v42, v0
	v_mov_b32_e32 v43, v0
	v_mov_b32_e32 v44, v0
	v_mov_b32_e32 v45, v0
	v_mov_b32_e32 v46, v0
	v_mov_b32_e32 v47, v0
	v_mov_b32_e32 v56, v0
	v_mov_b32_e32 v57, v0
	v_mov_b32_e32 v58, v0
	v_mov_b32_e32 v59, v0
	v_mov_b32_e32 v60, v0
	v_mov_b32_e32 v61, v0
	v_mov_b32_e32 v62, v0
	v_mov_b32_e32 v63, v0
	v_mov_b32_e32 v64, v0
	v_mov_b32_e32 v65, v0
	v_mov_b32_e32 v66, v0
	v_mov_b32_e32 v67, v0
	v_mov_b32_e32 v68, v0
	v_mov_b32_e32 v69, v0
	v_mov_b32_e32 v70, v0
	v_mov_b32_e32 v71, v0
	v_mov_b32_e32 v80, v0
	v_mov_b32_e32 v81, v0
	v_mov_b32_e32 v82, v0
	v_mov_b32_e32 v83, v0
	v_mov_b32_e32 v84, v0
	v_mov_b32_e32 v85, v0
	v_mov_b32_e32 v86, v0
	v_mov_b32_e32 v87, v0
	v_mov_b32_e32 v96, v0
	v_mov_b32_e32 v97, v0
	v_mov_b32_e32 v98, v0
	v_mov_b32_e32 v99, v0
	v_mov_b32_e32 v100, v0
	v_mov_b32_e32 v101, v0
	v_mov_b32_e32 v102, v0
	v_mov_b32_e32 v103, v0
	v_mov_b32_e32 v112, v0
	v_mov_b32_e32 v113, v0
	v_mov_b32_e32 v114, v0
	v_mov_b32_e32 v115, v0
	v_mov_b32_e32 v116, v0
	v_mov_b32_e32 v117, v0
	v_mov_b32_e32 v118, v0
	v_mov_b32_e32 v119, v0
	v_mov_b32_e32 v72, v0
	v_mov_b32_e32 v73, v0
	v_mov_b32_e32 v74, v0
	v_mov_b32_e32 v75, v0
	v_mov_b32_e32 v76, v0
	v_mov_b32_e32 v77, v0
	v_mov_b32_e32 v78, v0
	v_mov_b32_e32 v79, v0
	v_mov_b32_e32 v88, v0
	v_mov_b32_e32 v89, v0
	v_mov_b32_e32 v90, v0
	v_mov_b32_e32 v91, v0
	v_mov_b32_e32 v92, v0
	v_mov_b32_e32 v93, v0
	v_mov_b32_e32 v94, v0
	v_mov_b32_e32 v95, v0
	v_mov_b32_e32 v104, v0
	v_mov_b32_e32 v105, v0
	v_mov_b32_e32 v106, v0
	v_mov_b32_e32 v107, v0
	v_mov_b32_e32 v108, v0
	v_mov_b32_e32 v109, v0
	v_mov_b32_e32 v110, v0
	v_mov_b32_e32 v111, v0
	v_mov_b32_e32 v120, v0
	v_mov_b32_e32 v121, v0
	v_mov_b32_e32 v122, v0
	v_mov_b32_e32 v123, v0
	v_mov_b32_e32 v124, v0
	v_mov_b32_e32 v125, v0
	v_mov_b32_e32 v126, v0
	v_mov_b32_e32 v127, v0
	v_add_u32_e32 v240, 0x18000, v150
	v_add_u32_e32 v241, 0x1c000, v150
	s_and_b64 vcc, exec, s[14:15]
	s_cbranch_vccz .Lsp5
	s_setprio 1
.Lsp5:
.LBB0_1001:
	ds_read_b128 v[146:149], v152
	ds_read_b128 v[156:159], v152 offset:1024
	ds_read_b128 v[160:163], v152 offset:2048
	ds_read_b128 v[164:167], v152 offset:3072
	ds_read_b128 v[168:171], v153
	ds_read_b128 v[172:175], v153 offset:1024
	ds_read_b128 v[176:179], v153 offset:2048
	ds_read_b128 v[180:183], v153 offset:3072
	s_add_u32 s30, s28, 0xfff00080
	s_addc_u32 s31, s29, -1
	s_cmp_eq_u32 s51, 60
	s_cselect_b32 s35, s21, s31
	s_cselect_b32 s34, s47, s30
	s_cselect_b32 s31, s19, s50
	s_cselect_b32 s30, s48, s49
	s_add_i32 m0, s27, 0xc000
	ds_read_b128 v[184:187], v154
	ds_read_b128 v[188:191], v154 offset:1024
	ds_read_b128 v[192:195], v154 offset:2048
	ds_read_b128 v[196:199], v154 offset:3072
	ds_read_b128 v[200:203], v154 offset:4096
	ds_read_b128 v[206:209], v154 offset:5120
	ds_read_b128 v[210:213], v154 offset:6144
	ds_read_b128 v[214:217], v154 offset:7168
	global_load_lds_dwordx4 v138, s[28:29]
	s_add_i32 m0, s27, 0xe000
	s_nop 0
	global_load_lds_dwordx4 v140, s[28:29]
	s_waitcnt vmcnt(8)
	s_waitcnt lgkmcnt(0)
	s_barrier
; #define PG8_STAGE(bufoff, gbase, voff) do { _Pragma("unroll") for (int _i = 0; _i < 2; ++_i) \
;         __builtin_amdgcn_global_load_lds((const unsigned*)((const char*)(gbase) + (voff)[_i]), (PG8_LAS unsigned*)(lds + (bufoff) + ldsw + _i * 8192), 16, 0, 0); } while (0)
; #define PG8_LDA(dst, b, h) do { _Pragma("unroll") for (int m = 0; m < 4; ++m) _Pragma("unroll") for (int k = 0; k < 2; ++k) dst[m][k] = *(const PG8_LAS bf16x8*)(lds + PG8_SA(b, h) + aoff + m * 2048 + k * 1024); } while (0)
; #define PG8_MMA(ai, bj, At, Bt) do { __builtin_amdgcn_s_setprio(1); _Pragma("unroll") for (int m = 0; m < 4; ++m) _Pragma("unroll") for (int n = 0; n < 2; ++n) _Pragma("unroll") for (int k = 0; k < 2; ++k) \
;         acc[ai][bj][m][n] = __builtin_amdgcn_mfma_f32_16x16x32_bf16(Bt[n][k], At[m][k], acc[ai][bj][m][n], 0, 0, 0); __builtin_amdgcn_s_setprio(0); } while (0)
; #define PG8_WAIT_V(n) asm volatile("s_waitcnt vmcnt(" #n ")" ::: "memory")
; #define PG8_WAIT_L(n) asm volatile("s_waitcnt lgkmcnt(" #n ")" ::: "memory")
; #define PG8_BAR __builtin_amdgcn_s_barrier()
; #define PG8_SCHED __builtin_amdgcn_sched_barrier(0)
; template <class Epi, class Sched, bool ALIGN_EPI = false, bool SP2 = false>
; __device__ __forceinline__ void gemm_phase(PG8_LAS unsigned char* lds, const Gemm g, const Sched& S, const Epi& E) {
;     ...
;             PG8_WAIT_V(8); PG8_WAIT_L(0); PG8_BAR; PG8_MMA(0, 0, At, B0); PG8_MMA(0, 1, At, B1); PG8_BAR; PG8_SCHED;
;             PG8_LDA(At, 0, 1); PG8_STAGE(PG8_SB(0, 0), b2, voffB); PG8_STAGE(PG8_SB(0, 1), b2 + hstep, voffB); PG8_STAGE(PG8_SA(0, 0), a2, voffA);
;             PG8_WAIT_V(8); PG8_WAIT_L(0); PG8_BAR; PG8_MMA(1, 0, At, B0); PG8_MMA(1, 1, At, B1); PG8_BAR; PG8_SCHED;
	v_mfma_f32_16x16x32_bf16 v[124:127], v[146:149], v[184:187], v[124:127]
	v_mfma_f32_16x16x32_bf16 v[120:123], v[160:163], v[184:187], v[120:123]
	v_mfma_f32_16x16x32_bf16 v[108:111], v[146:149], v[192:195], v[108:111]
	v_mfma_f32_16x16x32_bf16 v[104:107], v[160:163], v[192:195], v[104:107]
	v_mfma_f32_16x16x32_bf16 v[92:95], v[146:149], v[200:203], v[92:95]
	v_mfma_f32_16x16x32_bf16 v[88:91], v[160:163], v[200:203], v[88:91]
	v_mfma_f32_16x16x32_bf16 v[76:79], v[146:149], v[210:213], v[76:79]
	v_mfma_f32_16x16x32_bf16 v[72:75], v[160:163], v[210:213], v[72:75]
	v_mfma_f32_16x16x32_bf16 v[124:127], v[156:159], v[188:191], v[124:127]
	v_mfma_f32_16x16x32_bf16 v[120:123], v[164:167], v[188:191], v[120:123]
	v_mfma_f32_16x16x32_bf16 v[108:111], v[156:159], v[196:199], v[108:111]
	v_mfma_f32_16x16x32_bf16 v[104:107], v[164:167], v[196:199], v[104:107]
	v_mfma_f32_16x16x32_bf16 v[92:95], v[156:159], v[206:209], v[92:95]
	v_mfma_f32_16x16x32_bf16 v[88:91], v[164:167], v[206:209], v[88:91]
	v_mfma_f32_16x16x32_bf16 v[76:79], v[156:159], v[214:217], v[76:79]
	v_mfma_f32_16x16x32_bf16 v[72:75], v[164:167], v[214:217], v[72:75]
	v_mfma_f32_16x16x32_bf16 v[116:119], v[168:171], v[184:187], v[116:119]
	v_mfma_f32_16x16x32_bf16 v[112:115], v[176:179], v[184:187], v[112:115]
	v_mfma_f32_16x16x32_bf16 v[100:103], v[168:171], v[192:195], v[100:103]
	v_mfma_f32_16x16x32_bf16 v[96:99], v[176:179], v[192:195], v[96:99]
	v_mfma_f32_16x16x32_bf16 v[84:87], v[168:171], v[200:203], v[84:87]
	v_mfma_f32_16x16x32_bf16 v[80:83], v[176:179], v[200:203], v[80:83]
	v_mfma_f32_16x16x32_bf16 v[68:71], v[168:171], v[210:213], v[68:71]
	v_mfma_f32_16x16x32_bf16 v[64:67], v[176:179], v[210:213], v[64:67]
	v_mfma_f32_16x16x32_bf16 v[116:119], v[172:175], v[188:191], v[116:119]
	v_mfma_f32_16x16x32_bf16 v[112:115], v[180:183], v[188:191], v[112:115]
	v_mfma_f32_16x16x32_bf16 v[100:103], v[172:175], v[196:199], v[100:103]
	v_mfma_f32_16x16x32_bf16 v[96:99], v[180:183], v[196:199], v[96:99]
	v_mfma_f32_16x16x32_bf16 v[84:87], v[172:175], v[206:209], v[84:87]
	v_mfma_f32_16x16x32_bf16 v[80:83], v[180:183], v[206:209], v[80:83]
	v_mfma_f32_16x16x32_bf16 v[68:71], v[172:175], v[214:217], v[68:71]
	v_mfma_f32_16x16x32_bf16 v[64:67], v[180:183], v[214:217], v[64:67]
	s_barrier
	s_add_i32 s52, s44, s33
	s_mov_b32 m0, s52
	ds_read_b128 v[184:187], v154 offset:16384
	ds_read_b128 v[188:191], v154 offset:17408
	ds_read_b128 v[192:195], v154 offset:18432
	ds_read_b128 v[196:199], v154 offset:19456
	ds_read_b128 v[200:203], v154 offset:20480
	ds_read_b128 v[206:209], v154 offset:21504
	ds_read_b128 v[210:213], v154 offset:22528
	ds_read_b128 v[214:217], v154 offset:23552
	global_load_lds_dwordx4 v132, s[30:31]
	s_add_i32 m0, s52, 0x2000
	s_add_u32 s98, s30, 0x80
	s_addc_u32 s99, s31, 0
	s_add_u32 s52, s30, 0x100000
	s_addc_u32 s53, s31, 0
	s_add_i32 s54, s45, s33
	global_load_lds_dwordx4 v136, s[30:31]
	s_mov_b32 m0, s54
	s_nop 0
	global_load_lds_dwordx4 v132, s[52:53]
	s_add_i32 m0, s54, 0x2000
	s_nop 0
	global_load_lds_dwordx4 v136, s[52:53]
	s_mov_b32 m0, s27
	s_nop 0
	global_load_lds_dwordx4 v130, s[34:35]
	s_mov_b32 m0, s36
	s_nop 0
	global_load_lds_dwordx4 v134, s[34:35]
	s_waitcnt vmcnt(8)
	s_waitcnt lgkmcnt(0)
	s_barrier
	v_mfma_f32_16x16x32_bf16 v[60:63], v[146:149], v[184:187], v[60:63]
	v_mfma_f32_16x16x32_bf16 v[56:59], v[160:163], v[184:187], v[56:59]
	v_mfma_f32_16x16x32_bf16 v[44:47], v[146:149], v[192:195], v[44:47]
	v_mfma_f32_16x16x32_bf16 v[40:43], v[160:163], v[192:195], v[40:43]
	v_mfma_f32_16x16x32_bf16 v[28:31], v[146:149], v[200:203], v[28:31]
	v_mfma_f32_16x16x32_bf16 v[24:27], v[160:163], v[200:203], v[24:27]
	v_mfma_f32_16x16x32_bf16 v[12:15], v[146:149], v[210:213], v[12:15]
	v_mfma_f32_16x16x32_bf16 v[8:11], v[160:163], v[210:213], v[8:11]
	v_mfma_f32_16x16x32_bf16 v[60:63], v[156:159], v[188:191], v[60:63]
	v_mfma_f32_16x16x32_bf16 v[56:59], v[164:167], v[188:191], v[56:59]
	v_mfma_f32_16x16x32_bf16 v[44:47], v[156:159], v[196:199], v[44:47]
	v_mfma_f32_16x16x32_bf16 v[40:43], v[164:167], v[196:199], v[40:43]
	v_mfma_f32_16x16x32_bf16 v[28:31], v[156:159], v[206:209], v[28:31]
	v_mfma_f32_16x16x32_bf16 v[24:27], v[164:167], v[206:209], v[24:27]
	v_mfma_f32_16x16x32_bf16 v[12:15], v[156:159], v[214:217], v[12:15]
	v_mfma_f32_16x16x32_bf16 v[8:11], v[164:167], v[214:217], v[8:11]
	v_mfma_f32_16x16x32_bf16 v[52:55], v[168:171], v[184:187], v[52:55]
	v_mfma_f32_16x16x32_bf16 v[48:51], v[176:179], v[184:187], v[48:51]
	v_mfma_f32_16x16x32_bf16 v[36:39], v[168:171], v[192:195], v[36:39]
	v_mfma_f32_16x16x32_bf16 v[32:35], v[176:179], v[192:195], v[32:35]
	v_mfma_f32_16x16x32_bf16 v[20:23], v[168:171], v[200:203], v[20:23]
	v_mfma_f32_16x16x32_bf16 v[16:19], v[176:179], v[200:203], v[16:19]
	v_mfma_f32_16x16x32_bf16 v[4:7], v[168:171], v[210:213], v[4:7]
	v_mfma_f32_16x16x32_bf16 v[0:3], v[176:179], v[210:213], v[0:3]
	v_mfma_f32_16x16x32_bf16 v[52:55], v[172:175], v[188:191], v[52:55]
	v_mfma_f32_16x16x32_bf16 v[48:51], v[180:183], v[188:191], v[48:51]
	v_mfma_f32_16x16x32_bf16 v[36:39], v[172:175], v[196:199], v[36:39]
	v_mfma_f32_16x16x32_bf16 v[32:35], v[180:183], v[196:199], v[32:35]
	v_mfma_f32_16x16x32_bf16 v[20:23], v[172:175], v[206:209], v[20:23]
	v_mfma_f32_16x16x32_bf16 v[16:19], v[180:183], v[206:209], v[16:19]
	v_mfma_f32_16x16x32_bf16 v[4:7], v[172:175], v[214:217], v[4:7]
	v_mfma_f32_16x16x32_bf16 v[0:3], v[180:183], v[214:217], v[0:3]
	s_barrier
; #define PG8_STAGE(bufoff, gbase, voff) do { _Pragma("unroll") for (int _i = 0; _i < 2; ++_i) \
;         __builtin_amdgcn_global_load_lds((const unsigned*)((const char*)(gbase) + (voff)[_i]), (PG8_LAS unsigned*)(lds + (bufoff) + ldsw + _i * 8192), 16, 0, 0); } while (0)
; #define PG8_LDA(dst, b, h) do { _Pragma("unroll") for (int m = 0; m < 4; ++m) _Pragma("unroll") for (int k = 0; k < 2; ++k) dst[m][k] = *(const PG8_LAS bf16x8*)(lds + PG8_SA(b, h) + aoff + m * 2048 + k * 1024); } while (0)
; #define PG8_LDB(dst, b, h) do { _Pragma("unroll") for (int n = 0; n < 2; ++n) _Pragma("unroll") for (int k = 0; k < 2; ++k) dst[n][k] = *(const PG8_LAS bf16x8*)(lds + PG8_SB(b, h) + boff + n * 2048 + k * 1024); } while (0)
; #define PG8_MMA(ai, bj, At, Bt) do { __builtin_amdgcn_s_setprio(1); _Pragma("unroll") for (int m = 0; m < 4; ++m) _Pragma("unroll") for (int n = 0; n < 2; ++n) _Pragma("unroll") for (int k = 0; k < 2; ++k) \
;         acc[ai][bj][m][n] = __builtin_amdgcn_mfma_f32_16x16x32_bf16(Bt[n][k], At[m][k], acc[ai][bj][m][n], 0, 0, 0); __builtin_amdgcn_s_setprio(0); } while (0)
; #define PG8_WAIT_V(n) asm volatile("s_waitcnt vmcnt(" #n ")" ::: "memory")
; #define PG8_WAIT_L(n) asm volatile("s_waitcnt lgkmcnt(" #n ")" ::: "memory")
; #define PG8_BAR __builtin_amdgcn_s_barrier()
; #define PG8_SCHED __builtin_amdgcn_sched_barrier(0)
; template <class Epi, class Sched, bool ALIGN_EPI = false, bool SP2 = false>
; __device__ __forceinline__ void gemm_phase(PG8_LAS unsigned char* lds, const Gemm g, const Sched& S, const Epi& E) {
;     ...
;             PG8_LDB(B0, 1, 0); PG8_LDB(B1, 1, 1); PG8_SCHED; PG8_LDA(At, 1, 0); PG8_STAGE(PG8_SA(0, 1), a2 + hstep, voffA);
;             PG8_WAIT_V(8); PG8_WAIT_L(0); PG8_BAR; PG8_MMA(0, 0, At, B0); PG8_MMA(0, 1, At, B1); PG8_BAR; PG8_SCHED;
;             PG8_LDA(At, 1, 1); PG8_STAGE(PG8_SB(1, 0), b3, voffB); PG8_STAGE(PG8_SB(1, 1), b3 + hstep, voffB); PG8_STAGE(PG8_SA(1, 0), a3, voffA);
;             PG8_WAIT_V(8); PG8_WAIT_L(0); PG8_BAR; PG8_MMA(1, 0, At, B0); PG8_MMA(1, 1, At, B1); PG8_BAR; PG8_SCHED;
;     ...
;         if constexpr (ALIGN_EPI) { if (wr == 0) PG8_BAR; }
	s_add_i32 s52, 0, 0x18000
	s_add_i32 s53, 0, 0x1c000
	ds_read_b128 v[146:149], v240
	ds_read_b128 v[156:159], v240 offset:1024
	ds_read_b128 v[160:163], v240 offset:2048
	ds_read_b128 v[164:167], v240 offset:3072
	ds_read_b128 v[168:171], v241
	ds_read_b128 v[172:175], v241 offset:1024
	ds_read_b128 v[176:179], v241 offset:2048
	ds_read_b128 v[180:183], v241 offset:3072
	s_add_u32 s100, s34, 0x80
	s_addc_u32 s101, s35, 0
	s_add_u32 s34, s34, 0x100000
	s_addc_u32 s35, s35, 0
	s_mov_b32 m0, s37
	ds_read_b128 v[184:187], v154 offset:32768
	ds_read_b128 v[188:191], v154 offset:33792
	ds_read_b128 v[192:195], v154 offset:34816
	ds_read_b128 v[196:199], v154 offset:35840
	ds_read_b128 v[200:203], v154 offset:36864
	ds_read_b128 v[206:209], v154 offset:37888
	ds_read_b128 v[210:213], v154 offset:38912
	ds_read_b128 v[214:217], v154 offset:39936
	global_load_lds_dwordx4 v130, s[34:35]
	s_mov_b32 m0, s38
	s_nop 0
	global_load_lds_dwordx4 v134, s[34:35]
	s_waitcnt vmcnt(8)
	s_waitcnt lgkmcnt(0)
	s_barrier
	v_mfma_f32_16x16x32_bf16 v[124:127], v[146:149], v[184:187], v[124:127]
	v_mfma_f32_16x16x32_bf16 v[120:123], v[160:163], v[184:187], v[120:123]
	v_mfma_f32_16x16x32_bf16 v[108:111], v[146:149], v[192:195], v[108:111]
	v_mfma_f32_16x16x32_bf16 v[104:107], v[160:163], v[192:195], v[104:107]
	v_mfma_f32_16x16x32_bf16 v[92:95], v[146:149], v[200:203], v[92:95]
	v_mfma_f32_16x16x32_bf16 v[88:91], v[160:163], v[200:203], v[88:91]
	v_mfma_f32_16x16x32_bf16 v[76:79], v[146:149], v[210:213], v[76:79]
	v_mfma_f32_16x16x32_bf16 v[72:75], v[160:163], v[210:213], v[72:75]
	v_mfma_f32_16x16x32_bf16 v[124:127], v[156:159], v[188:191], v[124:127]
	v_mfma_f32_16x16x32_bf16 v[120:123], v[164:167], v[188:191], v[120:123]
	v_mfma_f32_16x16x32_bf16 v[108:111], v[156:159], v[196:199], v[108:111]
	v_mfma_f32_16x16x32_bf16 v[104:107], v[164:167], v[196:199], v[104:107]
	v_mfma_f32_16x16x32_bf16 v[92:95], v[156:159], v[206:209], v[92:95]
	v_mfma_f32_16x16x32_bf16 v[88:91], v[164:167], v[206:209], v[88:91]
	v_mfma_f32_16x16x32_bf16 v[76:79], v[156:159], v[214:217], v[76:79]
	v_mfma_f32_16x16x32_bf16 v[72:75], v[164:167], v[214:217], v[72:75]
	v_mfma_f32_16x16x32_bf16 v[116:119], v[168:171], v[184:187], v[116:119]
	v_mfma_f32_16x16x32_bf16 v[112:115], v[176:179], v[184:187], v[112:115]
	v_mfma_f32_16x16x32_bf16 v[100:103], v[168:171], v[192:195], v[100:103]
	v_mfma_f32_16x16x32_bf16 v[96:99], v[176:179], v[192:195], v[96:99]
	v_mfma_f32_16x16x32_bf16 v[84:87], v[168:171], v[200:203], v[84:87]
	v_mfma_f32_16x16x32_bf16 v[80:83], v[176:179], v[200:203], v[80:83]
	v_mfma_f32_16x16x32_bf16 v[68:71], v[168:171], v[210:213], v[68:71]
	v_mfma_f32_16x16x32_bf16 v[64:67], v[176:179], v[210:213], v[64:67]
	v_mfma_f32_16x16x32_bf16 v[116:119], v[172:175], v[188:191], v[116:119]
	v_mfma_f32_16x16x32_bf16 v[112:115], v[180:183], v[188:191], v[112:115]
	v_mfma_f32_16x16x32_bf16 v[100:103], v[172:175], v[196:199], v[100:103]
	v_mfma_f32_16x16x32_bf16 v[96:99], v[180:183], v[196:199], v[96:99]
	v_mfma_f32_16x16x32_bf16 v[84:87], v[172:175], v[206:209], v[84:87]
	v_mfma_f32_16x16x32_bf16 v[80:83], v[180:183], v[206:209], v[80:83]
	v_mfma_f32_16x16x32_bf16 v[68:71], v[172:175], v[214:217], v[68:71]
	v_mfma_f32_16x16x32_bf16 v[64:67], v[180:183], v[214:217], v[64:67]
	s_barrier
	s_add_i32 s34, s52, s33
	s_mov_b32 m0, s34
	ds_read_b128 v[184:187], v154 offset:49152
	ds_read_b128 v[188:191], v154 offset:50176
	ds_read_b128 v[192:195], v154 offset:51200
	ds_read_b128 v[196:199], v154 offset:52224
	ds_read_b128 v[200:203], v154 offset:53248
	ds_read_b128 v[206:209], v154 offset:54272
	ds_read_b128 v[210:213], v154 offset:55296
	ds_read_b128 v[214:217], v154 offset:56320
	global_load_lds_dwordx4 v132, s[98:99]
	s_add_i32 m0, s34, 0x2000
	s_add_u32 s30, s30, 0x100080
	s_addc_u32 s31, s31, 0
	s_add_i32 s34, s53, s33
	global_load_lds_dwordx4 v136, s[98:99]
	s_mov_b32 m0, s34
	s_nop 0
	global_load_lds_dwordx4 v132, s[30:31]
	s_add_i32 m0, s34, 0x2000
	s_nop 0
	global_load_lds_dwordx4 v136, s[30:31]
	s_mov_b32 m0, s40
	s_nop 0
	global_load_lds_dwordx4 v130, s[100:101]
	s_mov_b32 m0, s41
	s_nop 0
	global_load_lds_dwordx4 v134, s[100:101]
	s_waitcnt vmcnt(8)
	s_waitcnt lgkmcnt(0)
	s_barrier
	v_mfma_f32_16x16x32_bf16 v[60:63], v[146:149], v[184:187], v[60:63]
	v_mfma_f32_16x16x32_bf16 v[56:59], v[160:163], v[184:187], v[56:59]
	v_mfma_f32_16x16x32_bf16 v[44:47], v[146:149], v[192:195], v[44:47]
	v_mfma_f32_16x16x32_bf16 v[40:43], v[160:163], v[192:195], v[40:43]
	v_mfma_f32_16x16x32_bf16 v[28:31], v[146:149], v[200:203], v[28:31]
	v_mfma_f32_16x16x32_bf16 v[24:27], v[160:163], v[200:203], v[24:27]
	v_mfma_f32_16x16x32_bf16 v[12:15], v[146:149], v[210:213], v[12:15]
	v_mfma_f32_16x16x32_bf16 v[8:11], v[160:163], v[210:213], v[8:11]
	v_mfma_f32_16x16x32_bf16 v[60:63], v[156:159], v[188:191], v[60:63]
	v_mfma_f32_16x16x32_bf16 v[56:59], v[164:167], v[188:191], v[56:59]
	v_mfma_f32_16x16x32_bf16 v[44:47], v[156:159], v[196:199], v[44:47]
	v_mfma_f32_16x16x32_bf16 v[40:43], v[164:167], v[196:199], v[40:43]
	v_mfma_f32_16x16x32_bf16 v[28:31], v[156:159], v[206:209], v[28:31]
	v_mfma_f32_16x16x32_bf16 v[24:27], v[164:167], v[206:209], v[24:27]
	v_mfma_f32_16x16x32_bf16 v[12:15], v[156:159], v[214:217], v[12:15]
	v_mfma_f32_16x16x32_bf16 v[8:11], v[164:167], v[214:217], v[8:11]
	v_mfma_f32_16x16x32_bf16 v[52:55], v[168:171], v[184:187], v[52:55]
	v_mfma_f32_16x16x32_bf16 v[48:51], v[176:179], v[184:187], v[48:51]
	v_mfma_f32_16x16x32_bf16 v[36:39], v[168:171], v[192:195], v[36:39]
	v_mfma_f32_16x16x32_bf16 v[32:35], v[176:179], v[192:195], v[32:35]
	v_mfma_f32_16x16x32_bf16 v[20:23], v[168:171], v[200:203], v[20:23]
	v_mfma_f32_16x16x32_bf16 v[16:19], v[176:179], v[200:203], v[16:19]
	v_mfma_f32_16x16x32_bf16 v[4:7], v[168:171], v[210:213], v[4:7]
	v_mfma_f32_16x16x32_bf16 v[0:3], v[176:179], v[210:213], v[0:3]
	v_mfma_f32_16x16x32_bf16 v[52:55], v[172:175], v[188:191], v[52:55]
	v_mfma_f32_16x16x32_bf16 v[48:51], v[180:183], v[188:191], v[48:51]
	v_mfma_f32_16x16x32_bf16 v[36:39], v[172:175], v[196:199], v[36:39]
	v_mfma_f32_16x16x32_bf16 v[32:35], v[180:183], v[196:199], v[32:35]
	v_mfma_f32_16x16x32_bf16 v[20:23], v[172:175], v[206:209], v[20:23]
	v_mfma_f32_16x16x32_bf16 v[16:19], v[180:183], v[206:209], v[16:19]
	v_mfma_f32_16x16x32_bf16 v[4:7], v[172:175], v[214:217], v[4:7]
	v_mfma_f32_16x16x32_bf16 v[0:3], v[180:183], v[214:217], v[0:3]
	s_barrier
	s_add_i32 s51, s51, 2
	s_add_u32 s28, s28, 0x100
	s_addc_u32 s29, s29, 0
	s_add_u32 s49, s49, 0x100
	s_addc_u32 s50, s50, 0
	s_cmp_gt_u32 s51, 61
	s_cbranch_scc0 .LBB0_1001
	s_setprio 0
	s_and_b64 vcc, exec, s[14:15]
	s_cbranch_vccz .LBB0_1004
	s_barrier

; #define PG8_STAGE(bufoff, gbase, voff) do { _Pragma("unroll") for (int _i = 0; _i < 2; ++_i) \
;         __builtin_amdgcn_global_load_lds((const unsigned*)((const char*)(gbase) + (voff)[_i]), (PG8_LAS unsigned*)(lds + (bufoff) + ldsw + _i * 8192), 16, 0, 0); } while (0)
; #define PG8_LDA(dst, b, h) do { _Pragma("unroll") for (int m = 0; m < 4; ++m) _Pragma("unroll") for (int k = 0; k < 2; ++k) dst[m][k] = *(const PG8_LAS bf16x8*)(lds + PG8_SA(b, h) + aoff + m * 2048 + k * 1024); } while (0)
; #define PG8_LDB(dst, b, h) do { _Pragma("unroll") for (int n = 0; n < 2; ++n) _Pragma("unroll") for (int k = 0; k < 2; ++k) dst[n][k] = *(const PG8_LAS bf16x8*)(lds + PG8_SB(b, h) + boff + n * 2048 + k * 1024); } while (0)
; #define PG8_WAIT_V(n) asm volatile("s_waitcnt vmcnt(" #n ")" ::: "memory")
; #define PG8_WAIT_L(n) asm volatile("s_waitcnt lgkmcnt(" #n ")" ::: "memory")
; #define PG8_BAR __builtin_amdgcn_s_barrier()
; #define PG8_SCHED __builtin_amdgcn_sched_barrier(0)
; template <class Epi, class Sched, bool ALIGN_EPI = false, bool SP2 = false>
; __device__ __forceinline__ void gemm_phase(PG8_LAS unsigned char* lds, const Gemm g, const Sched& S, const Epi& E) {
;     ...
;         const bool has_next = S.next(ui + 1, nxt);
;         const char* nA = has_next ? (const char*)g.A + (size_t)nxt.pm * tstep : cA; const char* nB = has_next ? (const char*)g.Bt + (size_t)nxt.pn * tstep : cB;
;         for (int t = 0; t < nt; t += 2) {
;             const bool last = (t == nt - 2);
;             const char* a1 = cA + (size_t)(t + 1) * kstep;
;             const char* a2 = last ? nA : cA + (size_t)(t + 2) * kstep; const char* b2 = last ? nB : cB + (size_t)(t + 2) * kstep;
;             const char* a3 = a2 + kstep; const char* b3 = b2 + kstep;
;             if (last && has_next) S.a_ready(nxt);
;             if constexpr (SP2) {
;             PG8_LDB(B0, 0, 0); PG8_LDB(B1, 0, 1); PG8_SCHED; PG8_LDA(At, 0, 0); PG8_STAGE(PG8_SA(1, 1), a1 + hstep, voffA);
;             PG8_WAIT_V(8); PG8_WAIT_L(0); PG8_BAR; PG8_MMA(0, 0, At, B0); PG8_MMA(0, 1, At, B1); PG8_BAR; PG8_SCHED;
;             PG8_LDA(At, 0, 1); PG8_STAGE(PG8_SB(0, 0), b2, voffB); PG8_STAGE(PG8_SB(0, 1), b2 + hstep, voffB); PG8_STAGE(PG8_SA(0, 0), a2, voffA);
;             PG8_WAIT_V(8); PG8_WAIT_L(0); PG8_BAR; PG8_MMA(1, 0, At, B0); PG8_MMA(1, 1, At, B1); PG8_BAR; PG8_SCHED;
.LBB0_1024:
	s_add_u32 s25, s28, 0x100
	s_addc_u32 s48, s29, 0
	s_ashr_i32 s21, s20, 31
	s_lshl_b64 s[22:23], s[20:21], 21
	v_readlane_b32 s16, v255, 26
	v_readlane_b32 s17, v255, 27
	s_add_u32 s26, s16, s22
	s_addc_u32 s27, s17, s23
	s_and_b64 s[22:23], s[6:7], exec
	s_cselect_b32 s21, s27, s13
	s_cselect_b32 s49, s26, s12
	s_ashr_i32 s19, s18, 31
	s_lshl_b64 s[22:23], s[18:19], 21
	s_add_u32 s22, s66, s22
	s_addc_u32 s23, s67, s23
	s_and_b64 s[30:31], s[6:7], exec
	s_cselect_b32 s19, s23, s29
	s_cselect_b32 s50, s22, s28
	v_lshl_add_u64 v[140:141], s[12:13], 0, v[128:129]
	v_lshl_add_u64 v[142:143], s[12:13], 0, v[134:135]
	s_mov_b32 s51, -2
	s_mov_b64 s[28:29], 0
	v_add_u32_e32 v240, 0x10000, v146
	v_add_u32_e32 v241, 0x14000, v146
	v_add_u32_e32 v242, 0x18000, v146
	v_add_u32_e32 v243, 0x1c000, v146
	s_cmpk_lt_u32 s33, 0x100
	s_cbranch_scc0 .Lsp6
	s_setprio 1
.Lsp6:
.LBB0_1025:
	s_add_u32 s98, s12, s28
	s_addc_u32 s99, s13, s29
	s_add_u32 s30, s12, s28
	ds_read_b128 v[148:151], v240
	ds_read_b128 v[152:155], v240 offset:1024
	ds_read_b128 v[156:159], v240 offset:2048
	ds_read_b128 v[160:163], v240 offset:3072
	ds_read_b128 v[164:167], v241
	ds_read_b128 v[168:171], v241 offset:1024
	ds_read_b128 v[172:175], v241 offset:2048
	ds_read_b128 v[176:179], v241 offset:3072
	s_addc_u32 s31, s13, s29
	s_add_u32 s30, s30, 0x100
	s_addc_u32 s31, s31, 0
	s_add_u32 s52, s25, s28
	s_addc_u32 s53, s48, s29
	s_cmpk_eq_i32 s28, 0x1f00
	s_cselect_b32 s35, s21, s31
	s_cselect_b32 s34, s49, s30
	s_cselect_b32 s31, s19, s53
	s_cselect_b32 s30, s50, s52
	s_add_i32 m0, s11, 0xc000
	ds_read_b128 v[180:183], v147
	ds_read_b128 v[184:187], v147 offset:1024
	ds_read_b128 v[188:191], v147 offset:2048
	ds_read_b128 v[192:195], v147 offset:3072
	ds_read_b128 v[196:199], v147 offset:4096
	ds_read_b128 v[200:203], v147 offset:5120
	ds_read_b128 v[206:209], v147 offset:6144
	ds_read_b128 v[210:213], v147 offset:7168
	global_load_lds_dwordx4 v128, s[98:99]
	s_add_i32 m0, s11, 0xe000
	s_nop 0
	global_load_lds_dwordx4 v134, s[98:99]
	s_waitcnt vmcnt(8)
	s_waitcnt lgkmcnt(0)
	s_barrier
	v_mfma_f32_16x16x32_bf16 v[124:127], v[148:151], v[180:183], v[124:127]
	v_mfma_f32_16x16x32_bf16 v[120:123], v[156:159], v[180:183], v[120:123]
	v_mfma_f32_16x16x32_bf16 v[108:111], v[148:151], v[188:191], v[108:111]
	v_mfma_f32_16x16x32_bf16 v[104:107], v[156:159], v[188:191], v[104:107]
	v_mfma_f32_16x16x32_bf16 v[92:95], v[148:151], v[196:199], v[92:95]
	v_mfma_f32_16x16x32_bf16 v[88:91], v[156:159], v[196:199], v[88:91]
	v_mfma_f32_16x16x32_bf16 v[76:79], v[148:151], v[206:209], v[76:79]
	v_mfma_f32_16x16x32_bf16 v[72:75], v[156:159], v[206:209], v[72:75]
	v_mfma_f32_16x16x32_bf16 v[124:127], v[152:155], v[184:187], v[124:127]
	v_mfma_f32_16x16x32_bf16 v[120:123], v[160:163], v[184:187], v[120:123]
	v_mfma_f32_16x16x32_bf16 v[108:111], v[152:155], v[192:195], v[108:111]
	v_mfma_f32_16x16x32_bf16 v[104:107], v[160:163], v[192:195], v[104:107]
	v_mfma_f32_16x16x32_bf16 v[92:95], v[152:155], v[200:203], v[92:95]
	v_mfma_f32_16x16x32_bf16 v[88:91], v[160:163], v[200:203], v[88:91]
	v_mfma_f32_16x16x32_bf16 v[76:79], v[152:155], v[210:213], v[76:79]
	v_mfma_f32_16x16x32_bf16 v[72:75], v[160:163], v[210:213], v[72:75]
	v_mfma_f32_16x16x32_bf16 v[116:119], v[164:167], v[180:183], v[116:119]
	v_mfma_f32_16x16x32_bf16 v[112:115], v[172:175], v[180:183], v[112:115]
	v_mfma_f32_16x16x32_bf16 v[100:103], v[164:167], v[188:191], v[100:103]
	v_mfma_f32_16x16x32_bf16 v[96:99], v[172:175], v[188:191], v[96:99]
	v_mfma_f32_16x16x32_bf16 v[84:87], v[164:167], v[196:199], v[84:87]
	v_mfma_f32_16x16x32_bf16 v[80:83], v[172:175], v[196:199], v[80:83]
	v_mfma_f32_16x16x32_bf16 v[68:71], v[164:167], v[206:209], v[68:71]
	v_mfma_f32_16x16x32_bf16 v[64:67], v[172:175], v[206:209], v[64:67]
	v_mfma_f32_16x16x32_bf16 v[116:119], v[168:171], v[184:187], v[116:119]
	v_mfma_f32_16x16x32_bf16 v[112:115], v[176:179], v[184:187], v[112:115]
	v_mfma_f32_16x16x32_bf16 v[100:103], v[168:171], v[192:195], v[100:103]
	v_mfma_f32_16x16x32_bf16 v[96:99], v[176:179], v[192:195], v[96:99]
	v_mfma_f32_16x16x32_bf16 v[84:87], v[168:171], v[200:203], v[84:87]
	v_mfma_f32_16x16x32_bf16 v[80:83], v[176:179], v[200:203], v[80:83]
	v_mfma_f32_16x16x32_bf16 v[68:71], v[168:171], v[210:213], v[68:71]
	v_mfma_f32_16x16x32_bf16 v[64:67], v[176:179], v[210:213], v[64:67]
	s_barrier
	s_add_i32 s52, s46, s36
	s_mov_b32 m0, s52
	ds_read_b128 v[180:183], v147 offset:16384
	ds_read_b128 v[184:187], v147 offset:17408
	ds_read_b128 v[188:191], v147 offset:18432
	ds_read_b128 v[192:195], v147 offset:19456
	ds_read_b128 v[196:199], v147 offset:20480
	ds_read_b128 v[200:203], v147 offset:21504
	ds_read_b128 v[206:209], v147 offset:22528
	ds_read_b128 v[210:213], v147 offset:23552
	global_load_lds_dwordx4 v130, s[30:31]
	s_add_i32 m0, s52, 0x2000
	s_add_u32 s98, s30, 0x80
	s_addc_u32 s99, s31, 0
	s_add_u32 s52, s30, 0x100000
	s_addc_u32 s53, s31, 0
	s_add_i32 s54, s47, s36
	global_load_lds_dwordx4 v132, s[30:31]
	s_mov_b32 m0, s54
	s_nop 0
	global_load_lds_dwordx4 v130, s[52:53]
	s_add_i32 m0, s54, 0x2000
	s_nop 0
	global_load_lds_dwordx4 v132, s[52:53]
	s_mov_b32 m0, s11
	s_nop 0
	global_load_lds_dwordx4 v130, s[34:35]
	s_mov_b32 m0, s37
	s_nop 0
	global_load_lds_dwordx4 v132, s[34:35]
	s_waitcnt vmcnt(8)
	s_waitcnt lgkmcnt(0)
	s_barrier
; #define PG8_STAGE(bufoff, gbase, voff) do { _Pragma("unroll") for (int _i = 0; _i < 2; ++_i) \
;         __builtin_amdgcn_global_load_lds((const unsigned*)((const char*)(gbase) + (voff)[_i]), (PG8_LAS unsigned*)(lds + (bufoff) + ldsw + _i * 8192), 16, 0, 0); } while (0)
; #define PG8_LDA(dst, b, h) do { _Pragma("unroll") for (int m = 0; m < 4; ++m) _Pragma("unroll") for (int k = 0; k < 2; ++k) dst[m][k] = *(const PG8_LAS bf16x8*)(lds + PG8_SA(b, h) + aoff + m * 2048 + k * 1024); } while (0)
; #define PG8_LDB(dst, b, h) do { _Pragma("unroll") for (int n = 0; n < 2; ++n) _Pragma("unroll") for (int k = 0; k < 2; ++k) dst[n][k] = *(const PG8_LAS bf16x8*)(lds + PG8_SB(b, h) + boff + n * 2048 + k * 1024); } while (0)
; #define PG8_MMA(ai, bj, At, Bt) do { __builtin_amdgcn_s_setprio(1); _Pragma("unroll") for (int m = 0; m < 4; ++m) _Pragma("unroll") for (int n = 0; n < 2; ++n) _Pragma("unroll") for (int k = 0; k < 2; ++k) \
;         acc[ai][bj][m][n] = __builtin_amdgcn_mfma_f32_16x16x32_bf16(Bt[n][k], At[m][k], acc[ai][bj][m][n], 0, 0, 0); __builtin_amdgcn_s_setprio(0); } while (0)
; #define PG8_WAIT_V(n) asm volatile("s_waitcnt vmcnt(" #n ")" ::: "memory")
; #define PG8_WAIT_L(n) asm volatile("s_waitcnt lgkmcnt(" #n ")" ::: "memory")
; #define PG8_BAR __builtin_amdgcn_s_barrier()
; #define PG8_SCHED __builtin_amdgcn_sched_barrier(0)
; template <class Epi, class Sched, bool ALIGN_EPI = false, bool SP2 = false>
; __device__ __forceinline__ void gemm_phase(PG8_LAS unsigned char* lds, const Gemm g, const Sched& S, const Epi& E) {
;     ...
;             PG8_WAIT_V(8); PG8_WAIT_L(0); PG8_BAR; PG8_MMA(1, 0, At, B0); PG8_MMA(1, 1, At, B1); PG8_BAR; PG8_SCHED;
;             PG8_LDB(B0, 1, 0); PG8_LDB(B1, 1, 1); PG8_SCHED; PG8_LDA(At, 1, 0); PG8_STAGE(PG8_SA(0, 1), a2 + hstep, voffA);
;             PG8_WAIT_V(8); PG8_WAIT_L(0); PG8_BAR; PG8_MMA(0, 0, At, B0); PG8_MMA(0, 1, At, B1); PG8_BAR; PG8_SCHED;
	v_mfma_f32_16x16x32_bf16 v[60:63], v[148:151], v[180:183], v[60:63]
	v_mfma_f32_16x16x32_bf16 v[56:59], v[156:159], v[180:183], v[56:59]
	v_mfma_f32_16x16x32_bf16 v[44:47], v[148:151], v[188:191], v[44:47]
	v_mfma_f32_16x16x32_bf16 v[40:43], v[156:159], v[188:191], v[40:43]
	v_mfma_f32_16x16x32_bf16 v[28:31], v[148:151], v[196:199], v[28:31]
	v_mfma_f32_16x16x32_bf16 v[24:27], v[156:159], v[196:199], v[24:27]
	v_mfma_f32_16x16x32_bf16 v[12:15], v[148:151], v[206:209], v[12:15]
	v_mfma_f32_16x16x32_bf16 v[8:11], v[156:159], v[206:209], v[8:11]
	v_mfma_f32_16x16x32_bf16 v[60:63], v[152:155], v[184:187], v[60:63]
	v_mfma_f32_16x16x32_bf16 v[56:59], v[160:163], v[184:187], v[56:59]
	v_mfma_f32_16x16x32_bf16 v[44:47], v[152:155], v[192:195], v[44:47]
	v_mfma_f32_16x16x32_bf16 v[40:43], v[160:163], v[192:195], v[40:43]
	v_mfma_f32_16x16x32_bf16 v[28:31], v[152:155], v[200:203], v[28:31]
	v_mfma_f32_16x16x32_bf16 v[24:27], v[160:163], v[200:203], v[24:27]
	v_mfma_f32_16x16x32_bf16 v[12:15], v[152:155], v[210:213], v[12:15]
	v_mfma_f32_16x16x32_bf16 v[8:11], v[160:163], v[210:213], v[8:11]
	v_mfma_f32_16x16x32_bf16 v[52:55], v[164:167], v[180:183], v[52:55]
	v_mfma_f32_16x16x32_bf16 v[48:51], v[172:175], v[180:183], v[48:51]
	v_mfma_f32_16x16x32_bf16 v[36:39], v[164:167], v[188:191], v[36:39]
	v_mfma_f32_16x16x32_bf16 v[32:35], v[172:175], v[188:191], v[32:35]
	v_mfma_f32_16x16x32_bf16 v[20:23], v[164:167], v[196:199], v[20:23]
	v_mfma_f32_16x16x32_bf16 v[16:19], v[172:175], v[196:199], v[16:19]
	v_mfma_f32_16x16x32_bf16 v[4:7], v[164:167], v[206:209], v[4:7]
	v_mfma_f32_16x16x32_bf16 v[0:3], v[172:175], v[206:209], v[0:3]
	v_mfma_f32_16x16x32_bf16 v[52:55], v[168:171], v[184:187], v[52:55]
	v_mfma_f32_16x16x32_bf16 v[48:51], v[176:179], v[184:187], v[48:51]
	v_mfma_f32_16x16x32_bf16 v[36:39], v[168:171], v[192:195], v[36:39]
	v_mfma_f32_16x16x32_bf16 v[32:35], v[176:179], v[192:195], v[32:35]
	v_mfma_f32_16x16x32_bf16 v[20:23], v[168:171], v[200:203], v[20:23]
	v_mfma_f32_16x16x32_bf16 v[16:19], v[176:179], v[200:203], v[16:19]
	v_mfma_f32_16x16x32_bf16 v[4:7], v[168:171], v[210:213], v[4:7]
	v_mfma_f32_16x16x32_bf16 v[0:3], v[176:179], v[210:213], v[0:3]
	s_barrier
	s_add_i32 s52, 0, 0x18000
	s_add_i32 s53, 0, 0x1c000
	ds_read_b128 v[148:151], v242
	ds_read_b128 v[152:155], v242 offset:1024
	ds_read_b128 v[156:159], v242 offset:2048
	ds_read_b128 v[160:163], v242 offset:3072
	ds_read_b128 v[164:167], v243
	ds_read_b128 v[168:171], v243 offset:1024
	ds_read_b128 v[172:175], v243 offset:2048
	ds_read_b128 v[176:179], v243 offset:3072
	s_add_u32 s100, s34, 0x80
	s_addc_u32 s101, s35, 0
	s_add_u32 s34, s34, 0x100000
	s_addc_u32 s35, s35, 0
	s_mov_b32 m0, s38
	ds_read_b128 v[180:183], v147 offset:32768
	ds_read_b128 v[184:187], v147 offset:33792
	ds_read_b128 v[188:191], v147 offset:34816
	ds_read_b128 v[192:195], v147 offset:35840
	ds_read_b128 v[196:199], v147 offset:36864
	ds_read_b128 v[200:203], v147 offset:37888
	ds_read_b128 v[206:209], v147 offset:38912
	ds_read_b128 v[210:213], v147 offset:39936
	global_load_lds_dwordx4 v130, s[34:35]
	s_mov_b32 m0, s40
	s_nop 0
	global_load_lds_dwordx4 v132, s[34:35]
	s_waitcnt vmcnt(8)
	s_waitcnt lgkmcnt(0)
	s_barrier
	v_mfma_f32_16x16x32_bf16 v[124:127], v[148:151], v[180:183], v[124:127]
	v_mfma_f32_16x16x32_bf16 v[120:123], v[156:159], v[180:183], v[120:123]
	v_mfma_f32_16x16x32_bf16 v[108:111], v[148:151], v[188:191], v[108:111]
	v_mfma_f32_16x16x32_bf16 v[104:107], v[156:159], v[188:191], v[104:107]
	v_mfma_f32_16x16x32_bf16 v[92:95], v[148:151], v[196:199], v[92:95]
	v_mfma_f32_16x16x32_bf16 v[88:91], v[156:159], v[196:199], v[88:91]
	v_mfma_f32_16x16x32_bf16 v[76:79], v[148:151], v[206:209], v[76:79]
	v_mfma_f32_16x16x32_bf16 v[72:75], v[156:159], v[206:209], v[72:75]
	v_mfma_f32_16x16x32_bf16 v[124:127], v[152:155], v[184:187], v[124:127]
	v_mfma_f32_16x16x32_bf16 v[120:123], v[160:163], v[184:187], v[120:123]
	v_mfma_f32_16x16x32_bf16 v[108:111], v[152:155], v[192:195], v[108:111]
	v_mfma_f32_16x16x32_bf16 v[104:107], v[160:163], v[192:195], v[104:107]
	v_mfma_f32_16x16x32_bf16 v[92:95], v[152:155], v[200:203], v[92:95]
	v_mfma_f32_16x16x32_bf16 v[88:91], v[160:163], v[200:203], v[88:91]
	v_mfma_f32_16x16x32_bf16 v[76:79], v[152:155], v[210:213], v[76:79]
	v_mfma_f32_16x16x32_bf16 v[72:75], v[160:163], v[210:213], v[72:75]
	v_mfma_f32_16x16x32_bf16 v[116:119], v[164:167], v[180:183], v[116:119]
	v_mfma_f32_16x16x32_bf16 v[112:115], v[172:175], v[180:183], v[112:115]
	v_mfma_f32_16x16x32_bf16 v[100:103], v[164:167], v[188:191], v[100:103]
	v_mfma_f32_16x16x32_bf16 v[96:99], v[172:175], v[188:191], v[96:99]
	v_mfma_f32_16x16x32_bf16 v[84:87], v[164:167], v[196:199], v[84:87]
	v_mfma_f32_16x16x32_bf16 v[80:83], v[172:175], v[196:199], v[80:83]
	v_mfma_f32_16x16x32_bf16 v[68:71], v[164:167], v[206:209], v[68:71]
	v_mfma_f32_16x16x32_bf16 v[64:67], v[172:175], v[206:209], v[64:67]
	v_mfma_f32_16x16x32_bf16 v[116:119], v[168:171], v[184:187], v[116:119]
	v_mfma_f32_16x16x32_bf16 v[112:115], v[176:179], v[184:187], v[112:115]
	v_mfma_f32_16x16x32_bf16 v[100:103], v[168:171], v[192:195], v[100:103]
	v_mfma_f32_16x16x32_bf16 v[96:99], v[176:179], v[192:195], v[96:99]
	v_mfma_f32_16x16x32_bf16 v[84:87], v[168:171], v[200:203], v[84:87]
	v_mfma_f32_16x16x32_bf16 v[80:83], v[176:179], v[200:203], v[80:83]
	v_mfma_f32_16x16x32_bf16 v[68:71], v[168:171], v[210:213], v[68:71]
	v_mfma_f32_16x16x32_bf16 v[64:67], v[176:179], v[210:213], v[64:67]
	s_barrier
; #define PG8_STAGE(bufoff, gbase, voff) do { _Pragma("unroll") for (int _i = 0; _i < 2; ++_i) \
;         __builtin_amdgcn_global_load_lds((const unsigned*)((const char*)(gbase) + (voff)[_i]), (PG8_LAS unsigned*)(lds + (bufoff) + ldsw + _i * 8192), 16, 0, 0); } while (0)
; #define PG8_LDA(dst, b, h) do { _Pragma("unroll") for (int m = 0; m < 4; ++m) _Pragma("unroll") for (int k = 0; k < 2; ++k) dst[m][k] = *(const PG8_LAS bf16x8*)(lds + PG8_SA(b, h) + aoff + m * 2048 + k * 1024); } while (0)
; #define PG8_MMA(ai, bj, At, Bt) do { __builtin_amdgcn_s_setprio(1); _Pragma("unroll") for (int m = 0; m < 4; ++m) _Pragma("unroll") for (int n = 0; n < 2; ++n) _Pragma("unroll") for (int k = 0; k < 2; ++k) \
;         acc[ai][bj][m][n] = __builtin_amdgcn_mfma_f32_16x16x32_bf16(Bt[n][k], At[m][k], acc[ai][bj][m][n], 0, 0, 0); __builtin_amdgcn_s_setprio(0); } while (0)
; #define PG8_WAIT_V(n) asm volatile("s_waitcnt vmcnt(" #n ")" ::: "memory")
; #define PG8_WAIT_L(n) asm volatile("s_waitcnt lgkmcnt(" #n ")" ::: "memory")
; #define PG8_BAR __builtin_amdgcn_s_barrier()
; #define PG8_SCHED __builtin_amdgcn_sched_barrier(0)
; template <class Epi, class Sched, bool ALIGN_EPI = false, bool SP2 = false>
; __device__ __forceinline__ void gemm_phase(PG8_LAS unsigned char* lds, const Gemm g, const Sched& S, const Epi& E) {
;     ...
;             PG8_LDA(At, 1, 1); PG8_STAGE(PG8_SB(1, 0), b3, voffB); PG8_STAGE(PG8_SB(1, 1), b3 + hstep, voffB); PG8_STAGE(PG8_SA(1, 0), a3, voffA);
;             PG8_WAIT_V(8); PG8_WAIT_L(0); PG8_BAR; PG8_MMA(1, 0, At, B0); PG8_MMA(1, 1, At, B1); PG8_BAR; PG8_SCHED;
;     ...
;         if (!has_next) break;
; #pragma unroll
;         for (int a = 0; a < 2; ++a)
; #pragma unroll
;             for (int b = 0; b < 2; ++b)
; #pragma unroll
;                 for (int m = 0; m < 4; ++m)
; #pragma unroll
;                     for (int n = 0; n < 2; ++n) acc[a][b][m][n] = (f32x4){0.f, 0.f, 0.f, 0.f};
;         cur = nxt; cA = nA; cB = nB; ++ui;
	s_add_i32 s34, s52, s36
	s_mov_b32 m0, s34
	ds_read_b128 v[180:183], v147 offset:49152
	ds_read_b128 v[184:187], v147 offset:50176
	ds_read_b128 v[188:191], v147 offset:51200
	ds_read_b128 v[192:195], v147 offset:52224
	ds_read_b128 v[196:199], v147 offset:53248
	ds_read_b128 v[200:203], v147 offset:54272
	ds_read_b128 v[206:209], v147 offset:55296
	ds_read_b128 v[210:213], v147 offset:56320
	global_load_lds_dwordx4 v130, s[98:99]
	s_add_i32 m0, s34, 0x2000
	s_add_u32 s30, s30, 0x100080
	s_addc_u32 s31, s31, 0
	s_add_i32 s34, s53, s36
	global_load_lds_dwordx4 v132, s[98:99]
	s_mov_b32 m0, s34
	s_nop 0
	global_load_lds_dwordx4 v130, s[30:31]
	s_add_i32 m0, s34, 0x2000
	s_nop 0
	global_load_lds_dwordx4 v132, s[30:31]
	s_mov_b32 m0, s42
	s_nop 0
	global_load_lds_dwordx4 v130, s[100:101]
	s_mov_b32 m0, s43
	s_nop 0
	global_load_lds_dwordx4 v132, s[100:101]
	s_waitcnt vmcnt(8)
	s_waitcnt lgkmcnt(0)
	s_barrier
	v_mfma_f32_16x16x32_bf16 v[60:63], v[148:151], v[180:183], v[60:63]
	v_mfma_f32_16x16x32_bf16 v[56:59], v[156:159], v[180:183], v[56:59]
	v_mfma_f32_16x16x32_bf16 v[44:47], v[148:151], v[188:191], v[44:47]
	v_mfma_f32_16x16x32_bf16 v[40:43], v[156:159], v[188:191], v[40:43]
	v_mfma_f32_16x16x32_bf16 v[28:31], v[148:151], v[196:199], v[28:31]
	v_mfma_f32_16x16x32_bf16 v[24:27], v[156:159], v[196:199], v[24:27]
	v_mfma_f32_16x16x32_bf16 v[12:15], v[148:151], v[206:209], v[12:15]
	v_mfma_f32_16x16x32_bf16 v[8:11], v[156:159], v[206:209], v[8:11]
	v_mfma_f32_16x16x32_bf16 v[60:63], v[152:155], v[184:187], v[60:63]
	v_mfma_f32_16x16x32_bf16 v[56:59], v[160:163], v[184:187], v[56:59]
	v_mfma_f32_16x16x32_bf16 v[44:47], v[152:155], v[192:195], v[44:47]
	v_mfma_f32_16x16x32_bf16 v[40:43], v[160:163], v[192:195], v[40:43]
	v_mfma_f32_16x16x32_bf16 v[28:31], v[152:155], v[200:203], v[28:31]
	v_mfma_f32_16x16x32_bf16 v[24:27], v[160:163], v[200:203], v[24:27]
	v_mfma_f32_16x16x32_bf16 v[12:15], v[152:155], v[210:213], v[12:15]
	v_mfma_f32_16x16x32_bf16 v[8:11], v[160:163], v[210:213], v[8:11]
	v_mfma_f32_16x16x32_bf16 v[52:55], v[164:167], v[180:183], v[52:55]
	v_mfma_f32_16x16x32_bf16 v[48:51], v[172:175], v[180:183], v[48:51]
	v_mfma_f32_16x16x32_bf16 v[36:39], v[164:167], v[188:191], v[36:39]
	v_mfma_f32_16x16x32_bf16 v[32:35], v[172:175], v[188:191], v[32:35]
	v_mfma_f32_16x16x32_bf16 v[20:23], v[164:167], v[196:199], v[20:23]
	v_mfma_f32_16x16x32_bf16 v[16:19], v[172:175], v[196:199], v[16:19]
	v_mfma_f32_16x16x32_bf16 v[4:7], v[164:167], v[206:209], v[4:7]
	v_mfma_f32_16x16x32_bf16 v[0:3], v[172:175], v[206:209], v[0:3]
	v_mfma_f32_16x16x32_bf16 v[52:55], v[168:171], v[184:187], v[52:55]
	v_mfma_f32_16x16x32_bf16 v[48:51], v[176:179], v[184:187], v[48:51]
	v_mfma_f32_16x16x32_bf16 v[36:39], v[168:171], v[192:195], v[36:39]
	v_mfma_f32_16x16x32_bf16 v[32:35], v[176:179], v[192:195], v[32:35]
	v_mfma_f32_16x16x32_bf16 v[20:23], v[168:171], v[200:203], v[20:23]
	v_mfma_f32_16x16x32_bf16 v[16:19], v[176:179], v[200:203], v[16:19]
	v_mfma_f32_16x16x32_bf16 v[4:7], v[168:171], v[210:213], v[4:7]
	v_mfma_f32_16x16x32_bf16 v[0:3], v[176:179], v[210:213], v[0:3]
	s_barrier
	s_add_i32 s51, s51, 2
	s_add_u32 s28, s28, 0x100
	s_addc_u32 s29, s29, 0
	s_cmp_gt_u32 s51, 61
	s_cbranch_scc0 .LBB0_1025
	s_setprio 0
	s_add_u32 s28, s25, 0xffffff00
	s_addc_u32 s29, s48, -1
	s_andn2_b64 vcc, exec, s[6:7]
	s_cbranch_vccnz .LBB0_1028
	v_mov_b32_e32 v0, 0
	s_mov_b32 s44, s18
	s_mov_b32 s10, s20
	s_mov_b64 s[12:13], s[26:27]
	s_mov_b32 s45, s24
	v_mov_b32_e32 v1, v0
	v_mov_b32_e32 v2, v0
	v_mov_b32_e32 v3, v0
	v_mov_b32_e32 v4, v0
	v_mov_b32_e32 v5, v0
	v_mov_b32_e32 v6, v0
	v_mov_b32_e32 v7, v0
	v_mov_b32_e32 v16, v0
	v_mov_b32_e32 v17, v0
	v_mov_b32_e32 v18, v0
	v_mov_b32_e32 v19, v0
	v_mov_b32_e32 v20, v0
	v_mov_b32_e32 v21, v0
	v_mov_b32_e32 v22, v0
	v_mov_b32_e32 v23, v0
	v_mov_b32_e32 v32, v0
	v_mov_b32_e32 v33, v0
	v_mov_b32_e32 v34, v0
	v_mov_b32_e32 v35, v0
	v_mov_b32_e32 v36, v0
	v_mov_b32_e32 v37, v0
	v_mov_b32_e32 v38, v0
	v_mov_b32_e32 v39, v0
	v_mov_b32_e32 v48, v0
	v_mov_b32_e32 v49, v0
	v_mov_b32_e32 v50, v0
	v_mov_b32_e32 v51, v0
	v_mov_b32_e32 v52, v0
	v_mov_b32_e32 v53, v0
	v_mov_b32_e32 v54, v0
	v_mov_b32_e32 v55, v0
	v_mov_b32_e32 v8, v0
	v_mov_b32_e32 v9, v0
	v_mov_b32_e32 v10, v0
	v_mov_b32_e32 v11, v0
	v_mov_b32_e32 v12, v0
	v_mov_b32_e32 v13, v0
	v_mov_b32_e32 v14, v0
	v_mov_b32_e32 v15, v0
	v_mov_b32_e32 v24, v0
	v_mov_b32_e32 v25, v0
	v_mov_b32_e32 v26, v0
	v_mov_b32_e32 v27, v0
	v_mov_b32_e32 v28, v0
	v_mov_b32_e32 v29, v0
	v_mov_b32_e32 v30, v0
	v_mov_b32_e32 v31, v0
	v_mov_b32_e32 v40, v0
	v_mov_b32_e32 v41, v0
	v_mov_b32_e32 v42, v0
	v_mov_b32_e32 v43, v0
	v_mov_b32_e32 v44, v0
	v_mov_b32_e32 v45, v0
	v_mov_b32_e32 v46, v0
	v_mov_b32_e32 v47, v0
	v_mov_b32_e32 v56, v0
	v_mov_b32_e32 v57, v0
	v_mov_b32_e32 v58, v0
	v_mov_b32_e32 v59, v0
	v_mov_b32_e32 v60, v0
	v_mov_b32_e32 v61, v0
	v_mov_b32_e32 v62, v0
	v_mov_b32_e32 v63, v0
	v_mov_b32_e32 v64, v0
	v_mov_b32_e32 v65, v0
	v_mov_b32_e32 v66, v0
	v_mov_b32_e32 v67, v0
	v_mov_b32_e32 v68, v0
	v_mov_b32_e32 v69, v0
	v_mov_b32_e32 v70, v0
	v_mov_b32_e32 v71, v0
	v_mov_b32_e32 v80, v0
	v_mov_b32_e32 v81, v0
	v_mov_b32_e32 v82, v0
	v_mov_b32_e32 v83, v0
	v_mov_b32_e32 v84, v0
	v_mov_b32_e32 v85, v0
	v_mov_b32_e32 v86, v0
	v_mov_b32_e32 v87, v0
	v_mov_b32_e32 v96, v0
	v_mov_b32_e32 v97, v0
	v_mov_b32_e32 v98, v0
	v_mov_b32_e32 v99, v0
	v_mov_b32_e32 v100, v0
	v_mov_b32_e32 v101, v0
	v_mov_b32_e32 v102, v0
	v_mov_b32_e32 v103, v0
	v_mov_b32_e32 v112, v0
	v_mov_b32_e32 v113, v0
	v_mov_b32_e32 v114, v0
	v_mov_b32_e32 v115, v0
	v_mov_b32_e32 v116, v0
	v_mov_b32_e32 v117, v0
	v_mov_b32_e32 v118, v0
	v_mov_b32_e32 v119, v0
	v_mov_b32_e32 v72, v0
	v_mov_b32_e32 v73, v0
	v_mov_b32_e32 v74, v0
	v_mov_b32_e32 v75, v0
	v_mov_b32_e32 v76, v0
	v_mov_b32_e32 v77, v0
	v_mov_b32_e32 v78, v0
	v_mov_b32_e32 v79, v0
	v_mov_b32_e32 v88, v0
	v_mov_b32_e32 v89, v0
	v_mov_b32_e32 v90, v0
	v_mov_b32_e32 v91, v0
	v_mov_b32_e32 v92, v0
	v_mov_b32_e32 v93, v0
	v_mov_b32_e32 v94, v0
	v_mov_b32_e32 v95, v0
	v_mov_b32_e32 v104, v0
	v_mov_b32_e32 v105, v0
	v_mov_b32_e32 v106, v0
	v_mov_b32_e32 v107, v0
	v_mov_b32_e32 v108, v0
	v_mov_b32_e32 v109, v0
	v_mov_b32_e32 v110, v0
	v_mov_b32_e32 v111, v0
	v_mov_b32_e32 v120, v0
	v_mov_b32_e32 v121, v0
	v_mov_b32_e32 v122, v0
	v_mov_b32_e32 v123, v0
	v_mov_b32_e32 v124, v0
	v_mov_b32_e32 v125, v0
	v_mov_b32_e32 v126, v0
	v_mov_b32_e32 v127, v0
	s_andn2_b64 vcc, exec, s[0:1]
	s_cbranch_vccnz .LBB0_1029
	s_branch .LBB0_1030
